# 84 back-to-back duplicate s_waitcnt lgkmcnt(0) (left adjacent after the s_setprio deletion) removed from the GEMM phases
# speedup vs baseline: 1.0044x; 1.0017x over previous
; #define G_LDA(dst, b, h)                                                                                                  \
;   _Pragma("unroll") for (int m = 0; m < 4; ++m) _Pragma("unroll") for (int k = 0; k < 2; ++k)                             \
;       dst[m][k] = *(const bf16x8*)((const char*)G_SA(b, h) + ((wr * 4 + m) * 2 + k) * 1024 + rdo)
; #define G_LDB(dst, b, h)                                                                                                  \
;   _Pragma("unroll") for (int n = 0; n < 2; ++n) _Pragma("unroll") for (int k = 0; k < 2; ++k)                             \
;       dst[n][k] = *(const bf16x8*)((const char*)G_SB(b, h) + ((wc * 2 + n) * 2 + k) * 1024 + rdo)
; #define G_WAIT_V(n) asm volatile("s_waitcnt vmcnt(" #n ")" ::: "memory")
; #define G_WAIT_L(n) asm volatile("s_waitcnt lgkmcnt(" #n ")" ::: "memory")
; #define G_BAR __builtin_amdgcn_s_barrier()
; #define G_SCHED __builtin_amdgcn_sched_barrier(0)
;     ...
;   for (int tt = 0; tt < nt - 2; tt += 2) {
;     G_LDB(B0, 0, 0); G_SCHED; G_LDA(At, 0, 0); G_STAGE(G_SA(1, 1), A, oa0, oa1, LDA, 128, KA(tt + 1));
;     G_WAIT_L(8); G_BAR; G_WAIT_L(0); G_MMA(0, 0, At, B0); G_BAR; G_SCHED;
;     G_LDB(B1, 0, 1); G_STAGE(G_SB(0, 0), B, ob0, ob1, LDB, 0, KB(tt + 2));
;     G_BAR; G_WAIT_L(0); G_MMA(0, 1, At, B1); G_BAR;
;     G_LDA(At, 0, 1); G_STAGE(G_SA(0, 0), A, oa0, oa1, LDA, 0, KA(tt + 2));
;     G_BAR; G_WAIT_L(0); G_MMA(1, 0, At, B0); G_BAR; G_SCHED;
;     G_STAGE(G_SB(0, 1), B, ob0, ob1, LDB, 128, KB(tt + 2));
;     G_WAIT_V(6); G_BAR; G_MMA(1, 1, At, B1); G_BAR;
.LBB0_40:
	ds_read_b128 v[164:167], v162
	ds_read_b128 v[182:185], v162 offset:1024
	ds_read_b128 v[186:189], v162 offset:2048
	ds_read_b128 v[190:193], v162 offset:3072
	v_lshl_add_u64 v[242:243], v[136:137], 0, s[20:21]
	v_readfirstlane_b32 s0, v161
	v_lshl_add_u64 v[226:227], v[242:243], 0, s[78:79]
	s_mov_b32 m0, s0
	v_lshl_add_u64 v[244:245], v[134:135], 0, s[20:21]
	v_readfirstlane_b32 s0, v160
	ds_read_b128 v[194:197], v142
	ds_read_b128 v[198:201], v142 offset:1024
	ds_read_b128 v[202:205], v142 offset:2048
	ds_read_b128 v[206:209], v142 offset:3072
	ds_read_b128 v[210:213], v142 offset:4096
	ds_read_b128 v[214:217], v142 offset:5120
	ds_read_b128 v[218:221], v142 offset:6144
	ds_read_b128 v[222:225], v142 offset:7168
	global_load_lds_dwordx4 v[226:227], off
	v_lshl_add_u64 v[226:227], v[244:245], 0, s[78:79]
	s_mov_b32 m0, s0
	s_nop 0
	global_load_lds_dwordx4 v[226:227], off
	s_waitcnt lgkmcnt(8)
	s_barrier
	s_waitcnt lgkmcnt(0)
	v_mfma_f32_16x16x32_bf16 v[126:129], v[194:197], v[164:167], v[126:129]
	v_mfma_f32_16x16x32_bf16 v[122:125], v[194:197], v[186:189], v[122:125]
	v_mfma_f32_16x16x32_bf16 v[118:121], v[202:205], v[164:167], v[118:121]
	v_mfma_f32_16x16x32_bf16 v[114:117], v[202:205], v[186:189], v[114:117]
	v_mfma_f32_16x16x32_bf16 v[110:113], v[210:213], v[164:167], v[110:113]
	v_mfma_f32_16x16x32_bf16 v[106:109], v[210:213], v[186:189], v[106:109]
	v_mfma_f32_16x16x32_bf16 v[102:105], v[218:221], v[164:167], v[102:105]
	v_mfma_f32_16x16x32_bf16 v[98:101], v[218:221], v[186:189], v[98:101]
	v_mfma_f32_16x16x32_bf16 v[126:129], v[198:201], v[182:185], v[126:129]
	v_mfma_f32_16x16x32_bf16 v[122:125], v[198:201], v[190:193], v[122:125]
	v_mfma_f32_16x16x32_bf16 v[118:121], v[206:209], v[182:185], v[118:121]
	v_mfma_f32_16x16x32_bf16 v[114:117], v[206:209], v[190:193], v[114:117]
	v_mfma_f32_16x16x32_bf16 v[110:113], v[214:217], v[182:185], v[110:113]
	v_mfma_f32_16x16x32_bf16 v[106:109], v[214:217], v[190:193], v[106:109]
	v_mfma_f32_16x16x32_bf16 v[102:105], v[222:225], v[182:185], v[102:105]
	v_mfma_f32_16x16x32_bf16 v[98:101], v[222:225], v[190:193], v[98:101]
	s_barrier
	v_lshl_add_u64 v[246:247], v[140:141], 0, s[20:21]
	v_readfirstlane_b32 s0, v146
	v_lshl_add_u64 v[248:249], v[246:247], 0, s[42:43]
	s_mov_b32 m0, s0
	ds_read_b128 v[226:229], v159
	ds_read_b128 v[230:233], v159 offset:1024
	ds_read_b128 v[234:237], v159 offset:2048
	ds_read_b128 v[238:241], v159 offset:3072
	global_load_lds_dwordx4 v[248:249], off
	v_lshl_add_u64 v[248:249], v[138:139], 0, s[20:21]
	v_readfirstlane_b32 s0, v147
	v_lshl_add_u64 v[250:251], v[248:249], 0, s[42:43]
	s_mov_b32 m0, s0
	s_nop 0
	global_load_lds_dwordx4 v[250:251], off
	s_barrier
	s_waitcnt lgkmcnt(0)
	v_mfma_f32_16x16x32_bf16 v[94:97], v[194:197], v[226:229], v[94:97]
	v_mfma_f32_16x16x32_bf16 v[78:81], v[194:197], v[234:237], v[78:81]
	v_mfma_f32_16x16x32_bf16 v[62:65], v[202:205], v[226:229], v[62:65]
	v_mfma_f32_16x16x32_bf16 v[54:57], v[202:205], v[234:237], v[54:57]
	v_mfma_f32_16x16x32_bf16 v[50:53], v[210:213], v[226:229], v[50:53]
	v_mfma_f32_16x16x32_bf16 v[46:49], v[210:213], v[234:237], v[46:49]
	v_mfma_f32_16x16x32_bf16 v[42:45], v[218:221], v[226:229], v[42:45]
	v_mfma_f32_16x16x32_bf16 v[38:41], v[218:221], v[234:237], v[38:41]
	v_mfma_f32_16x16x32_bf16 v[94:97], v[198:201], v[230:233], v[94:97]
	v_mfma_f32_16x16x32_bf16 v[78:81], v[198:201], v[238:241], v[78:81]
	v_mfma_f32_16x16x32_bf16 v[62:65], v[206:209], v[230:233], v[62:65]
	v_mfma_f32_16x16x32_bf16 v[54:57], v[206:209], v[238:241], v[54:57]
	v_mfma_f32_16x16x32_bf16 v[50:53], v[214:217], v[230:233], v[50:53]
	v_mfma_f32_16x16x32_bf16 v[46:49], v[214:217], v[238:241], v[46:49]
	v_mfma_f32_16x16x32_bf16 v[42:45], v[222:225], v[230:233], v[42:45]
	v_mfma_f32_16x16x32_bf16 v[38:41], v[222:225], v[238:241], v[38:41]
	v_readfirstlane_b32 s0, v143
	v_lshl_add_u64 v[250:251], v[242:243], 0, s[82:83]
	s_mov_b32 m0, s0
	v_readfirstlane_b32 s0, v144
	s_barrier
	ds_read_b128 v[194:197], v142 offset:16384
	ds_read_b128 v[198:201], v142 offset:17408
	ds_read_b128 v[202:205], v142 offset:18432
	ds_read_b128 v[206:209], v142 offset:19456
	ds_read_b128 v[210:213], v142 offset:20480
	ds_read_b128 v[214:217], v142 offset:21504
	ds_read_b128 v[218:221], v142 offset:22528
	ds_read_b128 v[222:225], v142 offset:23552
	global_load_lds_dwordx4 v[250:251], off
	v_lshl_add_u64 v[250:251], v[244:245], 0, s[82:83]
	s_mov_b32 m0, s0
	s_nop 0
	global_load_lds_dwordx4 v[250:251], off
	s_barrier
	s_waitcnt lgkmcnt(0)
	v_mfma_f32_16x16x32_bf16 v[34:37], v[194:197], v[164:167], v[34:37]
	v_mfma_f32_16x16x32_bf16 v[30:33], v[194:197], v[186:189], v[30:33]
	v_mfma_f32_16x16x32_bf16 v[26:29], v[202:205], v[164:167], v[26:29]
	v_mfma_f32_16x16x32_bf16 v[22:25], v[202:205], v[186:189], v[22:25]
	v_mfma_f32_16x16x32_bf16 v[18:21], v[210:213], v[164:167], v[18:21]
	v_mfma_f32_16x16x32_bf16 v[14:17], v[210:213], v[186:189], v[14:17]
	v_mfma_f32_16x16x32_bf16 v[10:13], v[218:221], v[164:167], v[10:13]
	v_mfma_f32_16x16x32_bf16 v[6:9], v[218:221], v[186:189], v[6:9]
	v_mfma_f32_16x16x32_bf16 v[34:37], v[198:201], v[182:185], v[34:37]
	v_mfma_f32_16x16x32_bf16 v[30:33], v[198:201], v[190:193], v[30:33]
	v_mfma_f32_16x16x32_bf16 v[26:29], v[206:209], v[182:185], v[26:29]
	v_mfma_f32_16x16x32_bf16 v[22:25], v[206:209], v[190:193], v[22:25]
	v_mfma_f32_16x16x32_bf16 v[18:21], v[214:217], v[182:185], v[18:21]
	v_mfma_f32_16x16x32_bf16 v[14:17], v[214:217], v[190:193], v[14:17]
	v_mfma_f32_16x16x32_bf16 v[10:13], v[222:225], v[182:185], v[10:13]
	v_mfma_f32_16x16x32_bf16 v[6:9], v[222:225], v[190:193], v[6:9]
	s_barrier
; #define G_LDA(dst, b, h)                                                                                                  \
;   _Pragma("unroll") for (int m = 0; m < 4; ++m) _Pragma("unroll") for (int k = 0; k < 2; ++k)                             \
;       dst[m][k] = *(const bf16x8*)((const char*)G_SA(b, h) + ((wr * 4 + m) * 2 + k) * 1024 + rdo)
; #define G_LDB(dst, b, h)                                                                                                  \
;   _Pragma("unroll") for (int n = 0; n < 2; ++n) _Pragma("unroll") for (int k = 0; k < 2; ++k)                             \
;       dst[n][k] = *(const bf16x8*)((const char*)G_SB(b, h) + ((wc * 2 + n) * 2 + k) * 1024 + rdo)
; #define G_WAIT_V(n) asm volatile("s_waitcnt vmcnt(" #n ")" ::: "memory")
; #define G_WAIT_L(n) asm volatile("s_waitcnt lgkmcnt(" #n ")" ::: "memory")
; #define G_BAR __builtin_amdgcn_s_barrier()
; #define G_SCHED __builtin_amdgcn_sched_barrier(0)
;     ...
;     G_STAGE(G_SB(0, 1), B, ob0, ob1, LDB, 128, KB(tt + 2));
;     G_WAIT_V(6); G_BAR; G_MMA(1, 1, At, B1); G_BAR;
;     G_LDB(B0, 1, 0); G_SCHED; G_LDA(At, 1, 0); G_STAGE(G_SA(0, 1), A, oa0, oa1, LDA, 128, KA(tt + 2));
;     G_WAIT_L(8); G_BAR; G_WAIT_L(0); G_MMA(0, 0, At, B0); G_BAR; G_SCHED;
;     G_LDB(B1, 1, 1); G_STAGE(G_SB(1, 0), B, ob0, ob1, LDB, 0, KB(tt + 3));
;     G_BAR; G_WAIT_L(0); G_MMA(0, 1, At, B1); G_BAR;
;     G_LDA(At, 1, 1); G_STAGE(G_SA(1, 0), A, oa0, oa1, LDA, 0, KA(tt + 3));
	v_readfirstlane_b32 s0, v148
	v_lshl_add_u64 v[164:165], v[246:247], 0, s[24:25]
	s_mov_b32 m0, s0
	v_readfirstlane_b32 s0, v149
	global_load_lds_dwordx4 v[164:165], off
	v_lshl_add_u64 v[164:165], v[248:249], 0, s[24:25]
	s_mov_b32 m0, s0
	s_nop 0
	global_load_lds_dwordx4 v[164:165], off
	s_waitcnt vmcnt(6)
	s_barrier
	v_mfma_f32_16x16x32_bf16 v[2:5], v[194:197], v[226:229], v[2:5]
	v_mfma_f32_16x16x32_bf16 v[58:61], v[194:197], v[234:237], v[58:61]
	v_mfma_f32_16x16x32_bf16 v[66:69], v[202:205], v[226:229], v[66:69]
	v_mfma_f32_16x16x32_bf16 v[70:73], v[202:205], v[234:237], v[70:73]
	v_mfma_f32_16x16x32_bf16 v[74:77], v[210:213], v[226:229], v[74:77]
	v_mfma_f32_16x16x32_bf16 v[82:85], v[210:213], v[234:237], v[82:85]
	v_mfma_f32_16x16x32_bf16 v[86:89], v[218:221], v[226:229], v[86:89]
	v_mfma_f32_16x16x32_bf16 v[90:93], v[218:221], v[234:237], v[90:93]
	v_mfma_f32_16x16x32_bf16 v[2:5], v[198:201], v[230:233], v[2:5]
	v_mfma_f32_16x16x32_bf16 v[58:61], v[198:201], v[238:241], v[58:61]
	v_mfma_f32_16x16x32_bf16 v[66:69], v[206:209], v[230:233], v[66:69]
	v_mfma_f32_16x16x32_bf16 v[70:73], v[206:209], v[238:241], v[70:73]
	v_mfma_f32_16x16x32_bf16 v[74:77], v[214:217], v[230:233], v[74:77]
	v_mfma_f32_16x16x32_bf16 v[82:85], v[214:217], v[238:241], v[82:85]
	v_mfma_f32_16x16x32_bf16 v[86:89], v[222:225], v[230:233], v[86:89]
	v_mfma_f32_16x16x32_bf16 v[90:93], v[222:225], v[238:241], v[90:93]
	s_barrier
	ds_read_b128 v[164:167], v150
	ds_read_b128 v[182:185], v150 offset:1024
	ds_read_b128 v[186:189], v150 offset:2048
	ds_read_b128 v[190:193], v150 offset:3072
	v_readfirstlane_b32 s0, v151
	v_lshl_add_u64 v[226:227], v[242:243], 0, s[86:87]
	s_mov_b32 m0, s0
	v_readfirstlane_b32 s0, v152
	ds_read_b128 v[194:197], v142 offset:32768
	ds_read_b128 v[198:201], v142 offset:33792
	ds_read_b128 v[202:205], v142 offset:34816
	ds_read_b128 v[206:209], v142 offset:35840
	ds_read_b128 v[210:213], v142 offset:36864
	ds_read_b128 v[214:217], v142 offset:37888
	ds_read_b128 v[218:221], v142 offset:38912
	ds_read_b128 v[222:225], v142 offset:39936
	global_load_lds_dwordx4 v[226:227], off
	v_lshl_add_u64 v[226:227], v[244:245], 0, s[86:87]
	s_mov_b32 m0, s0
	s_nop 0
	global_load_lds_dwordx4 v[226:227], off
	s_waitcnt lgkmcnt(8)
	s_barrier
	s_waitcnt lgkmcnt(0)
	v_mfma_f32_16x16x32_bf16 v[126:129], v[194:197], v[164:167], v[126:129]
	v_mfma_f32_16x16x32_bf16 v[122:125], v[194:197], v[186:189], v[122:125]
	v_mfma_f32_16x16x32_bf16 v[118:121], v[202:205], v[164:167], v[118:121]
	v_mfma_f32_16x16x32_bf16 v[114:117], v[202:205], v[186:189], v[114:117]
	v_mfma_f32_16x16x32_bf16 v[110:113], v[210:213], v[164:167], v[110:113]
	v_mfma_f32_16x16x32_bf16 v[106:109], v[210:213], v[186:189], v[106:109]
	v_mfma_f32_16x16x32_bf16 v[102:105], v[218:221], v[164:167], v[102:105]
	v_mfma_f32_16x16x32_bf16 v[98:101], v[218:221], v[186:189], v[98:101]
	v_mfma_f32_16x16x32_bf16 v[126:129], v[198:201], v[182:185], v[126:129]
	v_mfma_f32_16x16x32_bf16 v[122:125], v[198:201], v[190:193], v[122:125]
	v_mfma_f32_16x16x32_bf16 v[118:121], v[206:209], v[182:185], v[118:121]
	v_mfma_f32_16x16x32_bf16 v[114:117], v[206:209], v[190:193], v[114:117]
	v_mfma_f32_16x16x32_bf16 v[110:113], v[214:217], v[182:185], v[110:113]
	v_mfma_f32_16x16x32_bf16 v[106:109], v[214:217], v[190:193], v[106:109]
	v_mfma_f32_16x16x32_bf16 v[102:105], v[222:225], v[182:185], v[102:105]
	v_mfma_f32_16x16x32_bf16 v[98:101], v[222:225], v[190:193], v[98:101]
	s_barrier
	v_readfirstlane_b32 s0, v153
	v_lshl_add_u64 v[250:251], v[246:247], 0, s[36:37]
	s_mov_b32 m0, s0
	v_readfirstlane_b32 s0, v154
	ds_read_b128 v[226:229], v145
	ds_read_b128 v[230:233], v145 offset:1024
	ds_read_b128 v[234:237], v145 offset:2048
	ds_read_b128 v[238:241], v145 offset:3072
	global_load_lds_dwordx4 v[250:251], off
	v_lshl_add_u64 v[250:251], v[248:249], 0, s[36:37]
	s_mov_b32 m0, s0
	s_nop 0
	global_load_lds_dwordx4 v[250:251], off
	s_barrier
	s_waitcnt lgkmcnt(0)
	v_mfma_f32_16x16x32_bf16 v[94:97], v[194:197], v[226:229], v[94:97]
	v_mfma_f32_16x16x32_bf16 v[78:81], v[194:197], v[234:237], v[78:81]
	v_mfma_f32_16x16x32_bf16 v[62:65], v[202:205], v[226:229], v[62:65]
	v_mfma_f32_16x16x32_bf16 v[54:57], v[202:205], v[234:237], v[54:57]
	v_mfma_f32_16x16x32_bf16 v[50:53], v[210:213], v[226:229], v[50:53]
	v_mfma_f32_16x16x32_bf16 v[46:49], v[210:213], v[234:237], v[46:49]
	v_mfma_f32_16x16x32_bf16 v[42:45], v[218:221], v[226:229], v[42:45]
	v_mfma_f32_16x16x32_bf16 v[38:41], v[218:221], v[234:237], v[38:41]
	v_mfma_f32_16x16x32_bf16 v[94:97], v[198:201], v[230:233], v[94:97]
	v_mfma_f32_16x16x32_bf16 v[78:81], v[198:201], v[238:241], v[78:81]
	v_mfma_f32_16x16x32_bf16 v[62:65], v[206:209], v[230:233], v[62:65]
	v_mfma_f32_16x16x32_bf16 v[54:57], v[206:209], v[238:241], v[54:57]
	v_mfma_f32_16x16x32_bf16 v[50:53], v[214:217], v[230:233], v[50:53]
	v_mfma_f32_16x16x32_bf16 v[46:49], v[214:217], v[238:241], v[46:49]
	v_mfma_f32_16x16x32_bf16 v[42:45], v[222:225], v[230:233], v[42:45]
	v_mfma_f32_16x16x32_bf16 v[38:41], v[222:225], v[238:241], v[38:41]
	v_readfirstlane_b32 s0, v155
	v_lshl_add_u64 v[242:243], v[242:243], 0, s[90:91]
	s_mov_b32 m0, s0
	v_readfirstlane_b32 s0, v156
	s_barrier
	ds_read_b128 v[194:197], v142 offset:49152
	ds_read_b128 v[198:201], v142 offset:50176
	ds_read_b128 v[202:205], v142 offset:51200
	ds_read_b128 v[206:209], v142 offset:52224
	ds_read_b128 v[210:213], v142 offset:53248
	ds_read_b128 v[214:217], v142 offset:54272
	ds_read_b128 v[218:221], v142 offset:55296
	ds_read_b128 v[222:225], v142 offset:56320
	global_load_lds_dwordx4 v[242:243], off
	v_lshl_add_u64 v[242:243], v[244:245], 0, s[90:91]
	s_mov_b32 m0, s0
	s_nop 0
	global_load_lds_dwordx4 v[242:243], off
	s_barrier
; #define G_LDA(dst, b, h)                                                                                                  \
;   _Pragma("unroll") for (int m = 0; m < 4; ++m) _Pragma("unroll") for (int k = 0; k < 2; ++k)                             \
;       dst[m][k] = *(const bf16x8*)((const char*)G_SA(b, h) + ((wr * 4 + m) * 2 + k) * 1024 + rdo)
; #define G_LDB(dst, b, h)                                                                                                  \
;   _Pragma("unroll") for (int n = 0; n < 2; ++n) _Pragma("unroll") for (int k = 0; k < 2; ++k)                             \
;       dst[n][k] = *(const bf16x8*)((const char*)G_SB(b, h) + ((wc * 2 + n) * 2 + k) * 1024 + rdo)
; #define G_WAIT_V(n) asm volatile("s_waitcnt vmcnt(" #n ")" ::: "memory")
; #define G_WAIT_L(n) asm volatile("s_waitcnt lgkmcnt(" #n ")" ::: "memory")
; #define G_BAR __builtin_amdgcn_s_barrier()
; #define G_SCHED __builtin_amdgcn_sched_barrier(0)
; DI void br_flush(PREF p, f32x4 (&acc)[2][2][4][2], int slot) { br_store(p, acc, slot); zero_acc256(acc); }
;     ...
;     G_BAR; G_WAIT_L(0); G_MMA(1, 0, At, B0); G_BAR; G_SCHED;
;     G_STAGE(G_SB(1, 1), B, ob0, ob1, LDB, 128, KB(tt + 3));
;     G_WAIT_V(6); G_BAR; G_MMA(1, 1, At, B1); G_BAR;
;     if (MODE && ((tt + 1) & 3) == 3) br_flush(p, acc, (tt + 1) >> 2);
;   }
;   {
;     G_LDB(B0, 0, 0); G_LDA(At, 0, 0); G_STAGE(G_SA(1, 1), A, oa0, oa1, LDA, 128, KA(nt - 1));
;     G_BAR; G_WAIT_L(0); G_MMA(0, 0, At, B0); G_BAR;
;     G_LDB(B1, 0, 1); G_BAR; G_WAIT_L(0); G_MMA(0, 1, At, B1); G_BAR;
	s_waitcnt lgkmcnt(0)
	v_mfma_f32_16x16x32_bf16 v[34:37], v[194:197], v[164:167], v[34:37]
	v_mfma_f32_16x16x32_bf16 v[30:33], v[194:197], v[186:189], v[30:33]
	v_mfma_f32_16x16x32_bf16 v[26:29], v[202:205], v[164:167], v[26:29]
	v_mfma_f32_16x16x32_bf16 v[22:25], v[202:205], v[186:189], v[22:25]
	v_mfma_f32_16x16x32_bf16 v[18:21], v[210:213], v[164:167], v[18:21]
	v_mfma_f32_16x16x32_bf16 v[14:17], v[210:213], v[186:189], v[14:17]
	v_mfma_f32_16x16x32_bf16 v[10:13], v[218:221], v[164:167], v[10:13]
	v_mfma_f32_16x16x32_bf16 v[6:9], v[218:221], v[186:189], v[6:9]
	v_mfma_f32_16x16x32_bf16 v[34:37], v[198:201], v[182:185], v[34:37]
	v_mfma_f32_16x16x32_bf16 v[30:33], v[198:201], v[190:193], v[30:33]
	v_mfma_f32_16x16x32_bf16 v[26:29], v[206:209], v[182:185], v[26:29]
	v_mfma_f32_16x16x32_bf16 v[22:25], v[206:209], v[190:193], v[22:25]
	v_mfma_f32_16x16x32_bf16 v[18:21], v[214:217], v[182:185], v[18:21]
	v_mfma_f32_16x16x32_bf16 v[14:17], v[214:217], v[190:193], v[14:17]
	v_mfma_f32_16x16x32_bf16 v[10:13], v[222:225], v[182:185], v[10:13]
	v_mfma_f32_16x16x32_bf16 v[6:9], v[222:225], v[190:193], v[6:9]
	s_barrier
	v_readfirstlane_b32 s0, v157
	v_lshl_add_u64 v[164:165], v[246:247], 0, s[40:41]
	s_mov_b32 m0, s0
	v_readfirstlane_b32 s0, v158
	global_load_lds_dwordx4 v[164:165], off
	v_lshl_add_u64 v[164:165], v[248:249], 0, s[40:41]
	s_mov_b32 m0, s0
	s_nop 0
	global_load_lds_dwordx4 v[164:165], off
	s_waitcnt vmcnt(6)
	s_barrier
	v_mfma_f32_16x16x32_bf16 v[2:5], v[194:197], v[226:229], v[2:5]
	v_mfma_f32_16x16x32_bf16 v[58:61], v[194:197], v[234:237], v[58:61]
	v_mfma_f32_16x16x32_bf16 v[66:69], v[202:205], v[226:229], v[66:69]
	v_mfma_f32_16x16x32_bf16 v[70:73], v[202:205], v[234:237], v[70:73]
	v_mfma_f32_16x16x32_bf16 v[74:77], v[210:213], v[226:229], v[74:77]
	v_mfma_f32_16x16x32_bf16 v[82:85], v[210:213], v[234:237], v[82:85]
	v_mfma_f32_16x16x32_bf16 v[86:89], v[218:221], v[226:229], v[86:89]
	v_mfma_f32_16x16x32_bf16 v[90:93], v[218:221], v[234:237], v[90:93]
	v_mfma_f32_16x16x32_bf16 v[2:5], v[198:201], v[230:233], v[2:5]
	v_mfma_f32_16x16x32_bf16 v[58:61], v[198:201], v[238:241], v[58:61]
	v_mfma_f32_16x16x32_bf16 v[66:69], v[206:209], v[230:233], v[66:69]
	v_mfma_f32_16x16x32_bf16 v[70:73], v[206:209], v[238:241], v[70:73]
	v_mfma_f32_16x16x32_bf16 v[74:77], v[214:217], v[230:233], v[74:77]
	v_mfma_f32_16x16x32_bf16 v[82:85], v[214:217], v[238:241], v[82:85]
	v_mfma_f32_16x16x32_bf16 v[86:89], v[222:225], v[230:233], v[86:89]
	v_mfma_f32_16x16x32_bf16 v[90:93], v[222:225], v[238:241], v[90:93]
	s_add_i32 s22, s22, 2
	s_add_u32 s20, s20, 0x100
	s_addc_u32 s21, s21, 0
	s_cmp_lt_u32 s22, 12
	s_barrier
	s_cbranch_scc1 .LBB0_40
	s_add_u32 s0, s16, 0x40780
	s_addc_u32 s1, s17, 0
	v_readfirstlane_b32 s16, v161
	v_lshl_add_u64 v[132:133], v[132:133], 1, s[0:1]
	s_mov_b32 m0, s16
	v_lshl_add_u64 v[130:131], v[130:131], 1, s[0:1]
	v_readfirstlane_b32 s0, v160
	ds_read_b128 v[134:137], v162
	ds_read_b128 v[138:141], v162 offset:1024
	ds_read_b128 v[146:149], v162 offset:2048
	ds_read_b128 v[152:155], v162 offset:3072
	ds_read_b128 v[164:167], v142
	ds_read_b128 v[182:185], v142 offset:1024
	ds_read_b128 v[186:189], v142 offset:2048
	ds_read_b128 v[190:193], v142 offset:3072
	ds_read_b128 v[194:197], v142 offset:4096
	ds_read_b128 v[198:201], v142 offset:5120
	ds_read_b128 v[202:205], v142 offset:6144
	ds_read_b128 v[206:209], v142 offset:7168
	global_load_lds_dwordx4 v[132:133], off
	s_mov_b32 m0, s0
	s_nop 0
	global_load_lds_dwordx4 v[130:131], off
	s_barrier
	s_waitcnt lgkmcnt(0)
	v_mfma_f32_16x16x32_bf16 v[126:129], v[164:167], v[134:137], v[126:129]
	v_mfma_f32_16x16x32_bf16 v[122:125], v[164:167], v[146:149], v[122:125]
	v_mfma_f32_16x16x32_bf16 v[110:113], v[194:197], v[134:137], v[110:113]
	v_mfma_f32_16x16x32_bf16 v[102:105], v[202:205], v[134:137], v[102:105]
	v_mfma_f32_16x16x32_bf16 v[126:129], v[182:185], v[138:141], v[126:129]
	v_mfma_f32_16x16x32_bf16 v[122:125], v[182:185], v[152:155], v[122:125]
	v_mfma_f32_16x16x32_bf16 v[118:121], v[186:189], v[134:137], v[118:121]
	v_mfma_f32_16x16x32_bf16 v[114:117], v[186:189], v[146:149], v[114:117]
	v_mfma_f32_16x16x32_bf16 v[110:113], v[198:201], v[138:141], v[110:113]
	v_mfma_f32_16x16x32_bf16 v[106:109], v[194:197], v[146:149], v[106:109]
	v_mfma_f32_16x16x32_bf16 v[102:105], v[206:209], v[138:141], v[102:105]
	v_mfma_f32_16x16x32_bf16 v[98:101], v[202:205], v[146:149], v[98:101]
	v_mfma_f32_16x16x32_bf16 v[130:133], v[190:193], v[138:141], v[118:121]
	v_mfma_f32_16x16x32_bf16 v[210:213], v[190:193], v[152:155], v[114:117]
	v_mfma_f32_16x16x32_bf16 v[214:217], v[198:201], v[152:155], v[106:109]
	v_mfma_f32_16x16x32_bf16 v[218:221], v[206:209], v[152:155], v[98:101]
	s_barrier
	s_nop 1
	s_nop 0
	ds_read_b128 v[98:101], v159
	ds_read_b128 v[106:109], v159 offset:1024
	ds_read_b128 v[114:117], v159 offset:2048
	ds_read_b128 v[118:121], v159 offset:3072
	s_barrier
	s_waitcnt lgkmcnt(0)
	v_mfma_f32_16x16x32_bf16 v[94:97], v[164:167], v[98:101], v[94:97]
	v_mfma_f32_16x16x32_bf16 v[78:81], v[164:167], v[114:117], v[78:81]
	v_mfma_f32_16x16x32_bf16 v[62:65], v[186:189], v[98:101], v[62:65]
	v_mfma_f32_16x16x32_bf16 v[54:57], v[186:189], v[114:117], v[54:57]
	v_mfma_f32_16x16x32_bf16 v[50:53], v[194:197], v[98:101], v[50:53]
	v_mfma_f32_16x16x32_bf16 v[46:49], v[194:197], v[114:117], v[46:49]
	v_mfma_f32_16x16x32_bf16 v[42:45], v[202:205], v[98:101], v[42:45]
	v_mfma_f32_16x16x32_bf16 v[38:41], v[202:205], v[114:117], v[38:41]
	v_mfma_f32_16x16x32_bf16 v[94:97], v[182:185], v[106:109], v[94:97]
	v_mfma_f32_16x16x32_bf16 v[78:81], v[182:185], v[118:121], v[78:81]
	v_mfma_f32_16x16x32_bf16 v[62:65], v[190:193], v[106:109], v[62:65]
	v_mfma_f32_16x16x32_bf16 v[54:57], v[190:193], v[118:121], v[54:57]
	v_mfma_f32_16x16x32_bf16 v[50:53], v[198:201], v[106:109], v[50:53]
	v_mfma_f32_16x16x32_bf16 v[46:49], v[198:201], v[118:121], v[46:49]
	v_mfma_f32_16x16x32_bf16 v[42:45], v[206:209], v[106:109], v[42:45]
	v_mfma_f32_16x16x32_bf16 v[38:41], v[206:209], v[118:121], v[38:41]
	s_barrier
; #define G_LDA(dst, b, h)                                                                                                  \
;   _Pragma("unroll") for (int m = 0; m < 4; ++m) _Pragma("unroll") for (int k = 0; k < 2; ++k)                             \
;       dst[m][k] = *(const bf16x8*)((const char*)G_SA(b, h) + ((wr * 4 + m) * 2 + k) * 1024 + rdo)
; #define G_LDB(dst, b, h)                                                                                                  \
;   _Pragma("unroll") for (int n = 0; n < 2; ++n) _Pragma("unroll") for (int k = 0; k < 2; ++k)                             \
;       dst[n][k] = *(const bf16x8*)((const char*)G_SB(b, h) + ((wc * 2 + n) * 2 + k) * 1024 + rdo)
; #define G_WAIT_V(n) asm volatile("s_waitcnt vmcnt(" #n ")" ::: "memory")
; #define G_WAIT_L(n) asm volatile("s_waitcnt lgkmcnt(" #n ")" ::: "memory")
; #define G_BAR __builtin_amdgcn_s_barrier()
;     ...
;     G_LDA(At, 0, 1); G_WAIT_V(4); G_BAR; G_WAIT_L(0); G_MMA(1, 0, At, B0); G_MMA(1, 1, At, B1); G_BAR;
;   }
;   {
;     G_LDB(B0, 1, 0); G_LDA(At, 1, 0); G_WAIT_V(2); G_BAR; G_WAIT_L(0); G_MMA(0, 0, At, B0); G_BAR;
	ds_read_b128 v[156:159], v142 offset:16384
	ds_read_b128 v[164:167], v142 offset:17408
	ds_read_b128 v[182:185], v142 offset:18432
	ds_read_b128 v[186:189], v142 offset:19456
	ds_read_b128 v[190:193], v142 offset:20480
	ds_read_b128 v[194:197], v142 offset:21504
	ds_read_b128 v[198:201], v142 offset:22528
	ds_read_b128 v[202:205], v142 offset:23552
	s_waitcnt vmcnt(4)
	s_barrier
	s_waitcnt lgkmcnt(0)
	v_mfma_f32_16x16x32_bf16 v[34:37], v[156:159], v[134:137], v[34:37]
	v_mfma_f32_16x16x32_bf16 v[30:33], v[156:159], v[146:149], v[30:33]
	v_mfma_f32_16x16x32_bf16 v[26:29], v[182:185], v[134:137], v[26:29]
	v_mfma_f32_16x16x32_bf16 v[22:25], v[182:185], v[146:149], v[22:25]
	v_mfma_f32_16x16x32_bf16 v[18:21], v[190:193], v[134:137], v[18:21]
	v_mfma_f32_16x16x32_bf16 v[14:17], v[190:193], v[146:149], v[14:17]
	v_mfma_f32_16x16x32_bf16 v[10:13], v[198:201], v[134:137], v[10:13]
	v_mfma_f32_16x16x32_bf16 v[6:9], v[198:201], v[146:149], v[6:9]
	v_mfma_f32_16x16x32_bf16 v[34:37], v[164:167], v[138:141], v[34:37]
	v_mfma_f32_16x16x32_bf16 v[30:33], v[164:167], v[152:155], v[30:33]
	v_mfma_f32_16x16x32_bf16 v[26:29], v[186:189], v[138:141], v[26:29]
	v_mfma_f32_16x16x32_bf16 v[22:25], v[186:189], v[152:155], v[22:25]
	v_mfma_f32_16x16x32_bf16 v[18:21], v[194:197], v[138:141], v[18:21]
	v_mfma_f32_16x16x32_bf16 v[14:17], v[194:197], v[152:155], v[14:17]
	v_mfma_f32_16x16x32_bf16 v[10:13], v[202:205], v[138:141], v[10:13]
	v_mfma_f32_16x16x32_bf16 v[6:9], v[202:205], v[152:155], v[6:9]
	v_mfma_f32_16x16x32_bf16 v[58:61], v[156:159], v[114:117], v[58:61]
	v_mfma_f32_16x16x32_bf16 v[134:137], v[164:167], v[118:121], v[58:61]
	v_mfma_f32_16x16x32_bf16 v[58:61], v[182:185], v[98:101], v[66:69]
	v_mfma_f32_16x16x32_bf16 v[138:141], v[186:189], v[106:109], v[58:61]
	v_mfma_f32_16x16x32_bf16 v[58:61], v[182:185], v[114:117], v[70:73]
	v_mfma_f32_16x16x32_bf16 v[146:149], v[186:189], v[118:121], v[58:61]
	v_mfma_f32_16x16x32_bf16 v[58:61], v[190:193], v[98:101], v[74:77]
	v_mfma_f32_16x16x32_bf16 v[152:155], v[194:197], v[106:109], v[58:61]
	v_mfma_f32_16x16x32_bf16 v[58:61], v[190:193], v[114:117], v[82:85]
	v_mfma_f32_16x16x32_bf16 v[2:5], v[156:159], v[98:101], v[2:5]
	v_mfma_f32_16x16x32_bf16 v[156:159], v[194:197], v[118:121], v[58:61]
	v_mfma_f32_16x16x32_bf16 v[58:61], v[198:201], v[98:101], v[86:89]
	v_mfma_f32_16x16x32_bf16 v[2:5], v[164:167], v[106:109], v[2:5]
	v_mfma_f32_16x16x32_bf16 v[164:167], v[202:205], v[106:109], v[58:61]
	v_mfma_f32_16x16x32_bf16 v[58:61], v[198:201], v[114:117], v[90:93]
	v_mfma_f32_16x16x32_bf16 v[182:185], v[202:205], v[118:121], v[58:61]
	s_barrier
	ds_read_b128 v[186:189], v150
	ds_read_b128 v[190:193], v150 offset:1024
	ds_read_b128 v[194:197], v150 offset:2048
	ds_read_b128 v[198:201], v150 offset:3072
	s_nop 0
	s_nop 0
	ds_read_b128 v[58:61], v142 offset:32768
	ds_read_b128 v[66:69], v142 offset:33792
	ds_read_b128 v[70:73], v142 offset:34816
	ds_read_b128 v[74:77], v142 offset:35840
	ds_read_b128 v[202:205], v142 offset:36864
	ds_read_b128 v[206:209], v142 offset:37888
	ds_read_b128 v[222:225], v142 offset:38912
	ds_read_b128 v[226:229], v142 offset:39936
	s_waitcnt vmcnt(2)
	s_barrier
	s_waitcnt lgkmcnt(0)
	v_mfma_f32_16x16x32_bf16 v[82:85], v[58:61], v[186:189], v[126:129]
	v_mfma_f32_16x16x32_bf16 v[118:121], v[66:69], v[190:193], v[82:85]
	v_mfma_f32_16x16x32_bf16 v[82:85], v[58:61], v[194:197], v[122:125]
	v_mfma_f32_16x16x32_bf16 v[126:129], v[66:69], v[198:201], v[82:85]
	v_mfma_f32_16x16x32_bf16 v[82:85], v[70:73], v[186:189], v[130:133]
	v_mfma_f32_16x16x32_bf16 v[114:117], v[74:77], v[190:193], v[82:85]
	v_mfma_f32_16x16x32_bf16 v[82:85], v[70:73], v[194:197], v[210:213]
	v_mfma_f32_16x16x32_bf16 v[122:125], v[74:77], v[198:201], v[82:85]
	v_mfma_f32_16x16x32_bf16 v[82:85], v[202:205], v[186:189], v[110:113]
	v_mfma_f32_16x16x32_bf16 v[106:109], v[206:209], v[190:193], v[82:85]
	v_mfma_f32_16x16x32_bf16 v[82:85], v[202:205], v[194:197], v[214:217]
	v_mfma_f32_16x16x32_bf16 v[110:113], v[206:209], v[198:201], v[82:85]
	v_mfma_f32_16x16x32_bf16 v[82:85], v[222:225], v[186:189], v[102:105]
	v_mfma_f32_16x16x32_bf16 v[98:101], v[226:229], v[190:193], v[82:85]
	v_mfma_f32_16x16x32_bf16 v[82:85], v[222:225], v[194:197], v[218:221]
	v_mfma_f32_16x16x32_bf16 v[102:105], v[226:229], v[198:201], v[82:85]
	s_barrier
; #define G_LDA(dst, b, h)                                                                                                  \
;   _Pragma("unroll") for (int m = 0; m < 4; ++m) _Pragma("unroll") for (int k = 0; k < 2; ++k)                             \
;       dst[m][k] = *(const bf16x8*)((const char*)G_SA(b, h) + ((wr * 4 + m) * 2 + k) * 1024 + rdo)
; #define G_LDB(dst, b, h)                                                                                                  \
;   _Pragma("unroll") for (int n = 0; n < 2; ++n) _Pragma("unroll") for (int k = 0; k < 2; ++k)                             \
;       dst[n][k] = *(const bf16x8*)((const char*)G_SB(b, h) + ((wc * 2 + n) * 2 + k) * 1024 + rdo)
; #define G_WAIT_V(n) asm volatile("s_waitcnt vmcnt(" #n ")" ::: "memory")
; #define G_WAIT_L(n) asm volatile("s_waitcnt lgkmcnt(" #n ")" ::: "memory")
; #define G_BAR __builtin_amdgcn_s_barrier()
;     ...
;     G_LDB(B1, 1, 1); G_WAIT_V(0); G_BAR; G_WAIT_L(0); G_MMA(0, 1, At, B1); G_BAR;
;     G_LDA(At, 1, 1); G_BAR; G_WAIT_L(0); G_MMA(1, 0, At, B0); G_MMA(1, 1, At, B1); G_BAR;
;   }
;   if (wr == 0) G_BAR;
	ds_read_b128 v[130:133], v145
	ds_read_b128 v[210:213], v145 offset:1024
	ds_read_b128 v[214:217], v145 offset:2048
	ds_read_b128 v[218:221], v145 offset:3072
	s_waitcnt vmcnt(0)
	s_barrier
	s_waitcnt lgkmcnt(0)
	v_mfma_f32_16x16x32_bf16 v[82:85], v[58:61], v[130:133], v[94:97]
	v_mfma_f32_16x16x32_bf16 v[58:61], v[58:61], v[214:217], v[78:81]
	v_mfma_f32_16x16x32_bf16 v[94:97], v[66:69], v[218:221], v[58:61]
	v_mfma_f32_16x16x32_bf16 v[58:61], v[70:73], v[130:133], v[62:65]
	v_mfma_f32_16x16x32_bf16 v[54:57], v[70:73], v[214:217], v[54:57]
	v_mfma_f32_16x16x32_bf16 v[50:53], v[202:205], v[130:133], v[50:53]
	v_mfma_f32_16x16x32_bf16 v[46:49], v[202:205], v[214:217], v[46:49]
	v_mfma_f32_16x16x32_bf16 v[42:45], v[222:225], v[130:133], v[42:45]
	v_mfma_f32_16x16x32_bf16 v[38:41], v[222:225], v[214:217], v[38:41]
	v_mfma_f32_16x16x32_bf16 v[86:89], v[66:69], v[210:213], v[82:85]
	v_mfma_f32_16x16x32_bf16 v[82:85], v[74:77], v[210:213], v[58:61]
	v_mfma_f32_16x16x32_bf16 v[90:93], v[74:77], v[218:221], v[54:57]
	v_mfma_f32_16x16x32_bf16 v[74:77], v[206:209], v[210:213], v[50:53]
	v_mfma_f32_16x16x32_bf16 v[78:81], v[206:209], v[218:221], v[46:49]
	v_mfma_f32_16x16x32_bf16 v[66:69], v[226:229], v[210:213], v[42:45]
	v_mfma_f32_16x16x32_bf16 v[70:73], v[226:229], v[218:221], v[38:41]
	s_barrier
	ds_read_b128 v[202:205], v142 offset:49152
	ds_read_b128 v[206:209], v142 offset:50176
	ds_read_b128 v[222:225], v142 offset:51200
	ds_read_b128 v[226:229], v142 offset:52224
	ds_read_b128 v[230:233], v142 offset:53248
	ds_read_b128 v[234:237], v142 offset:54272
	ds_read_b128 v[238:241], v142 offset:55296
	ds_read_b128 v[142:145], v142 offset:56320
	s_barrier
	s_waitcnt lgkmcnt(0)
	v_mfma_f32_16x16x32_bf16 v[34:37], v[202:205], v[186:189], v[34:37]
	v_mfma_f32_16x16x32_bf16 v[30:33], v[202:205], v[194:197], v[30:33]
	v_mfma_f32_16x16x32_bf16 v[26:29], v[222:225], v[186:189], v[26:29]
	v_mfma_f32_16x16x32_bf16 v[22:25], v[222:225], v[194:197], v[22:25]
	v_mfma_f32_16x16x32_bf16 v[18:21], v[230:233], v[186:189], v[18:21]
	v_mfma_f32_16x16x32_bf16 v[14:17], v[230:233], v[194:197], v[14:17]
	v_mfma_f32_16x16x32_bf16 v[10:13], v[238:241], v[186:189], v[10:13]
	v_mfma_f32_16x16x32_bf16 v[6:9], v[238:241], v[194:197], v[6:9]
	v_mfma_f32_16x16x32_bf16 v[54:57], v[206:209], v[190:193], v[34:37]
	v_mfma_f32_16x16x32_bf16 v[62:65], v[206:209], v[198:201], v[30:33]
	v_mfma_f32_16x16x32_bf16 v[50:53], v[226:229], v[190:193], v[26:29]
	v_mfma_f32_16x16x32_bf16 v[58:61], v[226:229], v[198:201], v[22:25]
	v_mfma_f32_16x16x32_bf16 v[42:45], v[234:237], v[190:193], v[18:21]
	v_mfma_f32_16x16x32_bf16 v[46:49], v[234:237], v[198:201], v[14:17]
	v_mfma_f32_16x16x32_bf16 v[34:37], v[142:145], v[190:193], v[10:13]
	v_mfma_f32_16x16x32_bf16 v[38:41], v[142:145], v[198:201], v[6:9]
	v_mfma_f32_16x16x32_bf16 v[2:5], v[202:205], v[130:133], v[2:5]
	v_mfma_f32_16x16x32_bf16 v[22:25], v[206:209], v[210:213], v[2:5]
	v_mfma_f32_16x16x32_bf16 v[2:5], v[202:205], v[214:217], v[134:137]
	v_mfma_f32_16x16x32_bf16 v[30:33], v[206:209], v[218:221], v[2:5]
	v_mfma_f32_16x16x32_bf16 v[2:5], v[222:225], v[130:133], v[138:141]
	v_mfma_f32_16x16x32_bf16 v[18:21], v[226:229], v[210:213], v[2:5]
	v_mfma_f32_16x16x32_bf16 v[2:5], v[222:225], v[214:217], v[146:149]
	v_mfma_f32_16x16x32_bf16 v[26:29], v[226:229], v[218:221], v[2:5]
	v_mfma_f32_16x16x32_bf16 v[2:5], v[230:233], v[130:133], v[152:155]
	v_mfma_f32_16x16x32_bf16 v[10:13], v[234:237], v[210:213], v[2:5]
	v_mfma_f32_16x16x32_bf16 v[2:5], v[230:233], v[214:217], v[156:159]
	v_mfma_f32_16x16x32_bf16 v[14:17], v[234:237], v[218:221], v[2:5]
	v_mfma_f32_16x16x32_bf16 v[2:5], v[238:241], v[130:133], v[164:167]
	v_mfma_f32_16x16x32_bf16 v[6:9], v[238:241], v[214:217], v[182:185]
	v_mfma_f32_16x16x32_bf16 v[2:5], v[142:145], v[210:213], v[2:5]
	v_mfma_f32_16x16x32_bf16 v[6:9], v[142:145], v[218:221], v[6:9]
	v_cmp_gt_u32_e32 vcc, s67, v0
	s_barrier
	s_and_saveexec_b64 s[16:17], vcc
	s_cbranch_execz .LBB0_43
	s_barrier

; DI void lds_barrier() { asm volatile("s_waitcnt lgkmcnt(0)\n\ts_barrier" ::: "memory"); }
; #define G_LDA(dst, b, h)                                                                                                  \
;   _Pragma("unroll") for (int m = 0; m < 4; ++m) _Pragma("unroll") for (int k = 0; k < 2; ++k)                             \
;       dst[m][k] = *(const bf16x8*)((const char*)G_SA(b, h) + ((wr * 4 + m) * 2 + k) * 1024 + rdo)
; #define G_LDB(dst, b, h)                                                                                                  \
;   _Pragma("unroll") for (int n = 0; n < 2; ++n) _Pragma("unroll") for (int k = 0; k < 2; ++k)                             \
;       dst[n][k] = *(const bf16x8*)((const char*)G_SB(b, h) + ((wc * 2 + n) * 2 + k) * 1024 + rdo)
; #define G_WAIT_V(n) asm volatile("s_waitcnt vmcnt(" #n ")" ::: "memory")
; #define G_WAIT_L(n) asm volatile("s_waitcnt lgkmcnt(" #n ")" ::: "memory")
; #define G_BAR __builtin_amdgcn_s_barrier()
; #define G_SCHED __builtin_amdgcn_sched_barrier(0)
;     ...
;   lds_barrier();
;   G_STAGE(G_SB(0, 0), B, ob0, ob1, LDB, 0, KB(0)); G_STAGE(G_SA(0, 0), A, oa0, oa1, LDA, 0, KA(0));
;   G_STAGE(G_SB(0, 1), B, ob0, ob1, LDB, 128, KB(0)); G_STAGE(G_SA(0, 1), A, oa0, oa1, LDA, 128, KA(0));
;   if (wr == 1) G_BAR;
;   G_WAIT_V(4); G_BAR;
;   G_STAGE(G_SB(1, 0), B, ob0, ob1, LDB, 0, KB(1)); G_STAGE(G_SA(1, 0), A, oa0, oa1, LDA, 0, KA(1)); G_STAGE(G_SB(1, 1), B, ob0, ob1, LDB, 128, KB(1));
;   G_WAIT_V(6); G_BAR;
;   for (int tt = 0; tt < nt - 2; tt += 2) {
;     G_LDB(B0, 0, 0); G_SCHED; G_LDA(At, 0, 0); G_STAGE(G_SA(1, 1), A, oa0, oa1, LDA, 128, KA(tt + 1));
;     G_WAIT_L(8); G_BAR; G_WAIT_L(0); G_MMA(0, 0, At, B0); G_BAR; G_SCHED;
;     G_LDB(B1, 0, 1); G_STAGE(G_SB(0, 0), B, ob0, ob1, LDB, 0, KB(tt + 2));
;     G_BAR; G_WAIT_L(0); G_MMA(0, 1, At, B1); G_BAR;
.LBB0_45:
	s_or_b64 exec, exec, s[22:23]
	v_add_u32_e32 v13, 0x18000, v18
	v_lshl_add_u64 v[24:25], v[6:7], 0, s[76:77]
	v_readfirstlane_b32 s37, v13
	v_add_u32_e32 v13, 0x1a000, v18
	s_mov_b32 m0, s37
	v_readfirstlane_b32 s40, v13
	v_add_u32_e32 v13, 0x8000, v18
	s_waitcnt vmcnt(4)
	s_barrier
	global_load_lds_dwordx4 v[24:25], off
	v_lshl_add_u64 v[24:25], v[8:9], 0, s[76:77]
	s_mov_b32 m0, s40
	v_readfirstlane_b32 s35, v13
	v_add_u32_e32 v13, 0xa000, v18
	global_load_lds_dwordx4 v[24:25], off
	v_lshl_add_u64 v[24:25], v[10:11], 0, s[76:77]
	s_mov_b32 m0, s35
	v_readfirstlane_b32 s36, v13
	s_add_u32 s0, s18, 0x10080
	v_add_u32_e32 v13, 0x1c000, v18
	global_load_lds_dwordx4 v[24:25], off
	v_lshl_add_u64 v[24:25], v[14:15], 0, s[76:77]
	s_mov_b32 m0, s36
	s_addc_u32 s1, s19, 0
	v_readfirstlane_b32 s22, v13
	v_add_u32_e32 v13, 0x1e000, v18
	global_load_lds_dwordx4 v[24:25], off
	v_lshl_add_u64 v[24:25], s[0:1], 0, v[2:3]
	s_mov_b32 m0, s22
	v_readfirstlane_b32 s23, v13
	global_load_lds_dwordx4 v[24:25], off
	v_lshl_add_u64 v[24:25], s[0:1], 0, v[4:5]
	s_mov_b32 m0, s23
	v_lshlrev_b32_e32 v26, 2, v0
	global_load_lds_dwordx4 v[24:25], off
	v_lshlrev_b32_e32 v24, 6, v0
	v_and_b32_e32 v13, 48, v0
	v_and_b32_e32 v25, 0x3c0, v24
	v_and_b32_e32 v41, 32, v26
	v_or_b32_e32 v40, v25, v13
	v_bitop3_b32 v13, v25, v41, v13 bitop3:0x36
	s_movk_i32 s0, 0x3000
	v_and_or_b32 v162, v24, s0, v13
	s_add_u32 s0, s20, 0x10080
	s_addc_u32 s1, s21, 0
	v_lshl_add_u64 v[72:73], s[0:1], 0, v[2:3]
	v_lshl_add_u64 v[74:75], s[0:1], 0, v[4:5]
	s_add_u32 s0, s18, 0x10100
	s_addc_u32 s1, s19, 0
	v_or_b32_e32 v230, 0x10000, v162
	v_or_b32_e32 v232, 0x10800, v162
	s_waitcnt vmcnt(6)
	s_barrier
	v_lshl_add_u64 v[160:161], s[0:1], 0, v[2:3]
	v_lshl_add_u64 v[194:195], s[0:1], 0, v[4:5]
	s_add_u32 s0, s20, 0x10100
	v_or_b32_e32 v231, 0x10400, v162
	ds_read_b128 v[24:27], v230
	ds_read_b128 v[28:31], v231
	v_or_b32_e32 v233, 0x10c00, v162
	ds_read_b128 v[32:35], v232
	ds_read_b128 v[36:39], v233
	s_addc_u32 s1, s21, 0
	v_lshl_add_u64 v[214:215], s[0:1], 0, v[2:3]
	v_lshl_add_u64 v[216:217], s[0:1], 0, v[4:5]
	s_add_u32 s0, s18, 0x10180
	s_addc_u32 s1, s19, 0
	v_lshlrev_b32_e32 v42, 13, v12
	v_lshl_add_u64 v[120:121], v[6:7], 0, s[82:83]
	v_lshl_add_u64 v[122:123], v[8:9], 0, s[82:83]
	v_lshl_add_u64 v[152:153], v[10:11], 0, s[82:83]
	v_lshl_add_u64 v[226:227], v[6:7], 0, s[90:91]
	v_lshl_add_u64 v[228:229], v[8:9], 0, s[90:91]
	v_lshl_add_u64 v[12:13], v[10:11], 0, s[90:91]
	v_lshl_add_u64 v[10:11], v[14:15], 0, s[90:91]
	v_lshl_add_u64 v[8:9], s[0:1], 0, v[2:3]
	v_lshl_add_u64 v[6:7], s[0:1], 0, v[4:5]
	v_lshl_add_u64 v[154:155], v[14:15], 0, s[82:83]
	v_add_u32_e32 v14, 0xc000, v18
	v_bitop3_b32 v242, v40, v42, v41 bitop3:0xde
	v_readfirstlane_b32 s19, v14
	v_add_u32_e32 v14, 0xe000, v18
	s_mov_b32 m0, s19
	v_readfirstlane_b32 s18, v14
	ds_read_b128 v[40:43], v242
	ds_read_b128 v[44:47], v242 offset:1024
	ds_read_b128 v[48:51], v242 offset:2048
	ds_read_b128 v[52:55], v242 offset:3072
	ds_read_b128 v[56:59], v242 offset:4096
	ds_read_b128 v[60:63], v242 offset:5120
	ds_read_b128 v[64:67], v242 offset:6144
	ds_read_b128 v[68:71], v242 offset:7168
	global_load_lds_dwordx4 v[72:73], off
	s_mov_b32 m0, s18
	s_nop 0
	global_load_lds_dwordx4 v[74:75], off
	s_waitcnt lgkmcnt(8)
	s_barrier
	s_waitcnt lgkmcnt(0)
	v_mfma_f32_16x16x32_bf16 v[72:75], v[40:43], v[24:27], 0
	v_mfma_f32_16x16x32_bf16 v[76:79], v[40:43], v[32:35], 0
	v_mfma_f32_16x16x32_bf16 v[80:83], v[48:51], v[24:27], 0
	v_mfma_f32_16x16x32_bf16 v[84:87], v[48:51], v[32:35], 0
	v_mfma_f32_16x16x32_bf16 v[88:91], v[56:59], v[24:27], 0
	v_mfma_f32_16x16x32_bf16 v[92:95], v[56:59], v[32:35], 0
	v_mfma_f32_16x16x32_bf16 v[96:99], v[64:67], v[24:27], 0
	v_mfma_f32_16x16x32_bf16 v[100:103], v[64:67], v[32:35], 0
	v_mfma_f32_16x16x32_bf16 v[72:75], v[44:47], v[28:31], v[72:75]
	v_mfma_f32_16x16x32_bf16 v[76:79], v[44:47], v[36:39], v[76:79]
	v_mfma_f32_16x16x32_bf16 v[80:83], v[52:55], v[28:31], v[80:83]
	v_mfma_f32_16x16x32_bf16 v[84:87], v[52:55], v[36:39], v[84:87]
	v_mfma_f32_16x16x32_bf16 v[88:91], v[60:63], v[28:31], v[88:91]
	v_mfma_f32_16x16x32_bf16 v[92:95], v[60:63], v[36:39], v[92:95]
	v_mfma_f32_16x16x32_bf16 v[96:99], v[68:71], v[28:31], v[96:99]
	v_mfma_f32_16x16x32_bf16 v[100:103], v[68:71], v[36:39], v[100:103]
	s_barrier
	v_readfirstlane_b32 s0, v22
	v_or_b32_e32 v234, 0x14000, v162
	v_or_b32_e32 v236, 0x14800, v162
	s_mov_b32 m0, s0
	v_readfirstlane_b32 s0, v23
	v_or_b32_e32 v235, 0x14400, v162
	ds_read_b128 v[104:107], v234
	ds_read_b128 v[108:111], v235
	v_or_b32_e32 v237, 0x14c00, v162
	ds_read_b128 v[112:115], v236
	ds_read_b128 v[116:119], v237
	global_load_lds_dwordx4 v[120:121], off
	s_mov_b32 m0, s0
	s_nop 0
	global_load_lds_dwordx4 v[122:123], off
	s_barrier
	s_waitcnt lgkmcnt(0)
	v_mfma_f32_16x16x32_bf16 v[120:123], v[40:43], v[104:107], 0
	v_mfma_f32_16x16x32_bf16 v[40:43], v[40:43], v[112:115], 0
	v_mfma_f32_16x16x32_bf16 v[120:123], v[44:47], v[108:111], v[120:123]
	v_mfma_f32_16x16x32_bf16 v[40:43], v[44:47], v[116:119], v[40:43]
	v_mfma_f32_16x16x32_bf16 v[44:47], v[48:51], v[104:107], 0
	v_mfma_f32_16x16x32_bf16 v[48:51], v[48:51], v[112:115], 0
	v_mfma_f32_16x16x32_bf16 v[44:47], v[52:55], v[108:111], v[44:47]
	v_mfma_f32_16x16x32_bf16 v[48:51], v[52:55], v[116:119], v[48:51]
	v_mfma_f32_16x16x32_bf16 v[52:55], v[56:59], v[104:107], 0
	v_mfma_f32_16x16x32_bf16 v[56:59], v[56:59], v[112:115], 0
	v_mfma_f32_16x16x32_bf16 v[52:55], v[60:63], v[108:111], v[52:55]
	v_mfma_f32_16x16x32_bf16 v[56:59], v[60:63], v[116:119], v[56:59]
	v_mfma_f32_16x16x32_bf16 v[60:63], v[64:67], v[104:107], 0
	v_mfma_f32_16x16x32_bf16 v[64:67], v[64:67], v[112:115], 0
	v_mfma_f32_16x16x32_bf16 v[60:63], v[68:71], v[108:111], v[60:63]
	v_mfma_f32_16x16x32_bf16 v[64:67], v[68:71], v[116:119], v[64:67]
	v_readfirstlane_b32 s0, v18
	s_mov_b32 m0, s0
	v_readfirstlane_b32 s0, v19
	s_barrier
; #define G_LDA(dst, b, h)                                                                                                  \
;   _Pragma("unroll") for (int m = 0; m < 4; ++m) _Pragma("unroll") for (int k = 0; k < 2; ++k)                             \
;       dst[m][k] = *(const bf16x8*)((const char*)G_SA(b, h) + ((wr * 4 + m) * 2 + k) * 1024 + rdo)
; #define G_LDB(dst, b, h)                                                                                                  \
;   _Pragma("unroll") for (int n = 0; n < 2; ++n) _Pragma("unroll") for (int k = 0; k < 2; ++k)                             \
;       dst[n][k] = *(const bf16x8*)((const char*)G_SB(b, h) + ((wc * 2 + n) * 2 + k) * 1024 + rdo)
; #define G_WAIT_V(n) asm volatile("s_waitcnt vmcnt(" #n ")" ::: "memory")
; #define G_WAIT_L(n) asm volatile("s_waitcnt lgkmcnt(" #n ")" ::: "memory")
; #define G_BAR __builtin_amdgcn_s_barrier()
; #define G_SCHED __builtin_amdgcn_sched_barrier(0)
;     ...
;     G_LDA(At, 0, 1); G_STAGE(G_SA(0, 0), A, oa0, oa1, LDA, 0, KA(tt + 2));
;     G_BAR; G_WAIT_L(0); G_MMA(1, 0, At, B0); G_BAR; G_SCHED;
;     G_STAGE(G_SB(0, 1), B, ob0, ob1, LDB, 128, KB(tt + 2));
;     G_WAIT_V(6); G_BAR; G_MMA(1, 1, At, B1); G_BAR;
;     G_LDB(B0, 1, 0); G_SCHED; G_LDA(At, 1, 0); G_STAGE(G_SA(0, 1), A, oa0, oa1, LDA, 128, KA(tt + 2));
;     G_WAIT_L(8); G_BAR; G_WAIT_L(0); G_MMA(0, 0, At, B0); G_BAR; G_SCHED;
;     G_LDB(B1, 1, 1); G_STAGE(G_SB(1, 0), B, ob0, ob1, LDB, 0, KB(tt + 3));
	ds_read_b128 v[68:71], v242 offset:16384
	ds_read_b128 v[124:127], v242 offset:17408
	ds_read_b128 v[128:131], v242 offset:18432
	ds_read_b128 v[132:135], v242 offset:19456
	ds_read_b128 v[136:139], v242 offset:20480
	ds_read_b128 v[140:143], v242 offset:21504
	ds_read_b128 v[144:147], v242 offset:22528
	ds_read_b128 v[148:151], v242 offset:23552
	global_load_lds_dwordx4 v[152:153], off
	s_mov_b32 m0, s0
	s_nop 0
	global_load_lds_dwordx4 v[154:155], off
	s_barrier
	s_waitcnt lgkmcnt(0)
	v_mfma_f32_16x16x32_bf16 v[152:155], v[68:71], v[24:27], 0
	v_mfma_f32_16x16x32_bf16 v[164:167], v[128:131], v[24:27], 0
	v_mfma_f32_16x16x32_bf16 v[186:189], v[136:139], v[24:27], 0
	v_mfma_f32_16x16x32_bf16 v[22:25], v[144:147], v[24:27], 0
	v_mfma_f32_16x16x32_bf16 v[152:155], v[124:127], v[28:31], v[152:155]
	v_mfma_f32_16x16x32_bf16 v[164:167], v[132:135], v[28:31], v[164:167]
	v_mfma_f32_16x16x32_bf16 v[186:189], v[140:143], v[28:31], v[186:189]
	v_mfma_f32_16x16x32_bf16 v[22:25], v[148:151], v[28:31], v[22:25]
	v_mfma_f32_16x16x32_bf16 v[26:29], v[144:147], v[32:35], 0
	v_mfma_f32_16x16x32_bf16 v[156:159], v[68:71], v[32:35], 0
	v_mfma_f32_16x16x32_bf16 v[182:185], v[128:131], v[32:35], 0
	v_mfma_f32_16x16x32_bf16 v[190:193], v[136:139], v[32:35], 0
	v_mfma_f32_16x16x32_bf16 v[26:29], v[148:151], v[36:39], v[26:29]
	v_mfma_f32_16x16x32_bf16 v[156:159], v[124:127], v[36:39], v[156:159]
	v_mfma_f32_16x16x32_bf16 v[182:185], v[132:135], v[36:39], v[182:185]
	v_mfma_f32_16x16x32_bf16 v[190:193], v[140:143], v[36:39], v[190:193]
	s_barrier
	v_readfirstlane_b32 s0, v20
	s_mov_b32 m0, s0
	v_readfirstlane_b32 s0, v21
	global_load_lds_dwordx4 v[160:161], off
	s_mov_b32 m0, s0
	s_nop 0
	global_load_lds_dwordx4 v[194:195], off
	s_waitcnt vmcnt(6)
	s_barrier
	v_mfma_f32_16x16x32_bf16 v[18:21], v[68:71], v[104:107], 0
	v_mfma_f32_16x16x32_bf16 v[30:33], v[68:71], v[112:115], 0
	v_mfma_f32_16x16x32_bf16 v[18:21], v[124:127], v[108:111], v[18:21]
	v_mfma_f32_16x16x32_bf16 v[30:33], v[124:127], v[116:119], v[30:33]
	v_mfma_f32_16x16x32_bf16 v[34:37], v[128:131], v[104:107], 0
	v_mfma_f32_16x16x32_bf16 v[124:127], v[136:139], v[104:107], 0
	v_mfma_f32_16x16x32_bf16 v[104:107], v[144:147], v[104:107], 0
	v_mfma_f32_16x16x32_bf16 v[34:37], v[132:135], v[108:111], v[34:37]
	v_mfma_f32_16x16x32_bf16 v[68:71], v[128:131], v[112:115], 0
	v_mfma_f32_16x16x32_bf16 v[124:127], v[140:143], v[108:111], v[124:127]
	v_mfma_f32_16x16x32_bf16 v[128:131], v[136:139], v[112:115], 0
	v_mfma_f32_16x16x32_bf16 v[104:107], v[148:151], v[108:111], v[104:107]
	v_mfma_f32_16x16x32_bf16 v[108:111], v[144:147], v[112:115], 0
	v_mfma_f32_16x16x32_bf16 v[68:71], v[132:135], v[116:119], v[68:71]
	v_mfma_f32_16x16x32_bf16 v[128:131], v[140:143], v[116:119], v[128:131]
	v_mfma_f32_16x16x32_bf16 v[108:111], v[148:151], v[116:119], v[108:111]
	v_or_b32_e32 v160, 0x18000, v162
	v_or_b32_e32 v238, 0x18800, v162
	s_barrier
	v_or_b32_e32 v161, 0x18400, v162
	ds_read_b128 v[112:115], v160
	ds_read_b128 v[116:119], v161
	v_or_b32_e32 v239, 0x18c00, v162
	ds_read_b128 v[132:135], v238
	ds_read_b128 v[136:139], v239
	v_readfirstlane_b32 s0, v16
	s_mov_b32 m0, s0
	v_readfirstlane_b32 s0, v17
	ds_read_b128 v[140:143], v242 offset:32768
	ds_read_b128 v[144:147], v242 offset:33792
	ds_read_b128 v[148:151], v242 offset:34816
	ds_read_b128 v[194:197], v242 offset:35840
	ds_read_b128 v[198:201], v242 offset:36864
	ds_read_b128 v[202:205], v242 offset:37888
	ds_read_b128 v[206:209], v242 offset:38912
	ds_read_b128 v[210:213], v242 offset:39936
	global_load_lds_dwordx4 v[214:215], off
	s_mov_b32 m0, s0
	s_nop 0
	global_load_lds_dwordx4 v[216:217], off
	s_waitcnt lgkmcnt(8)
	s_barrier
	s_waitcnt lgkmcnt(0)
	v_mfma_f32_16x16x32_bf16 v[14:17], v[140:143], v[112:115], v[72:75]
	v_mfma_f32_16x16x32_bf16 v[72:75], v[140:143], v[132:135], v[76:79]
	v_mfma_f32_16x16x32_bf16 v[76:79], v[148:151], v[112:115], v[80:83]
	v_mfma_f32_16x16x32_bf16 v[80:83], v[148:151], v[132:135], v[84:87]
	v_mfma_f32_16x16x32_bf16 v[84:87], v[198:201], v[112:115], v[88:91]
	v_mfma_f32_16x16x32_bf16 v[88:91], v[198:201], v[132:135], v[92:95]
	v_mfma_f32_16x16x32_bf16 v[92:95], v[206:209], v[112:115], v[96:99]
	v_mfma_f32_16x16x32_bf16 v[96:99], v[206:209], v[132:135], v[100:103]
	v_mfma_f32_16x16x32_bf16 v[14:17], v[144:147], v[116:119], v[14:17]
	v_mfma_f32_16x16x32_bf16 v[72:75], v[144:147], v[136:139], v[72:75]
	v_mfma_f32_16x16x32_bf16 v[76:79], v[194:197], v[116:119], v[76:79]
	v_mfma_f32_16x16x32_bf16 v[80:83], v[194:197], v[136:139], v[80:83]
	v_mfma_f32_16x16x32_bf16 v[84:87], v[202:205], v[116:119], v[84:87]
	v_mfma_f32_16x16x32_bf16 v[88:91], v[202:205], v[136:139], v[88:91]
	v_mfma_f32_16x16x32_bf16 v[92:95], v[210:213], v[116:119], v[92:95]
	v_mfma_f32_16x16x32_bf16 v[96:99], v[210:213], v[136:139], v[96:99]
	s_barrier
	v_or_b32_e32 v240, 0x1c000, v162
	v_or_b32_e32 v243, 0x1c800, v162
	s_mov_b32 m0, s37
	v_or_b32_e32 v241, 0x1c400, v162
	ds_read_b128 v[100:103], v240
	ds_read_b128 v[214:217], v241
	v_or_b32_e32 v162, 0x1cc00, v162
	ds_read_b128 v[218:221], v243
	ds_read_b128 v[222:225], v162
	global_load_lds_dwordx4 v[226:227], off
	s_mov_b32 m0, s40
	s_nop 0
	global_load_lds_dwordx4 v[228:229], off
	s_barrier
; #define G_LDA(dst, b, h)                                                                                                  \
;   _Pragma("unroll") for (int m = 0; m < 4; ++m) _Pragma("unroll") for (int k = 0; k < 2; ++k)                             \
;       dst[m][k] = *(const bf16x8*)((const char*)G_SA(b, h) + ((wr * 4 + m) * 2 + k) * 1024 + rdo)
; #define G_LDB(dst, b, h)                                                                                                  \
;   _Pragma("unroll") for (int n = 0; n < 2; ++n) _Pragma("unroll") for (int k = 0; k < 2; ++k)                             \
;       dst[n][k] = *(const bf16x8*)((const char*)G_SB(b, h) + ((wc * 2 + n) * 2 + k) * 1024 + rdo)
; #define G_WAIT_V(n) asm volatile("s_waitcnt vmcnt(" #n ")" ::: "memory")
; #define G_WAIT_L(n) asm volatile("s_waitcnt lgkmcnt(" #n ")" ::: "memory")
; #define G_BAR __builtin_amdgcn_s_barrier()
; #define G_SCHED __builtin_amdgcn_sched_barrier(0)
; DI void br_flush(PREF p, f32x4 (&acc)[2][2][4][2], int slot) { br_store(p, acc, slot); zero_acc256(acc); }
;     ...
;     G_BAR; G_WAIT_L(0); G_MMA(0, 1, At, B1); G_BAR;
;     G_LDA(At, 1, 1); G_STAGE(G_SA(1, 0), A, oa0, oa1, LDA, 0, KA(tt + 3));
;     G_BAR; G_WAIT_L(0); G_MMA(1, 0, At, B0); G_BAR; G_SCHED;
;     G_STAGE(G_SB(1, 1), B, ob0, ob1, LDB, 128, KB(tt + 3));
;     G_WAIT_V(6); G_BAR; G_MMA(1, 1, At, B1); G_BAR;
;     if (MODE && ((tt + 1) & 3) == 3) br_flush(p, acc, (tt + 1) >> 2);
;   }
;   {
;     G_LDB(B0, 0, 0); G_LDA(At, 0, 0); G_STAGE(G_SA(1, 1), A, oa0, oa1, LDA, 128, KA(nt - 1));
;     G_BAR; G_WAIT_L(0); G_MMA(0, 0, At, B0); G_BAR;
	s_waitcnt lgkmcnt(0)
	v_mfma_f32_16x16x32_bf16 v[120:123], v[140:143], v[100:103], v[120:123]
	v_mfma_f32_16x16x32_bf16 v[38:41], v[140:143], v[218:221], v[40:43]
	v_mfma_f32_16x16x32_bf16 v[42:45], v[148:151], v[100:103], v[44:47]
	v_mfma_f32_16x16x32_bf16 v[46:49], v[148:151], v[218:221], v[48:51]
	v_mfma_f32_16x16x32_bf16 v[50:53], v[198:201], v[100:103], v[52:55]
	v_mfma_f32_16x16x32_bf16 v[54:57], v[198:201], v[218:221], v[56:59]
	v_mfma_f32_16x16x32_bf16 v[58:61], v[206:209], v[100:103], v[60:63]
	v_mfma_f32_16x16x32_bf16 v[62:65], v[206:209], v[218:221], v[64:67]
	v_mfma_f32_16x16x32_bf16 v[120:123], v[144:147], v[214:217], v[120:123]
	v_mfma_f32_16x16x32_bf16 v[38:41], v[144:147], v[222:225], v[38:41]
	v_mfma_f32_16x16x32_bf16 v[42:45], v[194:197], v[214:217], v[42:45]
	v_mfma_f32_16x16x32_bf16 v[46:49], v[194:197], v[222:225], v[46:49]
	v_mfma_f32_16x16x32_bf16 v[50:53], v[202:205], v[214:217], v[50:53]
	v_mfma_f32_16x16x32_bf16 v[54:57], v[202:205], v[222:225], v[54:57]
	v_mfma_f32_16x16x32_bf16 v[58:61], v[210:213], v[214:217], v[58:61]
	v_mfma_f32_16x16x32_bf16 v[62:65], v[210:213], v[222:225], v[62:65]
	s_mov_b32 m0, s35
	s_barrier
	ds_read_b128 v[140:143], v242 offset:49152
	ds_read_b128 v[144:147], v242 offset:50176
	ds_read_b128 v[148:151], v242 offset:51200
	ds_read_b128 v[194:197], v242 offset:52224
	ds_read_b128 v[198:201], v242 offset:53248
	ds_read_b128 v[202:205], v242 offset:54272
	ds_read_b128 v[206:209], v242 offset:55296
	ds_read_b128 v[210:213], v242 offset:56320
	global_load_lds_dwordx4 v[12:13], off
	s_mov_b32 m0, s36
	s_nop 0
	global_load_lds_dwordx4 v[10:11], off
	s_barrier
	s_waitcnt lgkmcnt(0)
	v_mfma_f32_16x16x32_bf16 v[10:13], v[140:143], v[112:115], v[152:155]
	v_mfma_f32_16x16x32_bf16 v[22:25], v[206:209], v[112:115], v[22:25]
	v_mfma_f32_16x16x32_bf16 v[26:29], v[206:209], v[132:135], v[26:29]
	v_mfma_f32_16x16x32_bf16 v[10:13], v[144:147], v[116:119], v[10:13]
	v_mfma_f32_16x16x32_bf16 v[152:155], v[140:143], v[132:135], v[156:159]
	v_mfma_f32_16x16x32_bf16 v[156:159], v[148:151], v[112:115], v[164:167]
	v_mfma_f32_16x16x32_bf16 v[164:167], v[148:151], v[132:135], v[182:185]
	v_mfma_f32_16x16x32_bf16 v[182:185], v[198:201], v[112:115], v[186:189]
	v_mfma_f32_16x16x32_bf16 v[186:189], v[198:201], v[132:135], v[190:193]
	v_mfma_f32_16x16x32_bf16 v[22:25], v[210:213], v[116:119], v[22:25]
	v_mfma_f32_16x16x32_bf16 v[26:29], v[210:213], v[136:139], v[26:29]
	v_mfma_f32_16x16x32_bf16 v[152:155], v[144:147], v[136:139], v[152:155]
	v_mfma_f32_16x16x32_bf16 v[156:159], v[194:197], v[116:119], v[156:159]
	v_mfma_f32_16x16x32_bf16 v[164:167], v[194:197], v[136:139], v[164:167]
	v_mfma_f32_16x16x32_bf16 v[182:185], v[202:205], v[116:119], v[182:185]
	v_mfma_f32_16x16x32_bf16 v[186:189], v[202:205], v[136:139], v[186:189]
	s_barrier
	s_mov_b32 m0, s22
	s_nop 0
	global_load_lds_dwordx4 v[8:9], off
	s_mov_b32 m0, s23
	s_nop 0
	global_load_lds_dwordx4 v[6:7], off
	s_waitcnt vmcnt(6)
	s_barrier
	v_mfma_f32_16x16x32_bf16 v[6:9], v[140:143], v[100:103], v[18:21]
	v_mfma_f32_16x16x32_bf16 v[18:21], v[140:143], v[218:221], v[30:33]
	v_mfma_f32_16x16x32_bf16 v[30:33], v[148:151], v[100:103], v[34:37]
	v_mfma_f32_16x16x32_bf16 v[34:37], v[148:151], v[218:221], v[68:71]
	v_mfma_f32_16x16x32_bf16 v[66:69], v[198:201], v[100:103], v[124:127]
	v_mfma_f32_16x16x32_bf16 v[100:103], v[206:209], v[100:103], v[104:107]
	v_mfma_f32_16x16x32_bf16 v[104:107], v[206:209], v[218:221], v[108:111]
	v_mfma_f32_16x16x32_bf16 v[6:9], v[144:147], v[214:217], v[6:9]
	v_mfma_f32_16x16x32_bf16 v[18:21], v[144:147], v[222:225], v[18:21]
	v_mfma_f32_16x16x32_bf16 v[30:33], v[194:197], v[214:217], v[30:33]
	v_mfma_f32_16x16x32_bf16 v[34:37], v[194:197], v[222:225], v[34:37]
	v_mfma_f32_16x16x32_bf16 v[66:69], v[202:205], v[214:217], v[66:69]
	v_mfma_f32_16x16x32_bf16 v[112:115], v[198:201], v[218:221], v[128:131]
	v_mfma_f32_16x16x32_bf16 v[100:103], v[210:213], v[214:217], v[100:103]
	v_mfma_f32_16x16x32_bf16 v[104:107], v[210:213], v[222:225], v[104:107]
	v_mfma_f32_16x16x32_bf16 v[112:115], v[202:205], v[222:225], v[112:115]
	s_add_u32 s0, s20, 0x10180
	s_addc_u32 s1, s21, 0
	s_mov_b32 m0, s19
	v_lshl_add_u64 v[2:3], s[0:1], 0, v[2:3]
	s_barrier
	ds_read_b128 v[108:111], v230
	ds_read_b128 v[116:119], v231
	ds_read_b128 v[124:127], v232
	ds_read_b128 v[128:131], v233
	ds_read_b128 v[132:135], v242
	ds_read_b128 v[136:139], v242 offset:1024
	ds_read_b128 v[140:143], v242 offset:2048
	ds_read_b128 v[144:147], v242 offset:3072
	ds_read_b128 v[148:151], v242 offset:4096
	ds_read_b128 v[190:193], v242 offset:5120
	ds_read_b128 v[194:197], v242 offset:6144
	ds_read_b128 v[198:201], v242 offset:7168
	global_load_lds_dwordx4 v[2:3], off
	v_lshl_add_u64 v[2:3], s[0:1], 0, v[4:5]
	s_mov_b32 m0, s18
	s_nop 0
	global_load_lds_dwordx4 v[2:3], off
	s_barrier
	s_waitcnt lgkmcnt(0)
	v_mfma_f32_16x16x32_bf16 v[2:5], v[132:135], v[108:111], v[14:17]
	v_mfma_f32_16x16x32_bf16 v[14:17], v[132:135], v[124:127], v[72:75]
	v_mfma_f32_16x16x32_bf16 v[70:73], v[140:143], v[108:111], v[76:79]
	v_mfma_f32_16x16x32_bf16 v[74:77], v[140:143], v[124:127], v[80:83]
	v_mfma_f32_16x16x32_bf16 v[78:81], v[148:151], v[108:111], v[84:87]
	v_mfma_f32_16x16x32_bf16 v[82:85], v[148:151], v[124:127], v[88:91]
	v_mfma_f32_16x16x32_bf16 v[86:89], v[194:197], v[108:111], v[92:95]
	v_mfma_f32_16x16x32_bf16 v[90:93], v[194:197], v[124:127], v[96:99]
	v_mfma_f32_16x16x32_bf16 v[2:5], v[136:139], v[116:119], v[2:5]
	v_mfma_f32_16x16x32_bf16 v[14:17], v[136:139], v[128:131], v[14:17]
	v_mfma_f32_16x16x32_bf16 v[70:73], v[144:147], v[116:119], v[70:73]
	v_mfma_f32_16x16x32_bf16 v[74:77], v[144:147], v[128:131], v[74:77]
	v_mfma_f32_16x16x32_bf16 v[78:81], v[190:193], v[116:119], v[78:81]
	v_mfma_f32_16x16x32_bf16 v[82:85], v[190:193], v[128:131], v[82:85]
	v_mfma_f32_16x16x32_bf16 v[86:89], v[198:201], v[116:119], v[86:89]
	v_mfma_f32_16x16x32_bf16 v[90:93], v[198:201], v[128:131], v[90:93]
	s_barrier
; #define G_LDA(dst, b, h)                                                                                                  \
;   _Pragma("unroll") for (int m = 0; m < 4; ++m) _Pragma("unroll") for (int k = 0; k < 2; ++k)                             \
;       dst[m][k] = *(const bf16x8*)((const char*)G_SA(b, h) + ((wr * 4 + m) * 2 + k) * 1024 + rdo)
; #define G_LDB(dst, b, h)                                                                                                  \
;   _Pragma("unroll") for (int n = 0; n < 2; ++n) _Pragma("unroll") for (int k = 0; k < 2; ++k)                             \
;       dst[n][k] = *(const bf16x8*)((const char*)G_SB(b, h) + ((wc * 2 + n) * 2 + k) * 1024 + rdo)
; #define G_WAIT_V(n) asm volatile("s_waitcnt vmcnt(" #n ")" ::: "memory")
; #define G_WAIT_L(n) asm volatile("s_waitcnt lgkmcnt(" #n ")" ::: "memory")
; #define G_BAR __builtin_amdgcn_s_barrier()
;     ...
;     G_LDB(B1, 0, 1); G_BAR; G_WAIT_L(0); G_MMA(0, 1, At, B1); G_BAR;
;     G_LDA(At, 0, 1); G_WAIT_V(4); G_BAR; G_WAIT_L(0); G_MMA(1, 0, At, B0); G_MMA(1, 1, At, B1); G_BAR;
;   }
;   {
;     G_LDB(B0, 1, 0); G_LDA(At, 1, 0); G_WAIT_V(2); G_BAR; G_WAIT_L(0); G_MMA(0, 0, At, B0); G_BAR;
	ds_read_b128 v[94:97], v234
	ds_read_b128 v[202:205], v235
	ds_read_b128 v[206:209], v236
	ds_read_b128 v[210:213], v237
	s_barrier
	s_waitcnt lgkmcnt(0)
	v_mfma_f32_16x16x32_bf16 v[38:41], v[132:135], v[206:209], v[38:41]
	v_mfma_f32_16x16x32_bf16 v[42:45], v[140:143], v[94:97], v[42:45]
	v_mfma_f32_16x16x32_bf16 v[46:49], v[140:143], v[206:209], v[46:49]
	v_mfma_f32_16x16x32_bf16 v[50:53], v[148:151], v[94:97], v[50:53]
	v_mfma_f32_16x16x32_bf16 v[54:57], v[148:151], v[206:209], v[54:57]
	v_mfma_f32_16x16x32_bf16 v[58:61], v[194:197], v[94:97], v[58:61]
	v_mfma_f32_16x16x32_bf16 v[62:65], v[194:197], v[206:209], v[62:65]
	v_mfma_f32_16x16x32_bf16 v[120:123], v[132:135], v[94:97], v[120:123]
	v_mfma_f32_16x16x32_bf16 v[38:41], v[136:139], v[210:213], v[38:41]
	v_mfma_f32_16x16x32_bf16 v[42:45], v[144:147], v[202:205], v[42:45]
	v_mfma_f32_16x16x32_bf16 v[46:49], v[144:147], v[210:213], v[46:49]
	v_mfma_f32_16x16x32_bf16 v[50:53], v[190:193], v[202:205], v[50:53]
	v_mfma_f32_16x16x32_bf16 v[54:57], v[190:193], v[210:213], v[54:57]
	v_mfma_f32_16x16x32_bf16 v[58:61], v[198:201], v[202:205], v[58:61]
	v_mfma_f32_16x16x32_bf16 v[62:65], v[198:201], v[210:213], v[62:65]
	v_mfma_f32_16x16x32_bf16 v[214:217], v[136:139], v[202:205], v[120:123]
	s_barrier
	s_nop 0
	ds_read_b128 v[120:123], v242 offset:16384
	ds_read_b128 v[132:135], v242 offset:17408
	ds_read_b128 v[136:139], v242 offset:18432
	ds_read_b128 v[140:143], v242 offset:19456
	ds_read_b128 v[144:147], v242 offset:20480
	ds_read_b128 v[148:151], v242 offset:21504
	ds_read_b128 v[190:193], v242 offset:22528
	ds_read_b128 v[194:197], v242 offset:23552
	s_waitcnt vmcnt(4)
	s_barrier
	s_waitcnt lgkmcnt(0)
	v_mfma_f32_16x16x32_bf16 v[10:13], v[120:123], v[108:111], v[10:13]
	v_mfma_f32_16x16x32_bf16 v[22:25], v[190:193], v[108:111], v[22:25]
	v_mfma_f32_16x16x32_bf16 v[26:29], v[190:193], v[124:127], v[26:29]
	v_mfma_f32_16x16x32_bf16 v[10:13], v[132:135], v[116:119], v[10:13]
	v_mfma_f32_16x16x32_bf16 v[152:155], v[120:123], v[124:127], v[152:155]
	v_mfma_f32_16x16x32_bf16 v[156:159], v[136:139], v[108:111], v[156:159]
	v_mfma_f32_16x16x32_bf16 v[164:167], v[136:139], v[124:127], v[164:167]
	v_mfma_f32_16x16x32_bf16 v[182:185], v[144:147], v[108:111], v[182:185]
	v_mfma_f32_16x16x32_bf16 v[186:189], v[144:147], v[124:127], v[186:189]
	v_mfma_f32_16x16x32_bf16 v[22:25], v[194:197], v[116:119], v[22:25]
	v_mfma_f32_16x16x32_bf16 v[26:29], v[194:197], v[128:131], v[26:29]
	v_mfma_f32_16x16x32_bf16 v[152:155], v[132:135], v[128:131], v[152:155]
	v_mfma_f32_16x16x32_bf16 v[156:159], v[140:143], v[116:119], v[156:159]
	v_mfma_f32_16x16x32_bf16 v[164:167], v[140:143], v[128:131], v[164:167]
	v_mfma_f32_16x16x32_bf16 v[182:185], v[148:151], v[116:119], v[182:185]
	v_mfma_f32_16x16x32_bf16 v[186:189], v[148:151], v[128:131], v[186:189]
	v_mfma_f32_16x16x32_bf16 v[30:33], v[136:139], v[94:97], v[30:33]
	v_mfma_f32_16x16x32_bf16 v[126:129], v[140:143], v[202:205], v[30:33]
	v_mfma_f32_16x16x32_bf16 v[30:33], v[136:139], v[206:209], v[34:37]
	v_mfma_f32_16x16x32_bf16 v[198:201], v[140:143], v[210:213], v[30:33]
	v_mfma_f32_16x16x32_bf16 v[30:33], v[144:147], v[94:97], v[66:69]
	v_mfma_f32_16x16x32_bf16 v[218:221], v[148:151], v[202:205], v[30:33]
	v_mfma_f32_16x16x32_bf16 v[30:33], v[144:147], v[206:209], v[112:115]
	v_mfma_f32_16x16x32_bf16 v[6:9], v[120:123], v[94:97], v[6:9]
	v_mfma_f32_16x16x32_bf16 v[18:21], v[120:123], v[206:209], v[18:21]
	v_mfma_f32_16x16x32_bf16 v[110:113], v[148:151], v[210:213], v[30:33]
	v_mfma_f32_16x16x32_bf16 v[30:33], v[190:193], v[94:97], v[100:103]
	v_mfma_f32_16x16x32_bf16 v[6:9], v[132:135], v[202:205], v[6:9]
	v_mfma_f32_16x16x32_bf16 v[18:21], v[132:135], v[210:213], v[18:21]
	v_mfma_f32_16x16x32_bf16 v[114:117], v[194:197], v[202:205], v[30:33]
	v_mfma_f32_16x16x32_bf16 v[30:33], v[190:193], v[206:209], v[104:107]
	v_mfma_f32_16x16x32_bf16 v[102:105], v[194:197], v[210:213], v[30:33]
	s_barrier
	s_nop 4
	s_nop 0
	ds_read_b128 v[30:33], v160
	ds_read_b128 v[34:37], v161
	ds_read_b128 v[146:149], v238
	ds_read_b128 v[190:193], v239
	ds_read_b128 v[66:69], v242 offset:32768
	ds_read_b128 v[94:97], v242 offset:33792
	ds_read_b128 v[194:197], v242 offset:34816
	ds_read_b128 v[202:205], v242 offset:35840
	ds_read_b128 v[206:209], v242 offset:36864
	ds_read_b128 v[210:213], v242 offset:37888
	ds_read_b128 v[222:225], v242 offset:38912
	ds_read_b128 v[226:229], v242 offset:39936
	s_waitcnt vmcnt(2)
	s_barrier
; #define G_LDA(dst, b, h)                                                                                                  \
;   _Pragma("unroll") for (int m = 0; m < 4; ++m) _Pragma("unroll") for (int k = 0; k < 2; ++k)                             \
;       dst[m][k] = *(const bf16x8*)((const char*)G_SA(b, h) + ((wr * 4 + m) * 2 + k) * 1024 + rdo)
; #define G_LDB(dst, b, h)                                                                                                  \
;   _Pragma("unroll") for (int n = 0; n < 2; ++n) _Pragma("unroll") for (int k = 0; k < 2; ++k)                             \
;       dst[n][k] = *(const bf16x8*)((const char*)G_SB(b, h) + ((wc * 2 + n) * 2 + k) * 1024 + rdo)
; #define G_WAIT_V(n) asm volatile("s_waitcnt vmcnt(" #n ")" ::: "memory")
; #define G_WAIT_L(n) asm volatile("s_waitcnt lgkmcnt(" #n ")" ::: "memory")
; #define G_BAR __builtin_amdgcn_s_barrier()
;     ...
;     G_LDB(B0, 1, 0); G_LDA(At, 1, 0); G_WAIT_V(2); G_BAR; G_WAIT_L(0); G_MMA(0, 0, At, B0); G_BAR;
;     G_LDB(B1, 1, 1); G_WAIT_V(0); G_BAR; G_WAIT_L(0); G_MMA(0, 1, At, B1); G_BAR;
;     G_LDA(At, 1, 1); G_BAR; G_WAIT_L(0); G_MMA(1, 0, At, B0); G_MMA(1, 1, At, B1); G_BAR;
;   }
;   if (wr == 0) G_BAR;
	s_waitcnt lgkmcnt(0)
	v_mfma_f32_16x16x32_bf16 v[2:5], v[66:69], v[30:33], v[2:5]
	v_mfma_f32_16x16x32_bf16 v[134:137], v[94:97], v[34:37], v[2:5]
	v_mfma_f32_16x16x32_bf16 v[2:5], v[66:69], v[146:149], v[14:17]
	v_mfma_f32_16x16x32_bf16 v[142:145], v[94:97], v[190:193], v[2:5]
	v_mfma_f32_16x16x32_bf16 v[2:5], v[194:197], v[30:33], v[70:73]
	v_mfma_f32_16x16x32_bf16 v[130:133], v[202:205], v[34:37], v[2:5]
	v_mfma_f32_16x16x32_bf16 v[2:5], v[194:197], v[146:149], v[74:77]
	v_mfma_f32_16x16x32_bf16 v[138:141], v[202:205], v[190:193], v[2:5]
	v_mfma_f32_16x16x32_bf16 v[2:5], v[206:209], v[30:33], v[78:81]
	v_mfma_f32_16x16x32_bf16 v[118:121], v[210:213], v[34:37], v[2:5]
	v_mfma_f32_16x16x32_bf16 v[2:5], v[206:209], v[146:149], v[82:85]
	v_mfma_f32_16x16x32_bf16 v[122:125], v[210:213], v[190:193], v[2:5]
	v_mfma_f32_16x16x32_bf16 v[2:5], v[222:225], v[30:33], v[86:89]
	v_mfma_f32_16x16x32_bf16 v[98:101], v[226:229], v[34:37], v[2:5]
	v_mfma_f32_16x16x32_bf16 v[2:5], v[222:225], v[146:149], v[90:93]
	v_mfma_f32_16x16x32_bf16 v[106:109], v[226:229], v[190:193], v[2:5]
	s_barrier
	s_nop 4
	s_nop 0
	ds_read_b128 v[2:5], v240
	ds_read_b128 v[230:233], v241
	ds_read_b128 v[234:237], v243
	ds_read_b128 v[238:241], v162
	s_waitcnt vmcnt(0)
	s_barrier
	s_waitcnt lgkmcnt(0)
	v_mfma_f32_16x16x32_bf16 v[14:17], v[66:69], v[2:5], v[214:217]
	v_mfma_f32_16x16x32_bf16 v[86:89], v[94:97], v[230:233], v[14:17]
	v_mfma_f32_16x16x32_bf16 v[14:17], v[66:69], v[234:237], v[38:41]
	v_mfma_f32_16x16x32_bf16 v[94:97], v[94:97], v[238:241], v[14:17]
	v_mfma_f32_16x16x32_bf16 v[14:17], v[194:197], v[2:5], v[42:45]
	v_mfma_f32_16x16x32_bf16 v[82:85], v[202:205], v[230:233], v[14:17]
	v_mfma_f32_16x16x32_bf16 v[14:17], v[194:197], v[234:237], v[46:49]
	v_mfma_f32_16x16x32_bf16 v[90:93], v[202:205], v[238:241], v[14:17]
	v_mfma_f32_16x16x32_bf16 v[14:17], v[206:209], v[2:5], v[50:53]
	v_mfma_f32_16x16x32_bf16 v[74:77], v[210:213], v[230:233], v[14:17]
	v_mfma_f32_16x16x32_bf16 v[14:17], v[206:209], v[234:237], v[54:57]
	v_mfma_f32_16x16x32_bf16 v[78:81], v[210:213], v[238:241], v[14:17]
	v_mfma_f32_16x16x32_bf16 v[14:17], v[222:225], v[2:5], v[58:61]
	v_mfma_f32_16x16x32_bf16 v[66:69], v[226:229], v[230:233], v[14:17]
	v_mfma_f32_16x16x32_bf16 v[14:17], v[222:225], v[234:237], v[62:65]
	v_mfma_f32_16x16x32_bf16 v[70:73], v[226:229], v[238:241], v[14:17]
	s_barrier
	s_nop 4
	s_nop 0
	ds_read_b128 v[14:17], v242 offset:49152
	ds_read_b128 v[194:197], v242 offset:50176
	ds_read_b128 v[202:205], v242 offset:51200
	ds_read_b128 v[206:209], v242 offset:52224
	ds_read_b128 v[210:213], v242 offset:53248
	ds_read_b128 v[214:217], v242 offset:54272
	ds_read_b128 v[222:225], v242 offset:55296
	ds_read_b128 v[226:229], v242 offset:56320
	s_barrier
	s_waitcnt lgkmcnt(0)
	v_mfma_f32_16x16x32_bf16 v[10:13], v[14:17], v[30:33], v[10:13]
	v_mfma_f32_16x16x32_bf16 v[54:57], v[194:197], v[34:37], v[10:13]
	v_mfma_f32_16x16x32_bf16 v[10:13], v[14:17], v[146:149], v[152:155]
	v_mfma_f32_16x16x32_bf16 v[62:65], v[194:197], v[190:193], v[10:13]
	v_mfma_f32_16x16x32_bf16 v[10:13], v[202:205], v[30:33], v[156:159]
	v_mfma_f32_16x16x32_bf16 v[50:53], v[206:209], v[34:37], v[10:13]
	v_mfma_f32_16x16x32_bf16 v[10:13], v[202:205], v[146:149], v[164:167]
	v_mfma_f32_16x16x32_bf16 v[58:61], v[206:209], v[190:193], v[10:13]
	v_mfma_f32_16x16x32_bf16 v[10:13], v[210:213], v[30:33], v[182:185]
	v_mfma_f32_16x16x32_bf16 v[42:45], v[214:217], v[34:37], v[10:13]
	v_mfma_f32_16x16x32_bf16 v[10:13], v[210:213], v[146:149], v[186:189]
	v_mfma_f32_16x16x32_bf16 v[46:49], v[214:217], v[190:193], v[10:13]
	v_mfma_f32_16x16x32_bf16 v[10:13], v[222:225], v[30:33], v[22:25]
	v_mfma_f32_16x16x32_bf16 v[34:37], v[226:229], v[34:37], v[10:13]
	v_mfma_f32_16x16x32_bf16 v[10:13], v[222:225], v[146:149], v[26:29]
	v_mfma_f32_16x16x32_bf16 v[38:41], v[226:229], v[190:193], v[10:13]
	v_mfma_f32_16x16x32_bf16 v[6:9], v[14:17], v[2:5], v[6:9]
	v_mfma_f32_16x16x32_bf16 v[22:25], v[194:197], v[230:233], v[6:9]
	v_mfma_f32_16x16x32_bf16 v[6:9], v[14:17], v[234:237], v[18:21]
	v_mfma_f32_16x16x32_bf16 v[30:33], v[194:197], v[238:241], v[6:9]
	v_mfma_f32_16x16x32_bf16 v[6:9], v[202:205], v[2:5], v[126:129]
	v_mfma_f32_16x16x32_bf16 v[18:21], v[206:209], v[230:233], v[6:9]
	v_mfma_f32_16x16x32_bf16 v[6:9], v[202:205], v[234:237], v[198:201]
	v_mfma_f32_16x16x32_bf16 v[26:29], v[206:209], v[238:241], v[6:9]
	v_mfma_f32_16x16x32_bf16 v[6:9], v[210:213], v[2:5], v[218:221]
	v_mfma_f32_16x16x32_bf16 v[10:13], v[214:217], v[230:233], v[6:9]
	v_mfma_f32_16x16x32_bf16 v[6:9], v[210:213], v[234:237], v[110:113]
	v_mfma_f32_16x16x32_bf16 v[14:17], v[214:217], v[238:241], v[6:9]
	v_mfma_f32_16x16x32_bf16 v[2:5], v[222:225], v[2:5], v[114:117]
	v_mfma_f32_16x16x32_bf16 v[6:9], v[222:225], v[234:237], v[102:105]
	v_mfma_f32_16x16x32_bf16 v[2:5], v[226:229], v[230:233], v[2:5]
	v_mfma_f32_16x16x32_bf16 v[6:9], v[226:229], v[238:241], v[6:9]
	v_cmp_gt_u32_e32 vcc, s67, v0
	s_barrier
	s_and_saveexec_b64 s[18:19], vcc
	s_cbranch_execz .LBB0_36
	s_barrier
	s_branch .LBB0_36

; #define G_LDA(dst, b, h)                                                                                                  \
;   _Pragma("unroll") for (int m = 0; m < 4; ++m) _Pragma("unroll") for (int k = 0; k < 2; ++k)                             \
;       dst[m][k] = *(const bf16x8*)((const char*)G_SA(b, h) + ((wr * 4 + m) * 2 + k) * 1024 + rdo)
; #define G_LDB(dst, b, h)                                                                                                  \
;   _Pragma("unroll") for (int n = 0; n < 2; ++n) _Pragma("unroll") for (int k = 0; k < 2; ++k)                             \
;       dst[n][k] = *(const bf16x8*)((const char*)G_SB(b, h) + ((wc * 2 + n) * 2 + k) * 1024 + rdo)
; #define G_WAIT_L(n) asm volatile("s_waitcnt lgkmcnt(" #n ")" ::: "memory")
; #define G_BAR __builtin_amdgcn_s_barrier()
; #define G_SCHED __builtin_amdgcn_sched_barrier(0)
;     ...
;   for (int tt = 0; tt < nt - 2; tt += 2) {
;     G_LDB(B0, 0, 0); G_SCHED; G_LDA(At, 0, 0); G_STAGE(G_SA(1, 1), A, oa0, oa1, LDA, 128, KA(tt + 1));
;     G_WAIT_L(8); G_BAR; G_WAIT_L(0); G_MMA(0, 0, At, B0); G_BAR; G_SCHED;
;     G_LDB(B1, 0, 1); G_STAGE(G_SB(0, 0), B, ob0, ob1, LDB, 0, KB(tt + 2));
;     G_BAR; G_WAIT_L(0); G_MMA(0, 1, At, B1); G_BAR;
;     G_LDA(At, 0, 1); G_STAGE(G_SA(0, 0), A, oa0, oa1, LDA, 0, KA(tt + 2));
;     G_BAR; G_WAIT_L(0); G_MMA(1, 0, At, B0); G_BAR; G_SCHED;
.LBB0_66:
	ds_read_b128 v[164:167], v160
	ds_read_b128 v[182:185], v160 offset:1024
	ds_read_b128 v[186:189], v160 offset:2048
	ds_read_b128 v[190:193], v160 offset:3072
	v_add_u32_e32 v161, 0xc000, v143
	v_lshl_add_u64 v[242:243], v[136:137], 0, s[22:23]
	v_readfirstlane_b32 s0, v161
	v_add_u32_e32 v162, 0xe000, v143
	v_lshl_add_u64 v[226:227], v[242:243], 0, s[78:79]
	s_mov_b32 m0, s0
	v_lshl_add_u64 v[244:245], v[134:135], 0, s[22:23]
	v_readfirstlane_b32 s0, v162
	ds_read_b128 v[194:197], v142
	ds_read_b128 v[198:201], v142 offset:1024
	ds_read_b128 v[202:205], v142 offset:2048
	ds_read_b128 v[206:209], v142 offset:3072
	ds_read_b128 v[210:213], v142 offset:4096
	ds_read_b128 v[214:217], v142 offset:5120
	ds_read_b128 v[218:221], v142 offset:6144
	ds_read_b128 v[222:225], v142 offset:7168
	global_load_lds_dwordx4 v[226:227], off
	v_lshl_add_u64 v[226:227], v[244:245], 0, s[78:79]
	s_mov_b32 m0, s0
	s_nop 0
	global_load_lds_dwordx4 v[226:227], off
	s_waitcnt lgkmcnt(8)
	s_barrier
	s_waitcnt lgkmcnt(0)
	v_mfma_f32_16x16x32_bf16 v[126:129], v[194:197], v[164:167], v[126:129]
	v_mfma_f32_16x16x32_bf16 v[122:125], v[194:197], v[186:189], v[122:125]
	v_mfma_f32_16x16x32_bf16 v[118:121], v[202:205], v[164:167], v[118:121]
	v_mfma_f32_16x16x32_bf16 v[114:117], v[202:205], v[186:189], v[114:117]
	v_mfma_f32_16x16x32_bf16 v[110:113], v[210:213], v[164:167], v[110:113]
	v_mfma_f32_16x16x32_bf16 v[106:109], v[210:213], v[186:189], v[106:109]
	v_mfma_f32_16x16x32_bf16 v[102:105], v[218:221], v[164:167], v[102:105]
	v_mfma_f32_16x16x32_bf16 v[98:101], v[218:221], v[186:189], v[98:101]
	v_mfma_f32_16x16x32_bf16 v[126:129], v[198:201], v[182:185], v[126:129]
	v_mfma_f32_16x16x32_bf16 v[122:125], v[198:201], v[190:193], v[122:125]
	v_mfma_f32_16x16x32_bf16 v[118:121], v[206:209], v[182:185], v[118:121]
	v_mfma_f32_16x16x32_bf16 v[114:117], v[206:209], v[190:193], v[114:117]
	v_mfma_f32_16x16x32_bf16 v[110:113], v[214:217], v[182:185], v[110:113]
	v_mfma_f32_16x16x32_bf16 v[106:109], v[214:217], v[190:193], v[106:109]
	v_mfma_f32_16x16x32_bf16 v[102:105], v[222:225], v[182:185], v[102:105]
	v_mfma_f32_16x16x32_bf16 v[98:101], v[222:225], v[190:193], v[98:101]
	s_barrier
	v_lshl_add_u64 v[246:247], v[140:141], 0, s[22:23]
	v_readfirstlane_b32 s0, v146
	v_lshl_add_u64 v[248:249], v[246:247], 0, s[48:49]
	s_mov_b32 m0, s0
	ds_read_b128 v[226:229], v158
	ds_read_b128 v[230:233], v158 offset:1024
	ds_read_b128 v[234:237], v158 offset:2048
	ds_read_b128 v[238:241], v158 offset:3072
	global_load_lds_dwordx4 v[248:249], off
	v_lshl_add_u64 v[248:249], v[138:139], 0, s[22:23]
	v_readfirstlane_b32 s0, v147
	v_lshl_add_u64 v[250:251], v[248:249], 0, s[48:49]
	s_mov_b32 m0, s0
	s_nop 0
	global_load_lds_dwordx4 v[250:251], off
	s_barrier
	s_waitcnt lgkmcnt(0)
	v_mfma_f32_16x16x32_bf16 v[94:97], v[194:197], v[226:229], v[94:97]
	v_mfma_f32_16x16x32_bf16 v[90:93], v[194:197], v[234:237], v[90:93]
	v_mfma_f32_16x16x32_bf16 v[86:89], v[202:205], v[226:229], v[86:89]
	v_mfma_f32_16x16x32_bf16 v[82:85], v[202:205], v[234:237], v[82:85]
	v_mfma_f32_16x16x32_bf16 v[78:81], v[210:213], v[226:229], v[78:81]
	v_mfma_f32_16x16x32_bf16 v[74:77], v[210:213], v[234:237], v[74:77]
	v_mfma_f32_16x16x32_bf16 v[70:73], v[218:221], v[226:229], v[70:73]
	v_mfma_f32_16x16x32_bf16 v[66:69], v[218:221], v[234:237], v[66:69]
	v_mfma_f32_16x16x32_bf16 v[94:97], v[198:201], v[230:233], v[94:97]
	v_mfma_f32_16x16x32_bf16 v[90:93], v[198:201], v[238:241], v[90:93]
	v_mfma_f32_16x16x32_bf16 v[86:89], v[206:209], v[230:233], v[86:89]
	v_mfma_f32_16x16x32_bf16 v[82:85], v[206:209], v[238:241], v[82:85]
	v_mfma_f32_16x16x32_bf16 v[78:81], v[214:217], v[230:233], v[78:81]
	v_mfma_f32_16x16x32_bf16 v[74:77], v[214:217], v[238:241], v[74:77]
	v_mfma_f32_16x16x32_bf16 v[70:73], v[222:225], v[230:233], v[70:73]
	v_mfma_f32_16x16x32_bf16 v[66:69], v[222:225], v[238:241], v[66:69]
	v_readfirstlane_b32 s0, v143
	v_lshl_add_u64 v[250:251], v[242:243], 0, s[82:83]
	s_mov_b32 m0, s0
	v_readfirstlane_b32 s0, v144
	s_barrier
	ds_read_b128 v[194:197], v142 offset:16384
	ds_read_b128 v[198:201], v142 offset:17408
	ds_read_b128 v[202:205], v142 offset:18432
	ds_read_b128 v[206:209], v142 offset:19456
	ds_read_b128 v[210:213], v142 offset:20480
	ds_read_b128 v[214:217], v142 offset:21504
	ds_read_b128 v[218:221], v142 offset:22528
	ds_read_b128 v[222:225], v142 offset:23552
	global_load_lds_dwordx4 v[250:251], off
	v_lshl_add_u64 v[250:251], v[244:245], 0, s[82:83]
	s_mov_b32 m0, s0
	s_nop 0
	global_load_lds_dwordx4 v[250:251], off
	s_barrier
	s_waitcnt lgkmcnt(0)
	v_mfma_f32_16x16x32_bf16 v[62:65], v[194:197], v[164:167], v[62:65]
	v_mfma_f32_16x16x32_bf16 v[58:61], v[194:197], v[186:189], v[58:61]
	v_mfma_f32_16x16x32_bf16 v[54:57], v[202:205], v[164:167], v[54:57]
	v_mfma_f32_16x16x32_bf16 v[50:53], v[202:205], v[186:189], v[50:53]
	v_mfma_f32_16x16x32_bf16 v[46:49], v[210:213], v[164:167], v[46:49]
	v_mfma_f32_16x16x32_bf16 v[42:45], v[210:213], v[186:189], v[42:45]
	v_mfma_f32_16x16x32_bf16 v[38:41], v[218:221], v[164:167], v[38:41]
	v_mfma_f32_16x16x32_bf16 v[34:37], v[218:221], v[186:189], v[34:37]
	v_mfma_f32_16x16x32_bf16 v[62:65], v[198:201], v[182:185], v[62:65]
	v_mfma_f32_16x16x32_bf16 v[58:61], v[198:201], v[190:193], v[58:61]
	v_mfma_f32_16x16x32_bf16 v[54:57], v[206:209], v[182:185], v[54:57]
	v_mfma_f32_16x16x32_bf16 v[50:53], v[206:209], v[190:193], v[50:53]
	v_mfma_f32_16x16x32_bf16 v[46:49], v[214:217], v[182:185], v[46:49]
	v_mfma_f32_16x16x32_bf16 v[42:45], v[214:217], v[190:193], v[42:45]
	v_mfma_f32_16x16x32_bf16 v[38:41], v[222:225], v[182:185], v[38:41]
	v_mfma_f32_16x16x32_bf16 v[34:37], v[222:225], v[190:193], v[34:37]
	s_barrier
; #define G_LDA(dst, b, h)                                                                                                  \
;   _Pragma("unroll") for (int m = 0; m < 4; ++m) _Pragma("unroll") for (int k = 0; k < 2; ++k)                             \
;       dst[m][k] = *(const bf16x8*)((const char*)G_SA(b, h) + ((wr * 4 + m) * 2 + k) * 1024 + rdo)
; #define G_LDB(dst, b, h)                                                                                                  \
;   _Pragma("unroll") for (int n = 0; n < 2; ++n) _Pragma("unroll") for (int k = 0; k < 2; ++k)                             \
;       dst[n][k] = *(const bf16x8*)((const char*)G_SB(b, h) + ((wc * 2 + n) * 2 + k) * 1024 + rdo)
; #define G_WAIT_V(n) asm volatile("s_waitcnt vmcnt(" #n ")" ::: "memory")
; #define G_WAIT_L(n) asm volatile("s_waitcnt lgkmcnt(" #n ")" ::: "memory")
; #define G_BAR __builtin_amdgcn_s_barrier()
; #define G_SCHED __builtin_amdgcn_sched_barrier(0)
;     ...
;     G_STAGE(G_SB(0, 1), B, ob0, ob1, LDB, 128, KB(tt + 2));
;     G_WAIT_V(6); G_BAR; G_MMA(1, 1, At, B1); G_BAR;
;     G_LDB(B0, 1, 0); G_SCHED; G_LDA(At, 1, 0); G_STAGE(G_SA(0, 1), A, oa0, oa1, LDA, 128, KA(tt + 2));
;     G_WAIT_L(8); G_BAR; G_WAIT_L(0); G_MMA(0, 0, At, B0); G_BAR; G_SCHED;
;     G_LDB(B1, 1, 1); G_STAGE(G_SB(1, 0), B, ob0, ob1, LDB, 0, KB(tt + 3));
;     G_BAR; G_WAIT_L(0); G_MMA(0, 1, At, B1); G_BAR;
;     G_LDA(At, 1, 1); G_STAGE(G_SA(1, 0), A, oa0, oa1, LDA, 0, KA(tt + 3));
	v_readfirstlane_b32 s0, v148
	v_lshl_add_u64 v[164:165], v[246:247], 0, s[24:25]
	s_mov_b32 m0, s0
	v_readfirstlane_b32 s0, v150
	global_load_lds_dwordx4 v[164:165], off
	v_lshl_add_u64 v[164:165], v[248:249], 0, s[24:25]
	s_mov_b32 m0, s0
	s_nop 0
	global_load_lds_dwordx4 v[164:165], off
	s_waitcnt vmcnt(6)
	s_barrier
	v_mfma_f32_16x16x32_bf16 v[30:33], v[194:197], v[226:229], v[30:33]
	v_mfma_f32_16x16x32_bf16 v[26:29], v[194:197], v[234:237], v[26:29]
	v_mfma_f32_16x16x32_bf16 v[22:25], v[202:205], v[226:229], v[22:25]
	v_mfma_f32_16x16x32_bf16 v[18:21], v[202:205], v[234:237], v[18:21]
	v_mfma_f32_16x16x32_bf16 v[14:17], v[210:213], v[226:229], v[14:17]
	v_mfma_f32_16x16x32_bf16 v[10:13], v[210:213], v[234:237], v[10:13]
	v_mfma_f32_16x16x32_bf16 v[6:9], v[218:221], v[226:229], v[6:9]
	v_mfma_f32_16x16x32_bf16 v[2:5], v[218:221], v[234:237], v[2:5]
	v_mfma_f32_16x16x32_bf16 v[30:33], v[198:201], v[230:233], v[30:33]
	v_mfma_f32_16x16x32_bf16 v[26:29], v[198:201], v[238:241], v[26:29]
	v_mfma_f32_16x16x32_bf16 v[22:25], v[206:209], v[230:233], v[22:25]
	v_mfma_f32_16x16x32_bf16 v[18:21], v[206:209], v[238:241], v[18:21]
	v_mfma_f32_16x16x32_bf16 v[14:17], v[214:217], v[230:233], v[14:17]
	v_mfma_f32_16x16x32_bf16 v[10:13], v[214:217], v[238:241], v[10:13]
	v_mfma_f32_16x16x32_bf16 v[6:9], v[222:225], v[230:233], v[6:9]
	v_mfma_f32_16x16x32_bf16 v[2:5], v[222:225], v[238:241], v[2:5]
	s_barrier
	ds_read_b128 v[164:167], v149
	ds_read_b128 v[182:185], v149 offset:1024
	ds_read_b128 v[186:189], v149 offset:2048
	ds_read_b128 v[190:193], v149 offset:3072
	v_readfirstlane_b32 s0, v151
	v_lshl_add_u64 v[226:227], v[242:243], 0, s[86:87]
	s_mov_b32 m0, s0
	v_readfirstlane_b32 s0, v152
	ds_read_b128 v[194:197], v142 offset:32768
	ds_read_b128 v[198:201], v142 offset:33792
	ds_read_b128 v[202:205], v142 offset:34816
	ds_read_b128 v[206:209], v142 offset:35840
	ds_read_b128 v[210:213], v142 offset:36864
	ds_read_b128 v[214:217], v142 offset:37888
	ds_read_b128 v[218:221], v142 offset:38912
	ds_read_b128 v[222:225], v142 offset:39936
	global_load_lds_dwordx4 v[226:227], off
	v_lshl_add_u64 v[226:227], v[244:245], 0, s[86:87]
	s_mov_b32 m0, s0
	s_nop 0
	global_load_lds_dwordx4 v[226:227], off
	s_waitcnt lgkmcnt(8)
	s_barrier
	s_waitcnt lgkmcnt(0)
	v_mfma_f32_16x16x32_bf16 v[126:129], v[194:197], v[164:167], v[126:129]
	v_mfma_f32_16x16x32_bf16 v[122:125], v[194:197], v[186:189], v[122:125]
	v_mfma_f32_16x16x32_bf16 v[118:121], v[202:205], v[164:167], v[118:121]
	v_mfma_f32_16x16x32_bf16 v[114:117], v[202:205], v[186:189], v[114:117]
	v_mfma_f32_16x16x32_bf16 v[110:113], v[210:213], v[164:167], v[110:113]
	v_mfma_f32_16x16x32_bf16 v[106:109], v[210:213], v[186:189], v[106:109]
	v_mfma_f32_16x16x32_bf16 v[102:105], v[218:221], v[164:167], v[102:105]
	v_mfma_f32_16x16x32_bf16 v[98:101], v[218:221], v[186:189], v[98:101]
	v_mfma_f32_16x16x32_bf16 v[126:129], v[198:201], v[182:185], v[126:129]
	v_mfma_f32_16x16x32_bf16 v[122:125], v[198:201], v[190:193], v[122:125]
	v_mfma_f32_16x16x32_bf16 v[118:121], v[206:209], v[182:185], v[118:121]
	v_mfma_f32_16x16x32_bf16 v[114:117], v[206:209], v[190:193], v[114:117]
	v_mfma_f32_16x16x32_bf16 v[110:113], v[214:217], v[182:185], v[110:113]
	v_mfma_f32_16x16x32_bf16 v[106:109], v[214:217], v[190:193], v[106:109]
	v_mfma_f32_16x16x32_bf16 v[102:105], v[222:225], v[182:185], v[102:105]
	v_mfma_f32_16x16x32_bf16 v[98:101], v[222:225], v[190:193], v[98:101]
	s_barrier
	v_readfirstlane_b32 s0, v153
	v_lshl_add_u64 v[250:251], v[246:247], 0, s[26:27]
	s_mov_b32 m0, s0
	v_readfirstlane_b32 s0, v154
	ds_read_b128 v[226:229], v145
	ds_read_b128 v[230:233], v145 offset:1024
	ds_read_b128 v[234:237], v145 offset:2048
	ds_read_b128 v[238:241], v145 offset:3072
	global_load_lds_dwordx4 v[250:251], off
	v_lshl_add_u64 v[250:251], v[248:249], 0, s[26:27]
	s_mov_b32 m0, s0
	s_nop 0
	global_load_lds_dwordx4 v[250:251], off
	s_barrier
	s_waitcnt lgkmcnt(0)
	v_mfma_f32_16x16x32_bf16 v[94:97], v[194:197], v[226:229], v[94:97]
	v_mfma_f32_16x16x32_bf16 v[90:93], v[194:197], v[234:237], v[90:93]
	v_mfma_f32_16x16x32_bf16 v[86:89], v[202:205], v[226:229], v[86:89]
	v_mfma_f32_16x16x32_bf16 v[82:85], v[202:205], v[234:237], v[82:85]
	v_mfma_f32_16x16x32_bf16 v[78:81], v[210:213], v[226:229], v[78:81]
	v_mfma_f32_16x16x32_bf16 v[74:77], v[210:213], v[234:237], v[74:77]
	v_mfma_f32_16x16x32_bf16 v[70:73], v[218:221], v[226:229], v[70:73]
	v_mfma_f32_16x16x32_bf16 v[66:69], v[218:221], v[234:237], v[66:69]
	v_mfma_f32_16x16x32_bf16 v[94:97], v[198:201], v[230:233], v[94:97]
	v_mfma_f32_16x16x32_bf16 v[90:93], v[198:201], v[238:241], v[90:93]
	v_mfma_f32_16x16x32_bf16 v[86:89], v[206:209], v[230:233], v[86:89]
	v_mfma_f32_16x16x32_bf16 v[82:85], v[206:209], v[238:241], v[82:85]
	v_mfma_f32_16x16x32_bf16 v[78:81], v[214:217], v[230:233], v[78:81]
	v_mfma_f32_16x16x32_bf16 v[74:77], v[214:217], v[238:241], v[74:77]
	v_mfma_f32_16x16x32_bf16 v[70:73], v[222:225], v[230:233], v[70:73]
	v_mfma_f32_16x16x32_bf16 v[66:69], v[222:225], v[238:241], v[66:69]
	v_readfirstlane_b32 s0, v155
	v_lshl_add_u64 v[242:243], v[242:243], 0, s[90:91]
	s_mov_b32 m0, s0
	v_readfirstlane_b32 s0, v156
	s_barrier
	ds_read_b128 v[194:197], v142 offset:49152
	ds_read_b128 v[198:201], v142 offset:50176
	ds_read_b128 v[202:205], v142 offset:51200
	ds_read_b128 v[206:209], v142 offset:52224
	ds_read_b128 v[210:213], v142 offset:53248
	ds_read_b128 v[214:217], v142 offset:54272
	ds_read_b128 v[218:221], v142 offset:55296
	ds_read_b128 v[222:225], v142 offset:56320
	global_load_lds_dwordx4 v[242:243], off
	v_lshl_add_u64 v[242:243], v[244:245], 0, s[90:91]
	s_mov_b32 m0, s0
	s_nop 0
	global_load_lds_dwordx4 v[242:243], off
	s_barrier
; #define G_LDA(dst, b, h)                                                                                                  \
;   _Pragma("unroll") for (int m = 0; m < 4; ++m) _Pragma("unroll") for (int k = 0; k < 2; ++k)                             \
;       dst[m][k] = *(const bf16x8*)((const char*)G_SA(b, h) + ((wr * 4 + m) * 2 + k) * 1024 + rdo)
; #define G_LDB(dst, b, h)                                                                                                  \
;   _Pragma("unroll") for (int n = 0; n < 2; ++n) _Pragma("unroll") for (int k = 0; k < 2; ++k)                             \
;       dst[n][k] = *(const bf16x8*)((const char*)G_SB(b, h) + ((wc * 2 + n) * 2 + k) * 1024 + rdo)
; #define G_WAIT_V(n) asm volatile("s_waitcnt vmcnt(" #n ")" ::: "memory")
; #define G_WAIT_L(n) asm volatile("s_waitcnt lgkmcnt(" #n ")" ::: "memory")
; #define G_BAR __builtin_amdgcn_s_barrier()
; #define G_SCHED __builtin_amdgcn_sched_barrier(0)
; DI void br_flush(PREF p, f32x4 (&acc)[2][2][4][2], int slot) { br_store(p, acc, slot); zero_acc256(acc); }
;     ...
;     G_BAR; G_WAIT_L(0); G_MMA(1, 0, At, B0); G_BAR; G_SCHED;
;     G_STAGE(G_SB(1, 1), B, ob0, ob1, LDB, 128, KB(tt + 3));
;     G_WAIT_V(6); G_BAR; G_MMA(1, 1, At, B1); G_BAR;
;     if (MODE && ((tt + 1) & 3) == 3) br_flush(p, acc, (tt + 1) >> 2);
;   }
;   {
;     G_LDB(B0, 0, 0); G_LDA(At, 0, 0); G_STAGE(G_SA(1, 1), A, oa0, oa1, LDA, 128, KA(nt - 1));
;     G_BAR; G_WAIT_L(0); G_MMA(0, 0, At, B0); G_BAR;
;     G_LDB(B1, 0, 1); G_BAR; G_WAIT_L(0); G_MMA(0, 1, At, B1); G_BAR;
	s_waitcnt lgkmcnt(0)
	v_mfma_f32_16x16x32_bf16 v[62:65], v[194:197], v[164:167], v[62:65]
	v_mfma_f32_16x16x32_bf16 v[58:61], v[194:197], v[186:189], v[58:61]
	v_mfma_f32_16x16x32_bf16 v[54:57], v[202:205], v[164:167], v[54:57]
	v_mfma_f32_16x16x32_bf16 v[50:53], v[202:205], v[186:189], v[50:53]
	v_mfma_f32_16x16x32_bf16 v[46:49], v[210:213], v[164:167], v[46:49]
	v_mfma_f32_16x16x32_bf16 v[42:45], v[210:213], v[186:189], v[42:45]
	v_mfma_f32_16x16x32_bf16 v[38:41], v[218:221], v[164:167], v[38:41]
	v_mfma_f32_16x16x32_bf16 v[34:37], v[218:221], v[186:189], v[34:37]
	v_mfma_f32_16x16x32_bf16 v[62:65], v[198:201], v[182:185], v[62:65]
	v_mfma_f32_16x16x32_bf16 v[58:61], v[198:201], v[190:193], v[58:61]
	v_mfma_f32_16x16x32_bf16 v[54:57], v[206:209], v[182:185], v[54:57]
	v_mfma_f32_16x16x32_bf16 v[50:53], v[206:209], v[190:193], v[50:53]
	v_mfma_f32_16x16x32_bf16 v[46:49], v[214:217], v[182:185], v[46:49]
	v_mfma_f32_16x16x32_bf16 v[42:45], v[214:217], v[190:193], v[42:45]
	v_mfma_f32_16x16x32_bf16 v[38:41], v[222:225], v[182:185], v[38:41]
	v_mfma_f32_16x16x32_bf16 v[34:37], v[222:225], v[190:193], v[34:37]
	s_barrier
	v_readfirstlane_b32 s0, v157
	v_lshl_add_u64 v[164:165], v[246:247], 0, s[36:37]
	s_mov_b32 m0, s0
	v_readfirstlane_b32 s0, v159
	global_load_lds_dwordx4 v[164:165], off
	v_lshl_add_u64 v[164:165], v[248:249], 0, s[36:37]
	s_mov_b32 m0, s0
	s_nop 0
	global_load_lds_dwordx4 v[164:165], off
	s_waitcnt vmcnt(6)
	s_barrier
	v_mfma_f32_16x16x32_bf16 v[30:33], v[194:197], v[226:229], v[30:33]
	v_mfma_f32_16x16x32_bf16 v[26:29], v[194:197], v[234:237], v[26:29]
	v_mfma_f32_16x16x32_bf16 v[22:25], v[202:205], v[226:229], v[22:25]
	v_mfma_f32_16x16x32_bf16 v[18:21], v[202:205], v[234:237], v[18:21]
	v_mfma_f32_16x16x32_bf16 v[14:17], v[210:213], v[226:229], v[14:17]
	v_mfma_f32_16x16x32_bf16 v[10:13], v[210:213], v[234:237], v[10:13]
	v_mfma_f32_16x16x32_bf16 v[6:9], v[218:221], v[226:229], v[6:9]
	v_mfma_f32_16x16x32_bf16 v[2:5], v[218:221], v[234:237], v[2:5]
	v_mfma_f32_16x16x32_bf16 v[30:33], v[198:201], v[230:233], v[30:33]
	v_mfma_f32_16x16x32_bf16 v[26:29], v[198:201], v[238:241], v[26:29]
	v_mfma_f32_16x16x32_bf16 v[22:25], v[206:209], v[230:233], v[22:25]
	v_mfma_f32_16x16x32_bf16 v[18:21], v[206:209], v[238:241], v[18:21]
	v_mfma_f32_16x16x32_bf16 v[14:17], v[214:217], v[230:233], v[14:17]
	v_mfma_f32_16x16x32_bf16 v[10:13], v[214:217], v[238:241], v[10:13]
	v_mfma_f32_16x16x32_bf16 v[6:9], v[222:225], v[230:233], v[6:9]
	v_mfma_f32_16x16x32_bf16 v[2:5], v[222:225], v[238:241], v[2:5]
	s_add_i32 s9, s9, 2
	s_add_u32 s22, s22, 0x100
	s_addc_u32 s23, s23, 0
	s_cmp_lt_u32 s9, 12
	s_barrier
	s_cbranch_scc1 .LBB0_66
	s_add_u32 s0, s20, 0x40780
	s_addc_u32 s1, s21, 0
	v_readfirstlane_b32 s9, v161
	v_lshl_add_u64 v[132:133], v[132:133], 1, s[0:1]
	s_mov_b32 m0, s9
	v_lshl_add_u64 v[130:131], v[130:131], 1, s[0:1]
	v_readfirstlane_b32 s0, v162
	ds_read_b128 v[134:137], v160
	ds_read_b128 v[138:141], v160 offset:1024
	ds_read_b128 v[150:153], v160 offset:2048
	ds_read_b128 v[154:157], v160 offset:3072
	ds_read_b128 v[164:167], v142
	ds_read_b128 v[182:185], v142 offset:1024
	ds_read_b128 v[186:189], v142 offset:2048
	ds_read_b128 v[190:193], v142 offset:3072
	ds_read_b128 v[194:197], v142 offset:4096
	ds_read_b128 v[198:201], v142 offset:5120
	ds_read_b128 v[202:205], v142 offset:6144
	ds_read_b128 v[206:209], v142 offset:7168
	global_load_lds_dwordx4 v[132:133], off
	s_mov_b32 m0, s0
	s_nop 0
	global_load_lds_dwordx4 v[130:131], off
	s_barrier
	s_waitcnt lgkmcnt(0)
	v_mfma_f32_16x16x32_bf16 v[126:129], v[164:167], v[134:137], v[126:129]
	v_mfma_f32_16x16x32_bf16 v[122:125], v[164:167], v[150:153], v[122:125]
	v_mfma_f32_16x16x32_bf16 v[110:113], v[194:197], v[134:137], v[110:113]
	v_mfma_f32_16x16x32_bf16 v[102:105], v[202:205], v[134:137], v[102:105]
	v_mfma_f32_16x16x32_bf16 v[126:129], v[182:185], v[138:141], v[126:129]
	v_mfma_f32_16x16x32_bf16 v[122:125], v[182:185], v[154:157], v[122:125]
	v_mfma_f32_16x16x32_bf16 v[118:121], v[186:189], v[134:137], v[118:121]
	v_mfma_f32_16x16x32_bf16 v[114:117], v[186:189], v[150:153], v[114:117]
	v_mfma_f32_16x16x32_bf16 v[110:113], v[198:201], v[138:141], v[110:113]
	v_mfma_f32_16x16x32_bf16 v[106:109], v[194:197], v[150:153], v[106:109]
	v_mfma_f32_16x16x32_bf16 v[102:105], v[206:209], v[138:141], v[102:105]
	v_mfma_f32_16x16x32_bf16 v[98:101], v[202:205], v[150:153], v[98:101]
	v_mfma_f32_16x16x32_bf16 v[130:133], v[190:193], v[138:141], v[118:121]
	v_mfma_f32_16x16x32_bf16 v[210:213], v[190:193], v[154:157], v[114:117]
	v_mfma_f32_16x16x32_bf16 v[214:217], v[198:201], v[154:157], v[106:109]
	v_mfma_f32_16x16x32_bf16 v[218:221], v[206:209], v[154:157], v[98:101]
	s_barrier
	s_nop 1
	s_nop 0
	ds_read_b128 v[98:101], v158
	ds_read_b128 v[106:109], v158 offset:1024
	ds_read_b128 v[114:117], v158 offset:2048
	ds_read_b128 v[118:121], v158 offset:3072
	s_barrier
	s_waitcnt lgkmcnt(0)
	v_mfma_f32_16x16x32_bf16 v[94:97], v[164:167], v[98:101], v[94:97]
	v_mfma_f32_16x16x32_bf16 v[90:93], v[164:167], v[114:117], v[90:93]
	v_mfma_f32_16x16x32_bf16 v[78:81], v[194:197], v[98:101], v[78:81]
	v_mfma_f32_16x16x32_bf16 v[70:73], v[202:205], v[98:101], v[70:73]
	v_mfma_f32_16x16x32_bf16 v[94:97], v[182:185], v[106:109], v[94:97]
	v_mfma_f32_16x16x32_bf16 v[90:93], v[182:185], v[118:121], v[90:93]
	v_mfma_f32_16x16x32_bf16 v[86:89], v[186:189], v[98:101], v[86:89]
	v_mfma_f32_16x16x32_bf16 v[82:85], v[186:189], v[114:117], v[82:85]
	v_mfma_f32_16x16x32_bf16 v[78:81], v[198:201], v[106:109], v[78:81]
	v_mfma_f32_16x16x32_bf16 v[74:77], v[194:197], v[114:117], v[74:77]
	v_mfma_f32_16x16x32_bf16 v[70:73], v[206:209], v[106:109], v[70:73]
	v_mfma_f32_16x16x32_bf16 v[66:69], v[202:205], v[114:117], v[66:69]
	v_mfma_f32_16x16x32_bf16 v[158:161], v[190:193], v[106:109], v[86:89]
	v_mfma_f32_16x16x32_bf16 v[164:167], v[190:193], v[118:121], v[82:85]
	v_mfma_f32_16x16x32_bf16 v[182:185], v[198:201], v[118:121], v[74:77]
	v_mfma_f32_16x16x32_bf16 v[186:189], v[206:209], v[118:121], v[66:69]
	s_barrier
; #define G_LDA(dst, b, h)                                                                                                  \
;   _Pragma("unroll") for (int m = 0; m < 4; ++m) _Pragma("unroll") for (int k = 0; k < 2; ++k)                             \
;       dst[m][k] = *(const bf16x8*)((const char*)G_SA(b, h) + ((wr * 4 + m) * 2 + k) * 1024 + rdo)
; #define G_LDB(dst, b, h)                                                                                                  \
;   _Pragma("unroll") for (int n = 0; n < 2; ++n) _Pragma("unroll") for (int k = 0; k < 2; ++k)                             \
;       dst[n][k] = *(const bf16x8*)((const char*)G_SB(b, h) + ((wc * 2 + n) * 2 + k) * 1024 + rdo)
; #define G_WAIT_V(n) asm volatile("s_waitcnt vmcnt(" #n ")" ::: "memory")
; #define G_WAIT_L(n) asm volatile("s_waitcnt lgkmcnt(" #n ")" ::: "memory")
; #define G_BAR __builtin_amdgcn_s_barrier()
;     ...
;     G_LDA(At, 0, 1); G_WAIT_V(4); G_BAR; G_WAIT_L(0); G_MMA(1, 0, At, B0); G_MMA(1, 1, At, B1); G_BAR;
;   }
;   {
;     G_LDB(B0, 1, 0); G_LDA(At, 1, 0); G_WAIT_V(2); G_BAR; G_WAIT_L(0); G_MMA(0, 0, At, B0); G_BAR;
	s_nop 1
	s_nop 0
	ds_read_b128 v[66:69], v142 offset:16384
	ds_read_b128 v[74:77], v142 offset:17408
	ds_read_b128 v[82:85], v142 offset:18432
	ds_read_b128 v[86:89], v142 offset:19456
	ds_read_b128 v[190:193], v142 offset:20480
	ds_read_b128 v[194:197], v142 offset:21504
	ds_read_b128 v[198:201], v142 offset:22528
	ds_read_b128 v[202:205], v142 offset:23552
	s_waitcnt vmcnt(4)
	s_barrier
	s_waitcnt lgkmcnt(0)
	v_mfma_f32_16x16x32_bf16 v[62:65], v[66:69], v[134:137], v[62:65]
	v_mfma_f32_16x16x32_bf16 v[58:61], v[66:69], v[150:153], v[58:61]
	v_mfma_f32_16x16x32_bf16 v[46:49], v[190:193], v[134:137], v[46:49]
	v_mfma_f32_16x16x32_bf16 v[38:41], v[198:201], v[134:137], v[38:41]
	v_mfma_f32_16x16x32_bf16 v[62:65], v[74:77], v[138:141], v[62:65]
	v_mfma_f32_16x16x32_bf16 v[58:61], v[74:77], v[154:157], v[58:61]
	v_mfma_f32_16x16x32_bf16 v[54:57], v[82:85], v[134:137], v[54:57]
	v_mfma_f32_16x16x32_bf16 v[50:53], v[82:85], v[150:153], v[50:53]
	v_mfma_f32_16x16x32_bf16 v[46:49], v[194:197], v[138:141], v[46:49]
	v_mfma_f32_16x16x32_bf16 v[42:45], v[190:193], v[150:153], v[42:45]
	v_mfma_f32_16x16x32_bf16 v[38:41], v[202:205], v[138:141], v[38:41]
	v_mfma_f32_16x16x32_bf16 v[34:37], v[198:201], v[150:153], v[34:37]
	v_mfma_f32_16x16x32_bf16 v[206:209], v[86:89], v[138:141], v[54:57]
	v_mfma_f32_16x16x32_bf16 v[222:225], v[86:89], v[154:157], v[50:53]
	v_mfma_f32_16x16x32_bf16 v[226:229], v[194:197], v[154:157], v[42:45]
	v_mfma_f32_16x16x32_bf16 v[134:137], v[202:205], v[154:157], v[34:37]
	v_mfma_f32_16x16x32_bf16 v[30:33], v[66:69], v[98:101], v[30:33]
	v_mfma_f32_16x16x32_bf16 v[26:29], v[66:69], v[114:117], v[26:29]
	v_mfma_f32_16x16x32_bf16 v[14:17], v[190:193], v[98:101], v[14:17]
	v_mfma_f32_16x16x32_bf16 v[6:9], v[198:201], v[98:101], v[6:9]
	v_mfma_f32_16x16x32_bf16 v[30:33], v[74:77], v[106:109], v[30:33]
	v_mfma_f32_16x16x32_bf16 v[26:29], v[74:77], v[118:121], v[26:29]
	v_mfma_f32_16x16x32_bf16 v[22:25], v[82:85], v[98:101], v[22:25]
	v_mfma_f32_16x16x32_bf16 v[18:21], v[82:85], v[114:117], v[18:21]
	v_mfma_f32_16x16x32_bf16 v[14:17], v[194:197], v[106:109], v[14:17]
	v_mfma_f32_16x16x32_bf16 v[10:13], v[190:193], v[114:117], v[10:13]
	v_mfma_f32_16x16x32_bf16 v[6:9], v[202:205], v[106:109], v[6:9]
	v_mfma_f32_16x16x32_bf16 v[2:5], v[198:201], v[114:117], v[2:5]
	v_mfma_f32_16x16x32_bf16 v[138:141], v[86:89], v[106:109], v[22:25]
	v_mfma_f32_16x16x32_bf16 v[150:153], v[86:89], v[118:121], v[18:21]
	v_mfma_f32_16x16x32_bf16 v[154:157], v[194:197], v[118:121], v[10:13]
	v_mfma_f32_16x16x32_bf16 v[190:193], v[202:205], v[118:121], v[2:5]
	s_barrier
	s_nop 1
	s_nop 0
	ds_read_b128 v[2:5], v149
	ds_read_b128 v[10:13], v149 offset:1024
	ds_read_b128 v[18:21], v149 offset:2048
	ds_read_b128 v[22:25], v149 offset:3072
	ds_read_b128 v[34:37], v142 offset:32768
	ds_read_b128 v[42:45], v142 offset:33792
	ds_read_b128 v[50:53], v142 offset:34816
	ds_read_b128 v[54:57], v142 offset:35840
	ds_read_b128 v[66:69], v142 offset:36864
	ds_read_b128 v[146:149], v142 offset:37888
	ds_read_b128 v[194:197], v142 offset:38912
	ds_read_b128 v[198:201], v142 offset:39936
	s_waitcnt vmcnt(2)
	s_barrier
	s_waitcnt lgkmcnt(0)
	v_mfma_f32_16x16x32_bf16 v[74:77], v[34:37], v[2:5], v[126:129]
	v_mfma_f32_16x16x32_bf16 v[118:121], v[42:45], v[10:13], v[74:77]
	v_mfma_f32_16x16x32_bf16 v[74:77], v[34:37], v[18:21], v[122:125]
	v_mfma_f32_16x16x32_bf16 v[126:129], v[42:45], v[22:25], v[74:77]
	v_mfma_f32_16x16x32_bf16 v[74:77], v[50:53], v[2:5], v[130:133]
	v_mfma_f32_16x16x32_bf16 v[114:117], v[54:57], v[10:13], v[74:77]
	v_mfma_f32_16x16x32_bf16 v[74:77], v[50:53], v[18:21], v[210:213]
	v_mfma_f32_16x16x32_bf16 v[122:125], v[54:57], v[22:25], v[74:77]
	v_mfma_f32_16x16x32_bf16 v[74:77], v[66:69], v[2:5], v[110:113]
	v_mfma_f32_16x16x32_bf16 v[106:109], v[146:149], v[10:13], v[74:77]
	v_mfma_f32_16x16x32_bf16 v[74:77], v[66:69], v[18:21], v[214:217]
	v_mfma_f32_16x16x32_bf16 v[110:113], v[146:149], v[22:25], v[74:77]
	v_mfma_f32_16x16x32_bf16 v[74:77], v[194:197], v[2:5], v[102:105]
	v_mfma_f32_16x16x32_bf16 v[98:101], v[198:201], v[10:13], v[74:77]
	v_mfma_f32_16x16x32_bf16 v[74:77], v[194:197], v[18:21], v[218:221]
	v_mfma_f32_16x16x32_bf16 v[102:105], v[198:201], v[22:25], v[74:77]
	s_barrier
; #define G_LDA(dst, b, h)                                                                                                  \
;   _Pragma("unroll") for (int m = 0; m < 4; ++m) _Pragma("unroll") for (int k = 0; k < 2; ++k)                             \
;       dst[m][k] = *(const bf16x8*)((const char*)G_SA(b, h) + ((wr * 4 + m) * 2 + k) * 1024 + rdo)
; #define G_LDB(dst, b, h)                                                                                                  \
;   _Pragma("unroll") for (int n = 0; n < 2; ++n) _Pragma("unroll") for (int k = 0; k < 2; ++k)                             \
;       dst[n][k] = *(const bf16x8*)((const char*)G_SB(b, h) + ((wc * 2 + n) * 2 + k) * 1024 + rdo)
; #define G_WAIT_V(n) asm volatile("s_waitcnt vmcnt(" #n ")" ::: "memory")
; #define G_WAIT_L(n) asm volatile("s_waitcnt lgkmcnt(" #n ")" ::: "memory")
; #define G_BAR __builtin_amdgcn_s_barrier()
;     ...
;     G_LDB(B1, 1, 1); G_WAIT_V(0); G_BAR; G_WAIT_L(0); G_MMA(0, 1, At, B1); G_BAR;
;     G_LDA(At, 1, 1); G_BAR; G_WAIT_L(0); G_MMA(1, 0, At, B0); G_MMA(1, 1, At, B1); G_BAR;
;   }
;   if (wr == 0) G_BAR;
	ds_read_b128 v[130:133], v145
	ds_read_b128 v[202:205], v145 offset:1024
	ds_read_b128 v[210:213], v145 offset:2048
	ds_read_b128 v[214:217], v145 offset:3072
	s_waitcnt vmcnt(0)
	s_barrier
	s_waitcnt lgkmcnt(0)
	v_mfma_f32_16x16x32_bf16 v[74:77], v[34:37], v[130:133], v[94:97]
	v_mfma_f32_16x16x32_bf16 v[34:37], v[34:37], v[210:213], v[90:93]
	v_mfma_f32_16x16x32_bf16 v[94:97], v[42:45], v[214:217], v[34:37]
	v_mfma_f32_16x16x32_bf16 v[34:37], v[50:53], v[130:133], v[158:161]
	v_mfma_f32_16x16x32_bf16 v[82:85], v[54:57], v[202:205], v[34:37]
	v_mfma_f32_16x16x32_bf16 v[34:37], v[50:53], v[210:213], v[164:167]
	v_mfma_f32_16x16x32_bf16 v[90:93], v[54:57], v[214:217], v[34:37]
	v_mfma_f32_16x16x32_bf16 v[34:37], v[66:69], v[130:133], v[78:81]
	v_mfma_f32_16x16x32_bf16 v[86:89], v[42:45], v[202:205], v[74:77]
	v_mfma_f32_16x16x32_bf16 v[74:77], v[146:149], v[202:205], v[34:37]
	v_mfma_f32_16x16x32_bf16 v[34:37], v[66:69], v[210:213], v[182:185]
	v_mfma_f32_16x16x32_bf16 v[78:81], v[146:149], v[214:217], v[34:37]
	v_mfma_f32_16x16x32_bf16 v[34:37], v[194:197], v[130:133], v[70:73]
	v_mfma_f32_16x16x32_bf16 v[66:69], v[198:201], v[202:205], v[34:37]
	v_mfma_f32_16x16x32_bf16 v[34:37], v[194:197], v[210:213], v[186:189]
	v_mfma_f32_16x16x32_bf16 v[70:73], v[198:201], v[214:217], v[34:37]
	s_barrier
	ds_read_b128 v[144:147], v142 offset:49152
	ds_read_b128 v[158:161], v142 offset:50176
	ds_read_b128 v[164:167], v142 offset:51200
	ds_read_b128 v[182:185], v142 offset:52224
	ds_read_b128 v[186:189], v142 offset:53248
	ds_read_b128 v[194:197], v142 offset:54272
	ds_read_b128 v[198:201], v142 offset:55296
	ds_read_b128 v[218:221], v142 offset:56320
	s_barrier
	s_waitcnt lgkmcnt(0)
	v_mfma_f32_16x16x32_bf16 v[34:37], v[144:147], v[2:5], v[62:65]
	v_mfma_f32_16x16x32_bf16 v[54:57], v[158:161], v[10:13], v[34:37]
	v_mfma_f32_16x16x32_bf16 v[34:37], v[144:147], v[18:21], v[58:61]
	v_mfma_f32_16x16x32_bf16 v[62:65], v[158:161], v[22:25], v[34:37]
	v_mfma_f32_16x16x32_bf16 v[34:37], v[164:167], v[2:5], v[206:209]
	v_mfma_f32_16x16x32_bf16 v[50:53], v[182:185], v[10:13], v[34:37]
	v_mfma_f32_16x16x32_bf16 v[34:37], v[164:167], v[18:21], v[222:225]
	v_mfma_f32_16x16x32_bf16 v[58:61], v[182:185], v[22:25], v[34:37]
	v_mfma_f32_16x16x32_bf16 v[34:37], v[186:189], v[2:5], v[46:49]
	v_mfma_f32_16x16x32_bf16 v[42:45], v[194:197], v[10:13], v[34:37]
	v_mfma_f32_16x16x32_bf16 v[34:37], v[186:189], v[18:21], v[226:229]
	v_mfma_f32_16x16x32_bf16 v[2:5], v[198:201], v[2:5], v[38:41]
	v_mfma_f32_16x16x32_bf16 v[46:49], v[194:197], v[22:25], v[34:37]
	v_mfma_f32_16x16x32_bf16 v[34:37], v[218:221], v[10:13], v[2:5]
	v_mfma_f32_16x16x32_bf16 v[2:5], v[198:201], v[18:21], v[134:137]
	v_mfma_f32_16x16x32_bf16 v[38:41], v[218:221], v[22:25], v[2:5]
	v_mfma_f32_16x16x32_bf16 v[2:5], v[144:147], v[130:133], v[30:33]
	v_mfma_f32_16x16x32_bf16 v[22:25], v[158:161], v[202:205], v[2:5]
	v_mfma_f32_16x16x32_bf16 v[2:5], v[144:147], v[210:213], v[26:29]
	v_mfma_f32_16x16x32_bf16 v[30:33], v[158:161], v[214:217], v[2:5]
	v_mfma_f32_16x16x32_bf16 v[2:5], v[164:167], v[130:133], v[138:141]
	v_mfma_f32_16x16x32_bf16 v[18:21], v[182:185], v[202:205], v[2:5]
	v_mfma_f32_16x16x32_bf16 v[2:5], v[164:167], v[210:213], v[150:153]
	v_mfma_f32_16x16x32_bf16 v[26:29], v[182:185], v[214:217], v[2:5]
	v_mfma_f32_16x16x32_bf16 v[2:5], v[186:189], v[130:133], v[14:17]
	v_mfma_f32_16x16x32_bf16 v[10:13], v[194:197], v[202:205], v[2:5]
	v_mfma_f32_16x16x32_bf16 v[2:5], v[186:189], v[210:213], v[154:157]
	v_mfma_f32_16x16x32_bf16 v[14:17], v[194:197], v[214:217], v[2:5]
	v_mfma_f32_16x16x32_bf16 v[2:5], v[198:201], v[130:133], v[6:9]
	v_mfma_f32_16x16x32_bf16 v[6:9], v[198:201], v[210:213], v[190:193]
	v_mfma_f32_16x16x32_bf16 v[2:5], v[218:221], v[202:205], v[2:5]
	v_mfma_f32_16x16x32_bf16 v[6:9], v[218:221], v[214:217], v[6:9]
	v_cmp_gt_u32_e32 vcc, s67, v0
	s_barrier
	s_and_saveexec_b64 s[20:21], vcc
	s_cbranch_execz .LBB0_69
	s_barrier

; #define G_LDA(dst, b, h)                                                                                                  \
;   _Pragma("unroll") for (int m = 0; m < 4; ++m) _Pragma("unroll") for (int k = 0; k < 2; ++k)                             \
;       dst[m][k] = *(const bf16x8*)((const char*)G_SA(b, h) + ((wr * 4 + m) * 2 + k) * 1024 + rdo)
; #define G_LDB(dst, b, h)                                                                                                  \
;   _Pragma("unroll") for (int n = 0; n < 2; ++n) _Pragma("unroll") for (int k = 0; k < 2; ++k)                             \
;       dst[n][k] = *(const bf16x8*)((const char*)G_SB(b, h) + ((wc * 2 + n) * 2 + k) * 1024 + rdo)
; #define G_WAIT_L(n) asm volatile("s_waitcnt lgkmcnt(" #n ")" ::: "memory")
; #define G_BAR __builtin_amdgcn_s_barrier()
; #define G_SCHED __builtin_amdgcn_sched_barrier(0)
;     ...
;   for (int tt = 0; tt < nt - 2; tt += 2) {
;     G_LDB(B0, 0, 0); G_SCHED; G_LDA(At, 0, 0); G_STAGE(G_SA(1, 1), A, oa0, oa1, LDA, 128, KA(tt + 1));
;     G_WAIT_L(8); G_BAR; G_WAIT_L(0); G_MMA(0, 0, At, B0); G_BAR; G_SCHED;
;     G_LDB(B1, 0, 1); G_STAGE(G_SB(0, 0), B, ob0, ob1, LDB, 0, KB(tt + 2));
;     G_BAR; G_WAIT_L(0); G_MMA(0, 1, At, B1); G_BAR;
;     G_LDA(At, 0, 1); G_STAGE(G_SA(0, 0), A, oa0, oa1, LDA, 0, KA(tt + 2));
;     G_BAR; G_WAIT_L(0); G_MMA(1, 0, At, B0); G_BAR; G_SCHED;
.LBB0_96:
	ds_read_b128 v[182:185], v151
	ds_read_b128 v[186:189], v151 offset:1024
	ds_read_b128 v[190:193], v151 offset:2048
	ds_read_b128 v[194:197], v151 offset:3072
	v_add_u32_e32 v162, 0xc000, v147
	v_lshl_add_u64 v[166:167], s[30:31], 0, v[140:141]
	v_readfirstlane_b32 s0, v162
	v_lshl_add_u64 v[164:165], v[166:167], 0, s[78:79]
	s_mov_b32 m0, s0
	ds_read_b128 v[198:201], v143
	ds_read_b128 v[202:205], v143 offset:1024
	ds_read_b128 v[206:209], v143 offset:2048
	ds_read_b128 v[210:213], v143 offset:3072
	ds_read_b128 v[214:217], v143 offset:4096
	ds_read_b128 v[218:221], v143 offset:5120
	ds_read_b128 v[222:225], v143 offset:6144
	ds_read_b128 v[226:229], v143 offset:7168
	global_load_lds_dwordx4 v[164:165], off
	v_add_u32_e32 v164, 0xe000, v147
	v_lshl_add_u64 v[246:247], s[30:31], 0, v[138:139]
	v_readfirstlane_b32 s0, v164
	v_lshl_add_u64 v[230:231], v[246:247], 0, s[78:79]
	s_mov_b32 m0, s0
	s_add_i32 s34, s13, -1
	global_load_lds_dwordx4 v[230:231], off
	s_waitcnt lgkmcnt(8)
	s_barrier
	s_waitcnt lgkmcnt(0)
	v_mfma_f32_16x16x32_bf16 v[126:129], v[198:201], v[182:185], v[126:129]
	v_mfma_f32_16x16x32_bf16 v[122:125], v[198:201], v[190:193], v[122:125]
	v_mfma_f32_16x16x32_bf16 v[118:121], v[206:209], v[182:185], v[118:121]
	v_mfma_f32_16x16x32_bf16 v[114:117], v[206:209], v[190:193], v[114:117]
	v_mfma_f32_16x16x32_bf16 v[110:113], v[214:217], v[182:185], v[110:113]
	v_mfma_f32_16x16x32_bf16 v[106:109], v[214:217], v[190:193], v[106:109]
	v_mfma_f32_16x16x32_bf16 v[102:105], v[222:225], v[182:185], v[102:105]
	v_mfma_f32_16x16x32_bf16 v[98:101], v[222:225], v[190:193], v[98:101]
	v_mfma_f32_16x16x32_bf16 v[126:129], v[202:205], v[186:189], v[126:129]
	v_mfma_f32_16x16x32_bf16 v[122:125], v[202:205], v[194:197], v[122:125]
	v_mfma_f32_16x16x32_bf16 v[118:121], v[210:213], v[186:189], v[118:121]
	v_mfma_f32_16x16x32_bf16 v[114:117], v[210:213], v[194:197], v[114:117]
	v_mfma_f32_16x16x32_bf16 v[110:113], v[218:221], v[186:189], v[110:113]
	v_mfma_f32_16x16x32_bf16 v[106:109], v[218:221], v[194:197], v[106:109]
	v_mfma_f32_16x16x32_bf16 v[102:105], v[226:229], v[186:189], v[102:105]
	v_mfma_f32_16x16x32_bf16 v[98:101], v[226:229], v[194:197], v[98:101]
	s_barrier
	s_add_i32 s0, s25, 0xffff0000
	s_sub_i32 s1, s23, 64
	s_and_b32 s0, s0, 0x1c0000
	s_and_b32 s1, s1, 0x80
	s_or_b32 s0, s0, s1
	s_lshl_b32 s35, s0, 1
	s_add_u32 s0, s26, s35
	s_addc_u32 s1, s27, 0
	v_readfirstlane_b32 s36, v149
	v_lshl_add_u64 v[248:249], s[0:1], 0, v[134:135]
	s_mov_b32 m0, s36
	ds_read_b128 v[230:233], v146
	ds_read_b128 v[234:237], v146 offset:1024
	ds_read_b128 v[238:241], v146 offset:2048
	ds_read_b128 v[242:245], v146 offset:3072
	global_load_lds_dwordx4 v[248:249], off
	v_lshl_add_u64 v[248:249], s[0:1], 0, v[136:137]
	v_readfirstlane_b32 s0, v150
	s_mov_b32 m0, s0
	s_nop 0
	global_load_lds_dwordx4 v[248:249], off
	s_barrier
	s_waitcnt lgkmcnt(0)
	v_mfma_f32_16x16x32_bf16 v[94:97], v[198:201], v[230:233], v[94:97]
	v_mfma_f32_16x16x32_bf16 v[90:93], v[198:201], v[238:241], v[90:93]
	v_mfma_f32_16x16x32_bf16 v[86:89], v[206:209], v[230:233], v[86:89]
	v_mfma_f32_16x16x32_bf16 v[82:85], v[206:209], v[238:241], v[82:85]
	v_mfma_f32_16x16x32_bf16 v[78:81], v[214:217], v[230:233], v[78:81]
	v_mfma_f32_16x16x32_bf16 v[74:77], v[214:217], v[238:241], v[74:77]
	v_mfma_f32_16x16x32_bf16 v[70:73], v[222:225], v[230:233], v[70:73]
	v_mfma_f32_16x16x32_bf16 v[66:69], v[222:225], v[238:241], v[66:69]
	v_mfma_f32_16x16x32_bf16 v[94:97], v[202:205], v[234:237], v[94:97]
	v_mfma_f32_16x16x32_bf16 v[90:93], v[202:205], v[242:245], v[90:93]
	v_mfma_f32_16x16x32_bf16 v[86:89], v[210:213], v[234:237], v[86:89]
	v_mfma_f32_16x16x32_bf16 v[82:85], v[210:213], v[242:245], v[82:85]
	v_mfma_f32_16x16x32_bf16 v[78:81], v[218:221], v[234:237], v[78:81]
	v_mfma_f32_16x16x32_bf16 v[74:77], v[218:221], v[242:245], v[74:77]
	v_mfma_f32_16x16x32_bf16 v[70:73], v[226:229], v[234:237], v[70:73]
	v_mfma_f32_16x16x32_bf16 v[66:69], v[226:229], v[242:245], v[66:69]
	v_readfirstlane_b32 s0, v147
	v_lshl_add_u64 v[248:249], v[166:167], 0, s[82:83]
	s_mov_b32 m0, s0
	v_readfirstlane_b32 s0, v148
	s_barrier
	ds_read_b128 v[198:201], v143 offset:16384
	ds_read_b128 v[202:205], v143 offset:17408
	ds_read_b128 v[206:209], v143 offset:18432
	ds_read_b128 v[210:213], v143 offset:19456
	ds_read_b128 v[214:217], v143 offset:20480
	ds_read_b128 v[218:221], v143 offset:21504
	ds_read_b128 v[222:225], v143 offset:22528
	ds_read_b128 v[226:229], v143 offset:23552
	global_load_lds_dwordx4 v[248:249], off
	v_lshl_add_u64 v[248:249], v[246:247], 0, s[82:83]
	s_mov_b32 m0, s0
	s_nop 0
	global_load_lds_dwordx4 v[248:249], off
	s_barrier
	s_waitcnt lgkmcnt(0)
	v_mfma_f32_16x16x32_bf16 v[62:65], v[198:201], v[182:185], v[62:65]
	v_mfma_f32_16x16x32_bf16 v[58:61], v[198:201], v[190:193], v[58:61]
	v_mfma_f32_16x16x32_bf16 v[54:57], v[206:209], v[182:185], v[54:57]
	v_mfma_f32_16x16x32_bf16 v[50:53], v[206:209], v[190:193], v[50:53]
	v_mfma_f32_16x16x32_bf16 v[46:49], v[214:217], v[182:185], v[46:49]
	v_mfma_f32_16x16x32_bf16 v[42:45], v[214:217], v[190:193], v[42:45]
	v_mfma_f32_16x16x32_bf16 v[38:41], v[222:225], v[182:185], v[38:41]
	v_mfma_f32_16x16x32_bf16 v[34:37], v[222:225], v[190:193], v[34:37]
	v_mfma_f32_16x16x32_bf16 v[62:65], v[202:205], v[186:189], v[62:65]
	v_mfma_f32_16x16x32_bf16 v[58:61], v[202:205], v[194:197], v[58:61]
	v_mfma_f32_16x16x32_bf16 v[54:57], v[210:213], v[186:189], v[54:57]
	v_mfma_f32_16x16x32_bf16 v[50:53], v[210:213], v[194:197], v[50:53]
	v_mfma_f32_16x16x32_bf16 v[46:49], v[218:221], v[186:189], v[46:49]
	v_mfma_f32_16x16x32_bf16 v[42:45], v[218:221], v[194:197], v[42:45]
	v_mfma_f32_16x16x32_bf16 v[38:41], v[226:229], v[186:189], v[38:41]
	v_mfma_f32_16x16x32_bf16 v[34:37], v[226:229], v[194:197], v[34:37]
	s_barrier
; #define G_LDA(dst, b, h)                                                                                                  \
;   _Pragma("unroll") for (int m = 0; m < 4; ++m) _Pragma("unroll") for (int k = 0; k < 2; ++k)                             \
;       dst[m][k] = *(const bf16x8*)((const char*)G_SA(b, h) + ((wr * 4 + m) * 2 + k) * 1024 + rdo)
; #define G_LDB(dst, b, h)                                                                                                  \
;   _Pragma("unroll") for (int n = 0; n < 2; ++n) _Pragma("unroll") for (int k = 0; k < 2; ++k)                             \
;       dst[n][k] = *(const bf16x8*)((const char*)G_SB(b, h) + ((wc * 2 + n) * 2 + k) * 1024 + rdo)
; #define G_WAIT_V(n) asm volatile("s_waitcnt vmcnt(" #n ")" ::: "memory")
; #define G_WAIT_L(n) asm volatile("s_waitcnt lgkmcnt(" #n ")" ::: "memory")
; #define G_BAR __builtin_amdgcn_s_barrier()
; #define G_SCHED __builtin_amdgcn_sched_barrier(0)
;     ...
;     G_STAGE(G_SB(0, 1), B, ob0, ob1, LDB, 128, KB(tt + 2));
;     G_WAIT_V(6); G_BAR; G_MMA(1, 1, At, B1); G_BAR;
;     G_LDB(B0, 1, 0); G_SCHED; G_LDA(At, 1, 0); G_STAGE(G_SA(0, 1), A, oa0, oa1, LDA, 128, KA(tt + 2));
;     G_WAIT_L(8); G_BAR; G_WAIT_L(0); G_MMA(0, 0, At, B0); G_BAR; G_SCHED;
;     G_LDB(B1, 1, 1); G_STAGE(G_SB(1, 0), B, ob0, ob1, LDB, 0, KB(tt + 3));
;     G_BAR; G_WAIT_L(0); G_MMA(0, 1, At, B1); G_BAR;
;     G_LDA(At, 1, 1); G_STAGE(G_SA(1, 0), A, oa0, oa1, LDA, 0, KA(tt + 3));
	s_add_u32 s0, s28, s35
	s_addc_u32 s1, s29, 0
	v_readfirstlane_b32 s35, v152
	v_lshl_add_u64 v[182:183], s[0:1], 0, v[134:135]
	s_mov_b32 m0, s35
	s_nop 0
	global_load_lds_dwordx4 v[182:183], off
	v_lshl_add_u64 v[182:183], s[0:1], 0, v[136:137]
	v_readfirstlane_b32 s0, v153
	s_mov_b32 m0, s0
	s_nop 0
	global_load_lds_dwordx4 v[182:183], off
	s_waitcnt vmcnt(6)
	s_barrier
	v_mfma_f32_16x16x32_bf16 v[30:33], v[198:201], v[230:233], v[30:33]
	v_mfma_f32_16x16x32_bf16 v[26:29], v[198:201], v[238:241], v[26:29]
	v_mfma_f32_16x16x32_bf16 v[22:25], v[206:209], v[230:233], v[22:25]
	v_mfma_f32_16x16x32_bf16 v[18:21], v[206:209], v[238:241], v[18:21]
	v_mfma_f32_16x16x32_bf16 v[14:17], v[214:217], v[230:233], v[14:17]
	v_mfma_f32_16x16x32_bf16 v[10:13], v[214:217], v[238:241], v[10:13]
	v_mfma_f32_16x16x32_bf16 v[6:9], v[222:225], v[230:233], v[6:9]
	v_mfma_f32_16x16x32_bf16 v[2:5], v[222:225], v[238:241], v[2:5]
	v_mfma_f32_16x16x32_bf16 v[30:33], v[202:205], v[234:237], v[30:33]
	v_mfma_f32_16x16x32_bf16 v[26:29], v[202:205], v[242:245], v[26:29]
	v_mfma_f32_16x16x32_bf16 v[22:25], v[210:213], v[234:237], v[22:25]
	v_mfma_f32_16x16x32_bf16 v[18:21], v[210:213], v[242:245], v[18:21]
	v_mfma_f32_16x16x32_bf16 v[14:17], v[218:221], v[234:237], v[14:17]
	v_mfma_f32_16x16x32_bf16 v[10:13], v[218:221], v[242:245], v[10:13]
	v_mfma_f32_16x16x32_bf16 v[6:9], v[226:229], v[234:237], v[6:9]
	v_mfma_f32_16x16x32_bf16 v[2:5], v[226:229], v[242:245], v[2:5]
	s_barrier
	ds_read_b128 v[182:185], v145
	ds_read_b128 v[186:189], v145 offset:1024
	ds_read_b128 v[190:193], v145 offset:2048
	ds_read_b128 v[194:197], v145 offset:3072
	v_readfirstlane_b32 s0, v154
	v_lshl_add_u64 v[230:231], v[166:167], 0, s[86:87]
	s_mov_b32 m0, s0
	v_readfirstlane_b32 s0, v155
	ds_read_b128 v[198:201], v143 offset:32768
	ds_read_b128 v[202:205], v143 offset:33792
	ds_read_b128 v[206:209], v143 offset:34816
	ds_read_b128 v[210:213], v143 offset:35840
	ds_read_b128 v[214:217], v143 offset:36864
	ds_read_b128 v[218:221], v143 offset:37888
	ds_read_b128 v[222:225], v143 offset:38912
	ds_read_b128 v[226:229], v143 offset:39936
	global_load_lds_dwordx4 v[230:231], off
	v_lshl_add_u64 v[230:231], v[246:247], 0, s[86:87]
	s_mov_b32 m0, s0
	s_nop 0
	global_load_lds_dwordx4 v[230:231], off
	s_waitcnt lgkmcnt(8)
	s_barrier
	s_waitcnt lgkmcnt(0)
	v_mfma_f32_16x16x32_bf16 v[126:129], v[198:201], v[182:185], v[126:129]
	v_mfma_f32_16x16x32_bf16 v[122:125], v[198:201], v[190:193], v[122:125]
	v_mfma_f32_16x16x32_bf16 v[118:121], v[206:209], v[182:185], v[118:121]
	v_mfma_f32_16x16x32_bf16 v[114:117], v[206:209], v[190:193], v[114:117]
	v_mfma_f32_16x16x32_bf16 v[110:113], v[214:217], v[182:185], v[110:113]
	v_mfma_f32_16x16x32_bf16 v[106:109], v[214:217], v[190:193], v[106:109]
	v_mfma_f32_16x16x32_bf16 v[102:105], v[222:225], v[182:185], v[102:105]
	v_mfma_f32_16x16x32_bf16 v[98:101], v[222:225], v[190:193], v[98:101]
	v_mfma_f32_16x16x32_bf16 v[126:129], v[202:205], v[186:189], v[126:129]
	v_mfma_f32_16x16x32_bf16 v[122:125], v[202:205], v[194:197], v[122:125]
	v_mfma_f32_16x16x32_bf16 v[118:121], v[210:213], v[186:189], v[118:121]
	v_mfma_f32_16x16x32_bf16 v[114:117], v[210:213], v[194:197], v[114:117]
	v_mfma_f32_16x16x32_bf16 v[110:113], v[218:221], v[186:189], v[110:113]
	v_mfma_f32_16x16x32_bf16 v[106:109], v[218:221], v[194:197], v[106:109]
	v_mfma_f32_16x16x32_bf16 v[102:105], v[226:229], v[186:189], v[102:105]
	v_mfma_f32_16x16x32_bf16 v[98:101], v[226:229], v[194:197], v[98:101]
	s_barrier
	s_and_b32 s0, s25, 0x1c0000
	s_and_b32 s1, s23, 0xc0
	s_or_b32 s0, s0, s1
	s_lshl_b32 s35, s0, 1
	s_add_u32 s0, s26, s35
	s_addc_u32 s1, s27, 0
	v_readfirstlane_b32 s36, v156
	v_lshl_add_u64 v[248:249], s[0:1], 0, v[134:135]
	s_mov_b32 m0, s36
	ds_read_b128 v[230:233], v144
	ds_read_b128 v[234:237], v144 offset:1024
	ds_read_b128 v[238:241], v144 offset:2048
	ds_read_b128 v[242:245], v144 offset:3072
	global_load_lds_dwordx4 v[248:249], off
	v_lshl_add_u64 v[248:249], s[0:1], 0, v[136:137]
	v_readfirstlane_b32 s0, v157
	s_mov_b32 m0, s0
	s_nop 0
	global_load_lds_dwordx4 v[248:249], off
	s_barrier
	s_waitcnt lgkmcnt(0)
	v_mfma_f32_16x16x32_bf16 v[94:97], v[198:201], v[230:233], v[94:97]
	v_mfma_f32_16x16x32_bf16 v[90:93], v[198:201], v[238:241], v[90:93]
	v_mfma_f32_16x16x32_bf16 v[86:89], v[206:209], v[230:233], v[86:89]
	v_mfma_f32_16x16x32_bf16 v[82:85], v[206:209], v[238:241], v[82:85]
	v_mfma_f32_16x16x32_bf16 v[78:81], v[214:217], v[230:233], v[78:81]
	v_mfma_f32_16x16x32_bf16 v[74:77], v[214:217], v[238:241], v[74:77]
	v_mfma_f32_16x16x32_bf16 v[70:73], v[222:225], v[230:233], v[70:73]
	v_mfma_f32_16x16x32_bf16 v[66:69], v[222:225], v[238:241], v[66:69]
	v_mfma_f32_16x16x32_bf16 v[94:97], v[202:205], v[234:237], v[94:97]
	v_mfma_f32_16x16x32_bf16 v[90:93], v[202:205], v[242:245], v[90:93]
	v_mfma_f32_16x16x32_bf16 v[86:89], v[210:213], v[234:237], v[86:89]
	v_mfma_f32_16x16x32_bf16 v[82:85], v[210:213], v[242:245], v[82:85]
	v_mfma_f32_16x16x32_bf16 v[78:81], v[218:221], v[234:237], v[78:81]
	v_mfma_f32_16x16x32_bf16 v[74:77], v[218:221], v[242:245], v[74:77]
	v_mfma_f32_16x16x32_bf16 v[70:73], v[226:229], v[234:237], v[70:73]
	v_mfma_f32_16x16x32_bf16 v[66:69], v[226:229], v[242:245], v[66:69]
	v_readfirstlane_b32 s0, v158
	v_lshl_add_u64 v[166:167], v[166:167], 0, s[90:91]
	s_mov_b32 m0, s0
	v_readfirstlane_b32 s0, v159
	s_barrier
; DI unsigned pack2(float a, float b) { unsigned r; asm("v_cvt_pk_bf16_f32 %0, %1, %2\n\ts_nop 1" : "=v"(r) : "v"(a), "v"(b)); return r; }
; #define G_WAIT_V(n) asm volatile("s_waitcnt vmcnt(" #n ")" ::: "memory")
; #define G_WAIT_L(n) asm volatile("s_waitcnt lgkmcnt(" #n ")" ::: "memory")
; #define G_BAR __builtin_amdgcn_s_barrier()
; #define G_SCHED __builtin_amdgcn_sched_barrier(0)
; DI u32x4* merge_scratch(PREF p, int region) { const int t = tid512(); return (u32x4*)p.fbuf + (size_t)blockIdx.x * 40960 + region * 8192 + (t >> 6) * 1024 + (t & 63); }
; DI void br_flush(PREF p, f32x4 (&acc)[2][2][4][2], int slot) { br_store(p, acc, slot); zero_acc256(acc); }
;     ...
;     G_BAR; G_WAIT_L(0); G_MMA(1, 0, At, B0); G_BAR; G_SCHED;
;     G_STAGE(G_SB(1, 1), B, ob0, ob1, LDB, 128, KB(tt + 3));
;     G_WAIT_V(6); G_BAR; G_MMA(1, 1, At, B1); G_BAR;
;     if (MODE && ((tt + 1) & 3) == 3) br_flush(p, acc, (tt + 1) >> 2);
; DI void br_store(PREF p, const f32x4 (&acc)[2][2][4][2], int slot) {
;   u32x4* sb = merge_scratch(p, slot);
; #pragma unroll
;   for (int ai = 0; ai < 2; ++ai)
; #pragma unroll
;     for (int bj = 0; bj < 2; ++bj)
; #pragma unroll
;       for (int m = 0; m < 4; ++m) {
;         u32x4 o;
;         o.x = pack2(acc[ai][bj][m][0][0], acc[ai][bj][m][0][1]); o.y = pack2(acc[ai][bj][m][0][2], acc[ai][bj][m][0][3]);
;         o.z = pack2(acc[ai][bj][m][1][0], acc[ai][bj][m][1][1]); o.w = pack2(acc[ai][bj][m][1][2], acc[ai][bj][m][1][3]);
;         sb[((ai * 2 + bj) * 4 + m) * 64] = o;
;       }
; }
	ds_read_b128 v[198:201], v143 offset:49152
	ds_read_b128 v[202:205], v143 offset:50176
	ds_read_b128 v[206:209], v143 offset:51200
	ds_read_b128 v[210:213], v143 offset:52224
	ds_read_b128 v[214:217], v143 offset:53248
	ds_read_b128 v[218:221], v143 offset:54272
	ds_read_b128 v[222:225], v143 offset:55296
	ds_read_b128 v[226:229], v143 offset:56320
	global_load_lds_dwordx4 v[166:167], off
	v_lshl_add_u64 v[166:167], v[246:247], 0, s[90:91]
	s_mov_b32 m0, s0
	s_nop 0
	global_load_lds_dwordx4 v[166:167], off
	s_barrier
	s_waitcnt lgkmcnt(0)
	v_mfma_f32_16x16x32_bf16 v[62:65], v[198:201], v[182:185], v[62:65]
	v_mfma_f32_16x16x32_bf16 v[58:61], v[198:201], v[190:193], v[58:61]
	v_mfma_f32_16x16x32_bf16 v[54:57], v[206:209], v[182:185], v[54:57]
	v_mfma_f32_16x16x32_bf16 v[50:53], v[206:209], v[190:193], v[50:53]
	v_mfma_f32_16x16x32_bf16 v[46:49], v[214:217], v[182:185], v[46:49]
	v_mfma_f32_16x16x32_bf16 v[42:45], v[214:217], v[190:193], v[42:45]
	v_mfma_f32_16x16x32_bf16 v[38:41], v[222:225], v[182:185], v[38:41]
	v_mfma_f32_16x16x32_bf16 v[34:37], v[222:225], v[190:193], v[34:37]
	v_mfma_f32_16x16x32_bf16 v[62:65], v[202:205], v[186:189], v[62:65]
	v_mfma_f32_16x16x32_bf16 v[58:61], v[202:205], v[194:197], v[58:61]
	v_mfma_f32_16x16x32_bf16 v[54:57], v[210:213], v[186:189], v[54:57]
	v_mfma_f32_16x16x32_bf16 v[50:53], v[210:213], v[194:197], v[50:53]
	v_mfma_f32_16x16x32_bf16 v[46:49], v[218:221], v[186:189], v[46:49]
	v_mfma_f32_16x16x32_bf16 v[42:45], v[218:221], v[194:197], v[42:45]
	v_mfma_f32_16x16x32_bf16 v[38:41], v[226:229], v[186:189], v[38:41]
	v_mfma_f32_16x16x32_bf16 v[34:37], v[226:229], v[194:197], v[34:37]
	s_barrier
	s_add_u32 s0, s28, s35
	s_addc_u32 s1, s29, 0
	v_readfirstlane_b32 s35, v160
	v_lshl_add_u64 v[166:167], s[0:1], 0, v[134:135]
	s_mov_b32 m0, s35
	s_nop 0
	global_load_lds_dwordx4 v[166:167], off
	v_lshl_add_u64 v[166:167], s[0:1], 0, v[136:137]
	v_readfirstlane_b32 s0, v161
	s_mov_b32 m0, s0
	s_nop 0
	global_load_lds_dwordx4 v[166:167], off
	s_waitcnt vmcnt(6)
	s_barrier
	v_mfma_f32_16x16x32_bf16 v[30:33], v[198:201], v[230:233], v[30:33]
	v_mfma_f32_16x16x32_bf16 v[26:29], v[198:201], v[238:241], v[26:29]
	v_mfma_f32_16x16x32_bf16 v[22:25], v[206:209], v[230:233], v[22:25]
	v_mfma_f32_16x16x32_bf16 v[18:21], v[206:209], v[238:241], v[18:21]
	v_mfma_f32_16x16x32_bf16 v[14:17], v[214:217], v[230:233], v[14:17]
	v_mfma_f32_16x16x32_bf16 v[10:13], v[214:217], v[238:241], v[10:13]
	v_mfma_f32_16x16x32_bf16 v[6:9], v[222:225], v[230:233], v[6:9]
	v_mfma_f32_16x16x32_bf16 v[2:5], v[222:225], v[238:241], v[2:5]
	v_mfma_f32_16x16x32_bf16 v[30:33], v[202:205], v[234:237], v[30:33]
	v_mfma_f32_16x16x32_bf16 v[26:29], v[202:205], v[242:245], v[26:29]
	v_mfma_f32_16x16x32_bf16 v[22:25], v[210:213], v[234:237], v[22:25]
	v_mfma_f32_16x16x32_bf16 v[18:21], v[210:213], v[242:245], v[18:21]
	v_mfma_f32_16x16x32_bf16 v[14:17], v[218:221], v[234:237], v[14:17]
	v_mfma_f32_16x16x32_bf16 v[10:13], v[218:221], v[242:245], v[10:13]
	v_mfma_f32_16x16x32_bf16 v[6:9], v[226:229], v[234:237], v[6:9]
	v_mfma_f32_16x16x32_bf16 v[2:5], v[226:229], v[242:245], v[2:5]
	s_and_b32 s0, s34, 3
	s_cmp_eq_u32 s0, 3
	s_barrier
	s_cbranch_scc0 .LBB0_95
	v_mov_b32_e32 v0, v168
	s_and_b32 s0, s12, 0x6000
	s_lshl_b32 s0, s0, 4
	v_lshlrev_b32_e32 v165, 4, v0
	s_add_u32 s0, s63, s0
	v_and_b32_e32 v166, 0xfffffc00, v165
	s_addc_u32 s1, s64, 0
	v_ashrrev_i32_e32 v167, 31, v166
	v_and_b32_e32 v0, 63, v0
	v_lshl_add_u64 v[166:167], v[166:167], 4, s[0:1]
	v_lshlrev_b32_e32 v0, 4, v0
	v_lshl_add_u64 v[166:167], v[166:167], 0, v[0:1]
	v_cvt_pk_bf16_f32 v94, v94, v95
	v_cvt_pk_bf16_f32 v95, v96, v97
	v_cvt_pk_bf16_f32 v96, v90, v91
	v_add_co_u32_e32 v90, vcc, s80, v166
	v_cvt_pk_bf16_f32 v97, v92, v93
	s_movk_i32 s0, 0x3000
	s_nop 0
	v_addc_co_u32_e32 v91, vcc, 0, v167, vcc
	v_add_co_u32_e32 v92, vcc, s40, v166
	v_cvt_pk_bf16_f32 v30, v30, v31
	v_cvt_pk_bf16_f32 v31, v32, v33
	v_cvt_pk_bf16_f32 v32, v26, v27
	v_cvt_pk_bf16_f32 v126, v126, v127
	s_nop 1
	v_addc_co_u32_e32 v93, vcc, 0, v167, vcc
	v_add_co_u32_e32 v26, vcc, s0, v166
	v_cvt_pk_bf16_f32 v127, v128, v129
	v_cvt_pk_bf16_f32 v128, v122, v123
	v_cvt_pk_bf16_f32 v129, v124, v125
	v_cvt_pk_bf16_f32 v118, v118, v119
	v_cvt_pk_bf16_f32 v119, v120, v121
	v_cvt_pk_bf16_f32 v120, v114, v115
	v_cvt_pk_bf16_f32 v121, v116, v117
	v_cvt_pk_bf16_f32 v110, v110, v111
	v_cvt_pk_bf16_f32 v111, v112, v113
	v_cvt_pk_bf16_f32 v112, v106, v107
	v_cvt_pk_bf16_f32 v113, v108, v109
	v_cvt_pk_bf16_f32 v102, v102, v103
	v_cvt_pk_bf16_f32 v103, v104, v105
	v_cvt_pk_bf16_f32 v104, v98, v99
	v_cvt_pk_bf16_f32 v105, v100, v101
	v_cvt_pk_bf16_f32 v86, v86, v87
	v_cvt_pk_bf16_f32 v87, v88, v89
	v_cvt_pk_bf16_f32 v88, v82, v83
	v_cvt_pk_bf16_f32 v89, v84, v85
	v_cvt_pk_bf16_f32 v78, v78, v79
	v_cvt_pk_bf16_f32 v79, v80, v81
	v_cvt_pk_bf16_f32 v80, v74, v75
	v_cvt_pk_bf16_f32 v81, v76, v77
	v_cvt_pk_bf16_f32 v70, v70, v71
	v_cvt_pk_bf16_f32 v71, v72, v73
	v_cvt_pk_bf16_f32 v72, v66, v67
	v_cvt_pk_bf16_f32 v73, v68, v69
	v_cvt_pk_bf16_f32 v62, v62, v63
	v_cvt_pk_bf16_f32 v63, v64, v65
	v_cvt_pk_bf16_f32 v64, v58, v59
	v_cvt_pk_bf16_f32 v65, v60, v61
	v_cvt_pk_bf16_f32 v54, v54, v55
	v_cvt_pk_bf16_f32 v55, v56, v57
	v_cvt_pk_bf16_f32 v56, v50, v51
	v_cvt_pk_bf16_f32 v57, v52, v53
	v_cvt_pk_bf16_f32 v46, v46, v47
	v_cvt_pk_bf16_f32 v47, v48, v49
	v_cvt_pk_bf16_f32 v48, v42, v43
	v_cvt_pk_bf16_f32 v49, v44, v45
	v_cvt_pk_bf16_f32 v38, v38, v39
	v_cvt_pk_bf16_f32 v39, v40, v41
	v_cvt_pk_bf16_f32 v40, v34, v35
	v_cvt_pk_bf16_f32 v41, v36, v37
	v_cvt_pk_bf16_f32 v33, v28, v29
	s_nop 1
	v_addc_co_u32_e32 v27, vcc, 0, v167, vcc
; DI unsigned pack2(float a, float b) { unsigned r; asm("v_cvt_pk_bf16_f32 %0, %1, %2\n\ts_nop 1" : "=v"(r) : "v"(a), "v"(b)); return r; }
; DI u32x4* merge_scratch(PREF p, int region) { const int t = tid512(); return (u32x4*)p.fbuf + (size_t)blockIdx.x * 40960 + region * 8192 + (t >> 6) * 1024 + (t & 63); }
; DI void br_store(PREF p, const f32x4 (&acc)[2][2][4][2], int slot) {
;   u32x4* sb = merge_scratch(p, slot);
; #pragma unroll
;   for (int ai = 0; ai < 2; ++ai)
; #pragma unroll
;     for (int bj = 0; bj < 2; ++bj)
; #pragma unroll
;       for (int m = 0; m < 4; ++m) {
;         u32x4 o;
;         o.x = pack2(acc[ai][bj][m][0][0], acc[ai][bj][m][0][1]); o.y = pack2(acc[ai][bj][m][0][2], acc[ai][bj][m][0][3]);
;         o.z = pack2(acc[ai][bj][m][1][0], acc[ai][bj][m][1][1]); o.w = pack2(acc[ai][bj][m][1][2], acc[ai][bj][m][1][3]);
;         sb[((ai * 2 + bj) * 4 + m) * 64] = o;
;       }
; }
; DI void br_flush(PREF p, f32x4 (&acc)[2][2][4][2], int slot) { br_store(p, acc, slot); zero_acc256(acc); }
	v_cvt_pk_bf16_f32 v22, v22, v23
	v_cvt_pk_bf16_f32 v23, v24, v25
	v_cvt_pk_bf16_f32 v24, v18, v19
	v_cvt_pk_bf16_f32 v25, v20, v21
	v_cvt_pk_bf16_f32 v14, v14, v15
	v_cvt_pk_bf16_f32 v15, v16, v17
	v_cvt_pk_bf16_f32 v16, v10, v11
	v_cvt_pk_bf16_f32 v17, v12, v13
	v_cvt_pk_bf16_f32 v6, v6, v7
	v_cvt_pk_bf16_f32 v7, v8, v9
	v_cvt_pk_bf16_f32 v8, v2, v3
	v_cvt_pk_bf16_f32 v9, v4, v5
	v_mov_b32_e32 v2, 0
	global_store_dwordx4 v[166:167], v[126:129], off
	global_store_dwordx4 v[166:167], v[118:121], off offset:1024
	global_store_dwordx4 v[166:167], v[110:113], off offset:2048
	global_store_dwordx4 v[166:167], v[102:105], off offset:3072
	global_store_dwordx4 v[92:93], v[94:97], off offset:-4096
	global_store_dwordx4 v[90:91], v[86:89], off offset:1024
	global_store_dwordx4 v[90:91], v[78:81], off offset:2048
	global_store_dwordx4 v[90:91], v[70:73], off offset:3072
	global_store_dwordx4 v[92:93], v[62:65], off
	global_store_dwordx4 v[92:93], v[54:57], off offset:1024
	global_store_dwordx4 v[92:93], v[46:49], off offset:2048
	global_store_dwordx4 v[92:93], v[38:41], off offset:3072
	global_store_dwordx4 v[26:27], v[30:33], off
	global_store_dwordx4 v[26:27], v[22:25], off offset:1024
	global_store_dwordx4 v[26:27], v[14:17], off offset:2048
	global_store_dwordx4 v[26:27], v[6:9], off offset:3072
	v_mov_b32_e32 v3, v2
	v_mov_b32_e32 v4, v2
	v_mov_b32_e32 v5, v2
	v_mov_b32_e32 v6, v2
	v_mov_b32_e32 v7, v2
	v_mov_b32_e32 v8, v2
	v_mov_b32_e32 v9, v2
	v_mov_b32_e32 v10, v2
	v_mov_b32_e32 v11, v2
	v_mov_b32_e32 v12, v2
	v_mov_b32_e32 v13, v2
	v_mov_b32_e32 v14, v2
	v_mov_b32_e32 v15, v2
	v_mov_b32_e32 v16, v2
	v_mov_b32_e32 v17, v2
	v_mov_b32_e32 v18, v2
	v_mov_b32_e32 v19, v2
	v_mov_b32_e32 v20, v2
	v_mov_b32_e32 v21, v2
	v_mov_b32_e32 v22, v2
	v_mov_b32_e32 v23, v2
	v_mov_b32_e32 v24, v2
	v_mov_b32_e32 v25, v2
	v_mov_b32_e32 v26, v2
	v_mov_b32_e32 v27, v2
	v_mov_b32_e32 v28, v2
	v_mov_b32_e32 v29, v2
	v_mov_b32_e32 v30, v2
	v_mov_b32_e32 v31, v2
	v_mov_b32_e32 v32, v2
	v_mov_b32_e32 v33, v2
	v_mov_b32_e32 v34, v2
	v_mov_b32_e32 v35, v2
	v_mov_b32_e32 v36, v2
	v_mov_b32_e32 v37, v2
	v_mov_b32_e32 v38, v2
	v_mov_b32_e32 v39, v2
	v_mov_b32_e32 v40, v2
	v_mov_b32_e32 v41, v2
	v_mov_b32_e32 v42, v2
	v_mov_b32_e32 v43, v2
	v_mov_b32_e32 v44, v2
	v_mov_b32_e32 v45, v2
	v_mov_b32_e32 v46, v2
	v_mov_b32_e32 v47, v2
	v_mov_b32_e32 v48, v2
	v_mov_b32_e32 v49, v2
	v_mov_b32_e32 v50, v2
	v_mov_b32_e32 v51, v2
	v_mov_b32_e32 v52, v2
	v_mov_b32_e32 v53, v2
	v_mov_b32_e32 v54, v2
	v_mov_b32_e32 v55, v2
	v_mov_b32_e32 v56, v2
	v_mov_b32_e32 v57, v2
	v_mov_b32_e32 v58, v2
	v_mov_b32_e32 v59, v2
	v_mov_b32_e32 v60, v2
	v_mov_b32_e32 v61, v2
	v_mov_b32_e32 v62, v2
	v_mov_b32_e32 v63, v2
	v_mov_b32_e32 v64, v2
	v_mov_b32_e32 v65, v2
	v_mov_b32_e32 v66, v2
	v_mov_b32_e32 v67, v2
	v_mov_b32_e32 v68, v2
	v_mov_b32_e32 v69, v2
	v_mov_b32_e32 v70, v2
	v_mov_b32_e32 v71, v2
	v_mov_b32_e32 v72, v2
	v_mov_b32_e32 v73, v2
	v_mov_b32_e32 v74, v2
	v_mov_b32_e32 v75, v2
	v_mov_b32_e32 v76, v2
	v_mov_b32_e32 v77, v2
	v_mov_b32_e32 v78, v2
	v_mov_b32_e32 v79, v2
	v_mov_b32_e32 v80, v2
	v_mov_b32_e32 v81, v2
	v_mov_b32_e32 v82, v2
	v_mov_b32_e32 v83, v2
	v_mov_b32_e32 v84, v2
	v_mov_b32_e32 v85, v2
	v_mov_b32_e32 v86, v2
	v_mov_b32_e32 v87, v2
	v_mov_b32_e32 v88, v2
	v_mov_b32_e32 v89, v2
	v_mov_b32_e32 v90, v2
	v_mov_b32_e32 v91, v2
	v_mov_b32_e32 v92, v2
	v_mov_b32_e32 v93, v2
	v_mov_b32_e32 v94, v2
	v_mov_b32_e32 v95, v2
	v_mov_b32_e32 v96, v2
	v_mov_b32_e32 v97, v2
	v_mov_b32_e32 v98, v2
	v_mov_b32_e32 v99, v2
	v_mov_b32_e32 v100, v2
	v_mov_b32_e32 v101, v2
	v_mov_b32_e32 v102, v2
	v_mov_b32_e32 v103, v2
	v_mov_b32_e32 v104, v2
	v_mov_b32_e32 v105, v2
	v_mov_b32_e32 v106, v2
	v_mov_b32_e32 v107, v2
	v_mov_b32_e32 v108, v2
	v_mov_b32_e32 v109, v2
	v_mov_b32_e32 v110, v2
	v_mov_b32_e32 v111, v2
	v_mov_b32_e32 v112, v2
	v_mov_b32_e32 v113, v2
	v_mov_b32_e32 v114, v2
	v_mov_b32_e32 v115, v2
	v_mov_b32_e32 v116, v2
	v_mov_b32_e32 v117, v2
	v_mov_b32_e32 v118, v2
	v_mov_b32_e32 v119, v2
	v_mov_b32_e32 v120, v2
	v_mov_b32_e32 v121, v2
	v_mov_b32_e32 v122, v2
	v_mov_b32_e32 v123, v2
	v_mov_b32_e32 v124, v2
	v_mov_b32_e32 v125, v2
	v_mov_b32_e32 v126, v2
	v_mov_b32_e32 v127, v2
	v_mov_b32_e32 v128, v2
	v_mov_b32_e32 v129, v2
	s_branch .LBB0_95
; #define G_LDA(dst, b, h)                                                                                                  \
;   _Pragma("unroll") for (int m = 0; m < 4; ++m) _Pragma("unroll") for (int k = 0; k < 2; ++k)                             \
;       dst[m][k] = *(const bf16x8*)((const char*)G_SA(b, h) + ((wr * 4 + m) * 2 + k) * 1024 + rdo)
; #define G_LDB(dst, b, h)                                                                                                  \
;   _Pragma("unroll") for (int n = 0; n < 2; ++n) _Pragma("unroll") for (int k = 0; k < 2; ++k)                             \
;       dst[n][k] = *(const bf16x8*)((const char*)G_SB(b, h) + ((wc * 2 + n) * 2 + k) * 1024 + rdo)
; #define G_WAIT_V(n) asm volatile("s_waitcnt vmcnt(" #n ")" ::: "memory")
; #define G_WAIT_L(n) asm volatile("s_waitcnt lgkmcnt(" #n ")" ::: "memory")
; #define G_BAR __builtin_amdgcn_s_barrier()
;     ...
;   {
;     G_LDB(B0, 0, 0); G_LDA(At, 0, 0); G_STAGE(G_SA(1, 1), A, oa0, oa1, LDA, 128, KA(nt - 1));
;     G_BAR; G_WAIT_L(0); G_MMA(0, 0, At, B0); G_BAR;
;     G_LDB(B1, 0, 1); G_BAR; G_WAIT_L(0); G_MMA(0, 1, At, B1); G_BAR;
;     G_LDA(At, 0, 1); G_WAIT_V(4); G_BAR; G_WAIT_L(0); G_MMA(1, 0, At, B0); G_MMA(1, 1, At, B1); G_BAR;
;   }
.LBB0_98:
	s_add_u32 s0, s10, 0x40780
	s_addc_u32 s1, s11, 0
	v_readfirstlane_b32 s10, v162
	v_lshl_add_u64 v[132:133], v[132:133], 1, s[0:1]
	s_mov_b32 m0, s10
	v_lshl_add_u64 v[130:131], v[130:131], 1, s[0:1]
	v_readfirstlane_b32 s0, v164
	ds_read_b128 v[134:137], v151
	ds_read_b128 v[138:141], v151 offset:1024
	ds_read_b128 v[152:155], v151 offset:2048
	ds_read_b128 v[148:151], v151 offset:3072
	ds_read_b128 v[156:159], v143
	ds_read_b128 v[182:185], v143 offset:1024
	ds_read_b128 v[186:189], v143 offset:2048
	ds_read_b128 v[190:193], v143 offset:3072
	ds_read_b128 v[194:197], v143 offset:4096
	ds_read_b128 v[198:201], v143 offset:5120
	ds_read_b128 v[202:205], v143 offset:6144
	ds_read_b128 v[206:209], v143 offset:7168
	global_load_lds_dwordx4 v[132:133], off
	s_mov_b32 m0, s0
	s_nop 0
	global_load_lds_dwordx4 v[130:131], off
	s_barrier
	s_waitcnt lgkmcnt(0)
	v_mfma_f32_16x16x32_bf16 v[126:129], v[156:159], v[134:137], v[126:129]
	v_mfma_f32_16x16x32_bf16 v[122:125], v[156:159], v[152:155], v[122:125]
	v_mfma_f32_16x16x32_bf16 v[118:121], v[186:189], v[134:137], v[118:121]
	v_mfma_f32_16x16x32_bf16 v[114:117], v[186:189], v[152:155], v[114:117]
	v_mfma_f32_16x16x32_bf16 v[110:113], v[194:197], v[134:137], v[110:113]
	v_mfma_f32_16x16x32_bf16 v[106:109], v[194:197], v[152:155], v[106:109]
	v_mfma_f32_16x16x32_bf16 v[102:105], v[202:205], v[134:137], v[102:105]
	v_mfma_f32_16x16x32_bf16 v[98:101], v[202:205], v[152:155], v[98:101]
	v_mfma_f32_16x16x32_bf16 v[126:129], v[182:185], v[138:141], v[126:129]
	v_mfma_f32_16x16x32_bf16 v[122:125], v[182:185], v[148:151], v[122:125]
	v_mfma_f32_16x16x32_bf16 v[118:121], v[190:193], v[138:141], v[118:121]
	v_mfma_f32_16x16x32_bf16 v[114:117], v[190:193], v[148:151], v[114:117]
	v_mfma_f32_16x16x32_bf16 v[110:113], v[198:201], v[138:141], v[110:113]
	v_mfma_f32_16x16x32_bf16 v[106:109], v[198:201], v[148:151], v[106:109]
	v_mfma_f32_16x16x32_bf16 v[102:105], v[206:209], v[138:141], v[102:105]
	v_mfma_f32_16x16x32_bf16 v[98:101], v[206:209], v[148:151], v[98:101]
	s_barrier
	ds_read_b128 v[130:133], v146
	ds_read_b128 v[164:167], v146 offset:1024
	ds_read_b128 v[210:213], v146 offset:2048
	ds_read_b128 v[214:217], v146 offset:3072
	s_barrier
	s_waitcnt lgkmcnt(0)
	v_mfma_f32_16x16x32_bf16 v[90:93], v[156:159], v[210:213], v[90:93]
	v_mfma_f32_16x16x32_bf16 v[86:89], v[186:189], v[130:133], v[86:89]
	v_mfma_f32_16x16x32_bf16 v[82:85], v[186:189], v[210:213], v[82:85]
	v_mfma_f32_16x16x32_bf16 v[78:81], v[194:197], v[130:133], v[78:81]
	v_mfma_f32_16x16x32_bf16 v[74:77], v[194:197], v[210:213], v[74:77]
	v_mfma_f32_16x16x32_bf16 v[70:73], v[202:205], v[130:133], v[70:73]
	v_mfma_f32_16x16x32_bf16 v[94:97], v[156:159], v[130:133], v[94:97]
	v_mfma_f32_16x16x32_bf16 v[90:93], v[182:185], v[214:217], v[90:93]
	v_mfma_f32_16x16x32_bf16 v[86:89], v[190:193], v[164:167], v[86:89]
	v_mfma_f32_16x16x32_bf16 v[82:85], v[190:193], v[214:217], v[82:85]
	v_mfma_f32_16x16x32_bf16 v[78:81], v[198:201], v[164:167], v[78:81]
	v_mfma_f32_16x16x32_bf16 v[74:77], v[198:201], v[214:217], v[74:77]
	v_mfma_f32_16x16x32_bf16 v[70:73], v[206:209], v[164:167], v[70:73]
	v_mfma_f32_16x16x32_bf16 v[66:69], v[202:205], v[210:213], v[66:69]
	v_mfma_f32_16x16x32_bf16 v[218:221], v[182:185], v[164:167], v[94:97]
	v_mfma_f32_16x16x32_bf16 v[156:159], v[206:209], v[214:217], v[66:69]
	s_barrier
	s_nop 3
	s_nop 0
	ds_read_b128 v[66:69], v143 offset:16384
	ds_read_b128 v[94:97], v143 offset:17408
	ds_read_b128 v[182:185], v143 offset:18432
	ds_read_b128 v[186:189], v143 offset:19456
	ds_read_b128 v[190:193], v143 offset:20480
	ds_read_b128 v[194:197], v143 offset:21504
	ds_read_b128 v[198:201], v143 offset:22528
	ds_read_b128 v[202:205], v143 offset:23552
	s_waitcnt vmcnt(4)
	s_barrier
	s_waitcnt lgkmcnt(0)
	v_mfma_f32_16x16x32_bf16 v[62:65], v[66:69], v[134:137], v[62:65]
	v_mfma_f32_16x16x32_bf16 v[54:57], v[182:185], v[134:137], v[54:57]
	v_mfma_f32_16x16x32_bf16 v[50:53], v[182:185], v[152:155], v[50:53]
	v_mfma_f32_16x16x32_bf16 v[46:49], v[190:193], v[134:137], v[46:49]
	v_mfma_f32_16x16x32_bf16 v[42:45], v[190:193], v[152:155], v[42:45]
	v_mfma_f32_16x16x32_bf16 v[38:41], v[198:201], v[134:137], v[38:41]
	v_mfma_f32_16x16x32_bf16 v[34:37], v[198:201], v[152:155], v[34:37]
	v_mfma_f32_16x16x32_bf16 v[62:65], v[94:97], v[138:141], v[62:65]
	v_mfma_f32_16x16x32_bf16 v[58:61], v[66:69], v[152:155], v[58:61]
	v_mfma_f32_16x16x32_bf16 v[54:57], v[186:189], v[138:141], v[54:57]
	v_mfma_f32_16x16x32_bf16 v[50:53], v[186:189], v[148:151], v[50:53]
	v_mfma_f32_16x16x32_bf16 v[46:49], v[194:197], v[138:141], v[46:49]
	v_mfma_f32_16x16x32_bf16 v[42:45], v[194:197], v[148:151], v[42:45]
	v_mfma_f32_16x16x32_bf16 v[38:41], v[202:205], v[138:141], v[38:41]
	v_mfma_f32_16x16x32_bf16 v[34:37], v[202:205], v[148:151], v[34:37]
	v_mfma_f32_16x16x32_bf16 v[206:209], v[94:97], v[148:151], v[58:61]
	v_mfma_f32_16x16x32_bf16 v[30:33], v[66:69], v[130:133], v[30:33]
	v_mfma_f32_16x16x32_bf16 v[26:29], v[66:69], v[210:213], v[26:29]
	v_mfma_f32_16x16x32_bf16 v[22:25], v[182:185], v[130:133], v[22:25]
	v_mfma_f32_16x16x32_bf16 v[18:21], v[182:185], v[210:213], v[18:21]
	v_mfma_f32_16x16x32_bf16 v[14:17], v[190:193], v[130:133], v[14:17]
	v_mfma_f32_16x16x32_bf16 v[10:13], v[190:193], v[210:213], v[10:13]
	v_mfma_f32_16x16x32_bf16 v[6:9], v[198:201], v[130:133], v[6:9]
	v_mfma_f32_16x16x32_bf16 v[2:5], v[198:201], v[210:213], v[2:5]
	v_mfma_f32_16x16x32_bf16 v[30:33], v[94:97], v[164:167], v[30:33]
	v_mfma_f32_16x16x32_bf16 v[26:29], v[94:97], v[214:217], v[26:29]
	v_mfma_f32_16x16x32_bf16 v[22:25], v[186:189], v[164:167], v[22:25]
	v_mfma_f32_16x16x32_bf16 v[18:21], v[186:189], v[214:217], v[18:21]
	v_mfma_f32_16x16x32_bf16 v[14:17], v[194:197], v[164:167], v[14:17]
	v_mfma_f32_16x16x32_bf16 v[10:13], v[194:197], v[214:217], v[10:13]
	v_mfma_f32_16x16x32_bf16 v[6:9], v[202:205], v[164:167], v[6:9]
	v_mfma_f32_16x16x32_bf16 v[2:5], v[202:205], v[214:217], v[2:5]
	s_barrier
; #define G_LDA(dst, b, h)                                                                                                  \
;   _Pragma("unroll") for (int m = 0; m < 4; ++m) _Pragma("unroll") for (int k = 0; k < 2; ++k)                             \
;       dst[m][k] = *(const bf16x8*)((const char*)G_SA(b, h) + ((wr * 4 + m) * 2 + k) * 1024 + rdo)
; #define G_LDB(dst, b, h)                                                                                                  \
;   _Pragma("unroll") for (int n = 0; n < 2; ++n) _Pragma("unroll") for (int k = 0; k < 2; ++k)                             \
;       dst[n][k] = *(const bf16x8*)((const char*)G_SB(b, h) + ((wc * 2 + n) * 2 + k) * 1024 + rdo)
; #define G_WAIT_V(n) asm volatile("s_waitcnt vmcnt(" #n ")" ::: "memory")
; #define G_WAIT_L(n) asm volatile("s_waitcnt lgkmcnt(" #n ")" ::: "memory")
; #define G_BAR __builtin_amdgcn_s_barrier()
;     ...
;   {
;     G_LDB(B0, 1, 0); G_LDA(At, 1, 0); G_WAIT_V(2); G_BAR; G_WAIT_L(0); G_MMA(0, 0, At, B0); G_BAR;
;     G_LDB(B1, 1, 1); G_WAIT_V(0); G_BAR; G_WAIT_L(0); G_MMA(0, 1, At, B1); G_BAR;
;     G_LDA(At, 1, 1); G_BAR; G_WAIT_L(0); G_MMA(1, 0, At, B0); G_MMA(1, 1, At, B1); G_BAR;
;   }
;   if (wr == 0) G_BAR;
	ds_read_b128 v[130:133], v145
	ds_read_b128 v[134:137], v145 offset:1024
	ds_read_b128 v[138:141], v145 offset:2048
	ds_read_b128 v[146:149], v145 offset:3072
	ds_read_b128 v[58:61], v143 offset:32768
	ds_read_b128 v[66:69], v143 offset:33792
	ds_read_b128 v[150:153], v143 offset:34816
	ds_read_b128 v[164:167], v143 offset:35840
	ds_read_b128 v[182:185], v143 offset:36864
	ds_read_b128 v[186:189], v143 offset:37888
	ds_read_b128 v[190:193], v143 offset:38912
	ds_read_b128 v[194:197], v143 offset:39936
	s_waitcnt vmcnt(2)
	s_barrier
	s_waitcnt lgkmcnt(0)
	v_mfma_f32_16x16x32_bf16 v[94:97], v[58:61], v[130:133], v[126:129]
	v_mfma_f32_16x16x32_bf16 v[126:129], v[66:69], v[134:137], v[94:97]
	v_mfma_f32_16x16x32_bf16 v[94:97], v[58:61], v[138:141], v[122:125]
	v_mfma_f32_16x16x32_bf16 v[122:125], v[66:69], v[146:149], v[94:97]
	v_mfma_f32_16x16x32_bf16 v[94:97], v[150:153], v[130:133], v[118:121]
	v_mfma_f32_16x16x32_bf16 v[118:121], v[164:167], v[134:137], v[94:97]
	v_mfma_f32_16x16x32_bf16 v[94:97], v[150:153], v[138:141], v[114:117]
	v_mfma_f32_16x16x32_bf16 v[114:117], v[164:167], v[146:149], v[94:97]
	v_mfma_f32_16x16x32_bf16 v[94:97], v[182:185], v[130:133], v[110:113]
	v_mfma_f32_16x16x32_bf16 v[110:113], v[186:189], v[134:137], v[94:97]
	v_mfma_f32_16x16x32_bf16 v[94:97], v[182:185], v[138:141], v[106:109]
	v_mfma_f32_16x16x32_bf16 v[106:109], v[186:189], v[146:149], v[94:97]
	v_mfma_f32_16x16x32_bf16 v[94:97], v[190:193], v[130:133], v[102:105]
	v_mfma_f32_16x16x32_bf16 v[102:105], v[194:197], v[134:137], v[94:97]
	v_mfma_f32_16x16x32_bf16 v[94:97], v[190:193], v[138:141], v[98:101]
	v_mfma_f32_16x16x32_bf16 v[94:97], v[194:197], v[146:149], v[94:97]
	s_barrier
	ds_read_b128 v[198:201], v144
	ds_read_b128 v[202:205], v144 offset:1024
	ds_read_b128 v[210:213], v144 offset:2048
	ds_read_b128 v[214:217], v144 offset:3072
	s_waitcnt vmcnt(0)
	s_barrier
	s_waitcnt lgkmcnt(0)
	v_mfma_f32_16x16x32_bf16 v[98:101], v[58:61], v[198:201], v[218:221]
	v_mfma_f32_16x16x32_bf16 v[58:61], v[58:61], v[210:213], v[90:93]
	v_mfma_f32_16x16x32_bf16 v[90:93], v[66:69], v[214:217], v[58:61]
	v_mfma_f32_16x16x32_bf16 v[58:61], v[150:153], v[198:201], v[86:89]
	v_mfma_f32_16x16x32_bf16 v[86:89], v[164:167], v[202:205], v[58:61]
	v_mfma_f32_16x16x32_bf16 v[58:61], v[150:153], v[210:213], v[82:85]
	v_mfma_f32_16x16x32_bf16 v[82:85], v[164:167], v[214:217], v[58:61]
	v_mfma_f32_16x16x32_bf16 v[58:61], v[182:185], v[198:201], v[78:81]
	v_mfma_f32_16x16x32_bf16 v[78:81], v[186:189], v[202:205], v[58:61]
	v_mfma_f32_16x16x32_bf16 v[58:61], v[182:185], v[210:213], v[74:77]
	v_mfma_f32_16x16x32_bf16 v[74:77], v[186:189], v[214:217], v[58:61]
	v_mfma_f32_16x16x32_bf16 v[58:61], v[190:193], v[198:201], v[70:73]
	v_mfma_f32_16x16x32_bf16 v[98:101], v[66:69], v[202:205], v[98:101]
	v_mfma_f32_16x16x32_bf16 v[66:69], v[194:197], v[202:205], v[58:61]
	v_mfma_f32_16x16x32_bf16 v[58:61], v[190:193], v[210:213], v[156:159]
	v_mfma_f32_16x16x32_bf16 v[58:61], v[194:197], v[214:217], v[58:61]
	s_barrier
	ds_read_b128 v[150:153], v143 offset:49152
	ds_read_b128 v[154:157], v143 offset:50176
	ds_read_b128 v[158:161], v143 offset:51200
	ds_read_b128 v[164:167], v143 offset:52224
	ds_read_b128 v[182:185], v143 offset:53248
	ds_read_b128 v[186:189], v143 offset:54272
	ds_read_b128 v[190:193], v143 offset:55296
	ds_read_b128 v[194:197], v143 offset:56320
	s_barrier
	s_waitcnt lgkmcnt(0)
	v_mfma_f32_16x16x32_bf16 v[62:65], v[150:153], v[130:133], v[62:65]
	v_mfma_f32_16x16x32_bf16 v[70:73], v[154:157], v[134:137], v[62:65]
	v_mfma_f32_16x16x32_bf16 v[62:65], v[150:153], v[138:141], v[206:209]
	v_mfma_f32_16x16x32_bf16 v[54:57], v[158:161], v[130:133], v[54:57]
	v_mfma_f32_16x16x32_bf16 v[50:53], v[158:161], v[138:141], v[50:53]
	v_mfma_f32_16x16x32_bf16 v[46:49], v[182:185], v[130:133], v[46:49]
	v_mfma_f32_16x16x32_bf16 v[42:45], v[182:185], v[138:141], v[42:45]
	v_mfma_f32_16x16x32_bf16 v[38:41], v[190:193], v[130:133], v[38:41]
	v_mfma_f32_16x16x32_bf16 v[34:37], v[190:193], v[138:141], v[34:37]
	v_mfma_f32_16x16x32_bf16 v[62:65], v[154:157], v[146:149], v[62:65]
	v_mfma_f32_16x16x32_bf16 v[54:57], v[164:167], v[134:137], v[54:57]
	v_mfma_f32_16x16x32_bf16 v[50:53], v[164:167], v[146:149], v[50:53]
	v_mfma_f32_16x16x32_bf16 v[46:49], v[186:189], v[134:137], v[46:49]
	v_mfma_f32_16x16x32_bf16 v[42:45], v[186:189], v[146:149], v[42:45]
	v_mfma_f32_16x16x32_bf16 v[38:41], v[194:197], v[134:137], v[38:41]
	v_mfma_f32_16x16x32_bf16 v[34:37], v[194:197], v[146:149], v[34:37]
	v_mfma_f32_16x16x32_bf16 v[30:33], v[150:153], v[198:201], v[30:33]
	v_mfma_f32_16x16x32_bf16 v[26:29], v[150:153], v[210:213], v[26:29]
	v_mfma_f32_16x16x32_bf16 v[22:25], v[158:161], v[198:201], v[22:25]
	v_mfma_f32_16x16x32_bf16 v[18:21], v[158:161], v[210:213], v[18:21]
	v_mfma_f32_16x16x32_bf16 v[14:17], v[182:185], v[198:201], v[14:17]
	v_mfma_f32_16x16x32_bf16 v[10:13], v[182:185], v[210:213], v[10:13]
	v_mfma_f32_16x16x32_bf16 v[6:9], v[190:193], v[198:201], v[6:9]
	v_mfma_f32_16x16x32_bf16 v[2:5], v[190:193], v[210:213], v[2:5]
	v_mfma_f32_16x16x32_bf16 v[30:33], v[154:157], v[202:205], v[30:33]
	v_mfma_f32_16x16x32_bf16 v[26:29], v[154:157], v[214:217], v[26:29]
	v_mfma_f32_16x16x32_bf16 v[22:25], v[164:167], v[202:205], v[22:25]
	v_mfma_f32_16x16x32_bf16 v[18:21], v[164:167], v[214:217], v[18:21]
	v_mfma_f32_16x16x32_bf16 v[14:17], v[186:189], v[202:205], v[14:17]
	v_mfma_f32_16x16x32_bf16 v[10:13], v[186:189], v[214:217], v[10:13]
	v_mfma_f32_16x16x32_bf16 v[6:9], v[194:197], v[202:205], v[6:9]
	v_mfma_f32_16x16x32_bf16 v[2:5], v[194:197], v[214:217], v[2:5]
	v_cmp_gt_u32_e32 vcc, s67, v142
	s_barrier
	s_and_saveexec_b64 s[10:11], vcc
	s_cbranch_execz .LBB0_100
	s_barrier

; #define G_LDA(dst, b, h)                                                                                                  \
;   _Pragma("unroll") for (int m = 0; m < 4; ++m) _Pragma("unroll") for (int k = 0; k < 2; ++k)                             \
;       dst[m][k] = *(const bf16x8*)((const char*)G_SA(b, h) + ((wr * 4 + m) * 2 + k) * 1024 + rdo)
; #define G_LDB(dst, b, h)                                                                                                  \
;   _Pragma("unroll") for (int n = 0; n < 2; ++n) _Pragma("unroll") for (int k = 0; k < 2; ++k)                             \
;       dst[n][k] = *(const bf16x8*)((const char*)G_SB(b, h) + ((wc * 2 + n) * 2 + k) * 1024 + rdo)
; #define G_WAIT_L(n) asm volatile("s_waitcnt lgkmcnt(" #n ")" ::: "memory")
; #define G_BAR __builtin_amdgcn_s_barrier()
; #define G_SCHED __builtin_amdgcn_sched_barrier(0)
;     ...
;   for (int tt = 0; tt < nt - 2; tt += 2) {
;     G_LDB(B0, 0, 0); G_SCHED; G_LDA(At, 0, 0); G_STAGE(G_SA(1, 1), A, oa0, oa1, LDA, 128, KA(tt + 1));
;     G_WAIT_L(8); G_BAR; G_WAIT_L(0); G_MMA(0, 0, At, B0); G_BAR; G_SCHED;
;     G_LDB(B1, 0, 1); G_STAGE(G_SB(0, 0), B, ob0, ob1, LDB, 0, KB(tt + 2));
;     G_BAR; G_WAIT_L(0); G_MMA(0, 1, At, B1); G_BAR;
;     G_LDA(At, 0, 1); G_STAGE(G_SA(0, 0), A, oa0, oa1, LDA, 0, KA(tt + 2));
;     G_BAR; G_WAIT_L(0); G_MMA(1, 0, At, B0); G_BAR; G_SCHED;
.LBB0_105:
	ds_read_b128 v[164:167], v160
	ds_read_b128 v[182:185], v160 offset:1024
	ds_read_b128 v[186:189], v160 offset:2048
	ds_read_b128 v[190:193], v160 offset:3072
	v_add_u32_e32 v161, 0xc000, v143
	v_lshl_add_u64 v[242:243], v[136:137], 0, s[8:9]
	v_readfirstlane_b32 s0, v161
	v_add_u32_e32 v162, 0xe000, v143
	v_lshl_add_u64 v[226:227], v[242:243], 0, s[78:79]
	s_mov_b32 m0, s0
	v_lshl_add_u64 v[244:245], v[134:135], 0, s[8:9]
	v_readfirstlane_b32 s0, v162
	ds_read_b128 v[194:197], v142
	ds_read_b128 v[198:201], v142 offset:1024
	ds_read_b128 v[202:205], v142 offset:2048
	ds_read_b128 v[206:209], v142 offset:3072
	ds_read_b128 v[210:213], v142 offset:4096
	ds_read_b128 v[214:217], v142 offset:5120
	ds_read_b128 v[218:221], v142 offset:6144
	ds_read_b128 v[222:225], v142 offset:7168
	global_load_lds_dwordx4 v[226:227], off
	v_lshl_add_u64 v[226:227], v[244:245], 0, s[78:79]
	s_mov_b32 m0, s0
	s_nop 0
	global_load_lds_dwordx4 v[226:227], off
	s_waitcnt lgkmcnt(8)
	s_barrier
	s_waitcnt lgkmcnt(0)
	v_mfma_f32_16x16x32_bf16 v[126:129], v[194:197], v[164:167], v[126:129]
	v_mfma_f32_16x16x32_bf16 v[122:125], v[194:197], v[186:189], v[122:125]
	v_mfma_f32_16x16x32_bf16 v[118:121], v[202:205], v[164:167], v[118:121]
	v_mfma_f32_16x16x32_bf16 v[114:117], v[202:205], v[186:189], v[114:117]
	v_mfma_f32_16x16x32_bf16 v[110:113], v[210:213], v[164:167], v[110:113]
	v_mfma_f32_16x16x32_bf16 v[106:109], v[210:213], v[186:189], v[106:109]
	v_mfma_f32_16x16x32_bf16 v[102:105], v[218:221], v[164:167], v[102:105]
	v_mfma_f32_16x16x32_bf16 v[98:101], v[218:221], v[186:189], v[98:101]
	v_mfma_f32_16x16x32_bf16 v[126:129], v[198:201], v[182:185], v[126:129]
	v_mfma_f32_16x16x32_bf16 v[122:125], v[198:201], v[190:193], v[122:125]
	v_mfma_f32_16x16x32_bf16 v[118:121], v[206:209], v[182:185], v[118:121]
	v_mfma_f32_16x16x32_bf16 v[114:117], v[206:209], v[190:193], v[114:117]
	v_mfma_f32_16x16x32_bf16 v[110:113], v[214:217], v[182:185], v[110:113]
	v_mfma_f32_16x16x32_bf16 v[106:109], v[214:217], v[190:193], v[106:109]
	v_mfma_f32_16x16x32_bf16 v[102:105], v[222:225], v[182:185], v[102:105]
	v_mfma_f32_16x16x32_bf16 v[98:101], v[222:225], v[190:193], v[98:101]
	s_barrier
	v_lshl_add_u64 v[246:247], v[140:141], 0, s[8:9]
	v_readfirstlane_b32 s0, v146
	v_lshl_add_u64 v[248:249], v[246:247], 0, s[50:51]
	s_mov_b32 m0, s0
	ds_read_b128 v[226:229], v158
	ds_read_b128 v[230:233], v158 offset:1024
	ds_read_b128 v[234:237], v158 offset:2048
	ds_read_b128 v[238:241], v158 offset:3072
	global_load_lds_dwordx4 v[248:249], off
	v_lshl_add_u64 v[248:249], v[138:139], 0, s[8:9]
	v_readfirstlane_b32 s0, v147
	v_lshl_add_u64 v[250:251], v[248:249], 0, s[50:51]
	s_mov_b32 m0, s0
	s_nop 0
	global_load_lds_dwordx4 v[250:251], off
	s_barrier
	s_waitcnt lgkmcnt(0)
	v_mfma_f32_16x16x32_bf16 v[94:97], v[194:197], v[226:229], v[94:97]
	v_mfma_f32_16x16x32_bf16 v[90:93], v[194:197], v[234:237], v[90:93]
	v_mfma_f32_16x16x32_bf16 v[86:89], v[202:205], v[226:229], v[86:89]
	v_mfma_f32_16x16x32_bf16 v[82:85], v[202:205], v[234:237], v[82:85]
	v_mfma_f32_16x16x32_bf16 v[78:81], v[210:213], v[226:229], v[78:81]
	v_mfma_f32_16x16x32_bf16 v[74:77], v[210:213], v[234:237], v[74:77]
	v_mfma_f32_16x16x32_bf16 v[70:73], v[218:221], v[226:229], v[70:73]
	v_mfma_f32_16x16x32_bf16 v[66:69], v[218:221], v[234:237], v[66:69]
	v_mfma_f32_16x16x32_bf16 v[94:97], v[198:201], v[230:233], v[94:97]
	v_mfma_f32_16x16x32_bf16 v[90:93], v[198:201], v[238:241], v[90:93]
	v_mfma_f32_16x16x32_bf16 v[86:89], v[206:209], v[230:233], v[86:89]
	v_mfma_f32_16x16x32_bf16 v[82:85], v[206:209], v[238:241], v[82:85]
	v_mfma_f32_16x16x32_bf16 v[78:81], v[214:217], v[230:233], v[78:81]
	v_mfma_f32_16x16x32_bf16 v[74:77], v[214:217], v[238:241], v[74:77]
	v_mfma_f32_16x16x32_bf16 v[70:73], v[222:225], v[230:233], v[70:73]
	v_mfma_f32_16x16x32_bf16 v[66:69], v[222:225], v[238:241], v[66:69]
	v_readfirstlane_b32 s0, v143
	v_lshl_add_u64 v[250:251], v[242:243], 0, s[82:83]
	s_mov_b32 m0, s0
	v_readfirstlane_b32 s0, v144
	s_barrier
	ds_read_b128 v[194:197], v142 offset:16384
	ds_read_b128 v[198:201], v142 offset:17408
	ds_read_b128 v[202:205], v142 offset:18432
	ds_read_b128 v[206:209], v142 offset:19456
	ds_read_b128 v[210:213], v142 offset:20480
	ds_read_b128 v[214:217], v142 offset:21504
	ds_read_b128 v[218:221], v142 offset:22528
	ds_read_b128 v[222:225], v142 offset:23552
	global_load_lds_dwordx4 v[250:251], off
	v_lshl_add_u64 v[250:251], v[244:245], 0, s[82:83]
	s_mov_b32 m0, s0
	s_nop 0
	global_load_lds_dwordx4 v[250:251], off
	s_barrier
	s_waitcnt lgkmcnt(0)
	v_mfma_f32_16x16x32_bf16 v[62:65], v[194:197], v[164:167], v[62:65]
	v_mfma_f32_16x16x32_bf16 v[58:61], v[194:197], v[186:189], v[58:61]
	v_mfma_f32_16x16x32_bf16 v[54:57], v[202:205], v[164:167], v[54:57]
	v_mfma_f32_16x16x32_bf16 v[50:53], v[202:205], v[186:189], v[50:53]
	v_mfma_f32_16x16x32_bf16 v[46:49], v[210:213], v[164:167], v[46:49]
	v_mfma_f32_16x16x32_bf16 v[42:45], v[210:213], v[186:189], v[42:45]
	v_mfma_f32_16x16x32_bf16 v[38:41], v[218:221], v[164:167], v[38:41]
	v_mfma_f32_16x16x32_bf16 v[34:37], v[218:221], v[186:189], v[34:37]
	v_mfma_f32_16x16x32_bf16 v[62:65], v[198:201], v[182:185], v[62:65]
	v_mfma_f32_16x16x32_bf16 v[58:61], v[198:201], v[190:193], v[58:61]
	v_mfma_f32_16x16x32_bf16 v[54:57], v[206:209], v[182:185], v[54:57]
	v_mfma_f32_16x16x32_bf16 v[50:53], v[206:209], v[190:193], v[50:53]
	v_mfma_f32_16x16x32_bf16 v[46:49], v[214:217], v[182:185], v[46:49]
	v_mfma_f32_16x16x32_bf16 v[42:45], v[214:217], v[190:193], v[42:45]
	v_mfma_f32_16x16x32_bf16 v[38:41], v[222:225], v[182:185], v[38:41]
	v_mfma_f32_16x16x32_bf16 v[34:37], v[222:225], v[190:193], v[34:37]
	s_barrier
; #define G_LDA(dst, b, h)                                                                                                  \
;   _Pragma("unroll") for (int m = 0; m < 4; ++m) _Pragma("unroll") for (int k = 0; k < 2; ++k)                             \
;       dst[m][k] = *(const bf16x8*)((const char*)G_SA(b, h) + ((wr * 4 + m) * 2 + k) * 1024 + rdo)
; #define G_LDB(dst, b, h)                                                                                                  \
;   _Pragma("unroll") for (int n = 0; n < 2; ++n) _Pragma("unroll") for (int k = 0; k < 2; ++k)                             \
;       dst[n][k] = *(const bf16x8*)((const char*)G_SB(b, h) + ((wc * 2 + n) * 2 + k) * 1024 + rdo)
; #define G_WAIT_V(n) asm volatile("s_waitcnt vmcnt(" #n ")" ::: "memory")
; #define G_WAIT_L(n) asm volatile("s_waitcnt lgkmcnt(" #n ")" ::: "memory")
; #define G_BAR __builtin_amdgcn_s_barrier()
; #define G_SCHED __builtin_amdgcn_sched_barrier(0)
;     ...
;     G_STAGE(G_SB(0, 1), B, ob0, ob1, LDB, 128, KB(tt + 2));
;     G_WAIT_V(6); G_BAR; G_MMA(1, 1, At, B1); G_BAR;
;     G_LDB(B0, 1, 0); G_SCHED; G_LDA(At, 1, 0); G_STAGE(G_SA(0, 1), A, oa0, oa1, LDA, 128, KA(tt + 2));
;     G_WAIT_L(8); G_BAR; G_WAIT_L(0); G_MMA(0, 0, At, B0); G_BAR; G_SCHED;
;     G_LDB(B1, 1, 1); G_STAGE(G_SB(1, 0), B, ob0, ob1, LDB, 0, KB(tt + 3));
;     G_BAR; G_WAIT_L(0); G_MMA(0, 1, At, B1); G_BAR;
;     G_LDA(At, 1, 1); G_STAGE(G_SA(1, 0), A, oa0, oa1, LDA, 0, KA(tt + 3));
	v_readfirstlane_b32 s0, v149
	v_lshl_add_u64 v[164:165], v[246:247], 0, s[38:39]
	s_mov_b32 m0, s0
	v_readfirstlane_b32 s0, v150
	global_load_lds_dwordx4 v[164:165], off
	v_lshl_add_u64 v[164:165], v[248:249], 0, s[38:39]
	s_mov_b32 m0, s0
	s_nop 0
	global_load_lds_dwordx4 v[164:165], off
	s_waitcnt vmcnt(6)
	s_barrier
	v_mfma_f32_16x16x32_bf16 v[30:33], v[194:197], v[226:229], v[30:33]
	v_mfma_f32_16x16x32_bf16 v[26:29], v[194:197], v[234:237], v[26:29]
	v_mfma_f32_16x16x32_bf16 v[22:25], v[202:205], v[226:229], v[22:25]
	v_mfma_f32_16x16x32_bf16 v[18:21], v[202:205], v[234:237], v[18:21]
	v_mfma_f32_16x16x32_bf16 v[14:17], v[210:213], v[226:229], v[14:17]
	v_mfma_f32_16x16x32_bf16 v[10:13], v[210:213], v[234:237], v[10:13]
	v_mfma_f32_16x16x32_bf16 v[6:9], v[218:221], v[226:229], v[6:9]
	v_mfma_f32_16x16x32_bf16 v[2:5], v[218:221], v[234:237], v[2:5]
	v_mfma_f32_16x16x32_bf16 v[30:33], v[198:201], v[230:233], v[30:33]
	v_mfma_f32_16x16x32_bf16 v[26:29], v[198:201], v[238:241], v[26:29]
	v_mfma_f32_16x16x32_bf16 v[22:25], v[206:209], v[230:233], v[22:25]
	v_mfma_f32_16x16x32_bf16 v[18:21], v[206:209], v[238:241], v[18:21]
	v_mfma_f32_16x16x32_bf16 v[14:17], v[214:217], v[230:233], v[14:17]
	v_mfma_f32_16x16x32_bf16 v[10:13], v[214:217], v[238:241], v[10:13]
	v_mfma_f32_16x16x32_bf16 v[6:9], v[222:225], v[230:233], v[6:9]
	v_mfma_f32_16x16x32_bf16 v[2:5], v[222:225], v[238:241], v[2:5]
	s_barrier
	ds_read_b128 v[164:167], v148
	ds_read_b128 v[182:185], v148 offset:1024
	ds_read_b128 v[186:189], v148 offset:2048
	ds_read_b128 v[190:193], v148 offset:3072
	v_readfirstlane_b32 s0, v151
	v_lshl_add_u64 v[226:227], v[242:243], 0, s[86:87]
	s_mov_b32 m0, s0
	v_readfirstlane_b32 s0, v152
	ds_read_b128 v[194:197], v142 offset:32768
	ds_read_b128 v[198:201], v142 offset:33792
	ds_read_b128 v[202:205], v142 offset:34816
	ds_read_b128 v[206:209], v142 offset:35840
	ds_read_b128 v[210:213], v142 offset:36864
	ds_read_b128 v[214:217], v142 offset:37888
	ds_read_b128 v[218:221], v142 offset:38912
	ds_read_b128 v[222:225], v142 offset:39936
	global_load_lds_dwordx4 v[226:227], off
	v_lshl_add_u64 v[226:227], v[244:245], 0, s[86:87]
	s_mov_b32 m0, s0
	s_nop 0
	global_load_lds_dwordx4 v[226:227], off
	s_waitcnt lgkmcnt(8)
	s_barrier
	s_waitcnt lgkmcnt(0)
	v_mfma_f32_16x16x32_bf16 v[126:129], v[194:197], v[164:167], v[126:129]
	v_mfma_f32_16x16x32_bf16 v[122:125], v[194:197], v[186:189], v[122:125]
	v_mfma_f32_16x16x32_bf16 v[118:121], v[202:205], v[164:167], v[118:121]
	v_mfma_f32_16x16x32_bf16 v[114:117], v[202:205], v[186:189], v[114:117]
	v_mfma_f32_16x16x32_bf16 v[110:113], v[210:213], v[164:167], v[110:113]
	v_mfma_f32_16x16x32_bf16 v[106:109], v[210:213], v[186:189], v[106:109]
	v_mfma_f32_16x16x32_bf16 v[102:105], v[218:221], v[164:167], v[102:105]
	v_mfma_f32_16x16x32_bf16 v[98:101], v[218:221], v[186:189], v[98:101]
	v_mfma_f32_16x16x32_bf16 v[126:129], v[198:201], v[182:185], v[126:129]
	v_mfma_f32_16x16x32_bf16 v[122:125], v[198:201], v[190:193], v[122:125]
	v_mfma_f32_16x16x32_bf16 v[118:121], v[206:209], v[182:185], v[118:121]
	v_mfma_f32_16x16x32_bf16 v[114:117], v[206:209], v[190:193], v[114:117]
	v_mfma_f32_16x16x32_bf16 v[110:113], v[214:217], v[182:185], v[110:113]
	v_mfma_f32_16x16x32_bf16 v[106:109], v[214:217], v[190:193], v[106:109]
	v_mfma_f32_16x16x32_bf16 v[102:105], v[222:225], v[182:185], v[102:105]
	v_mfma_f32_16x16x32_bf16 v[98:101], v[222:225], v[190:193], v[98:101]
	s_barrier
	v_readfirstlane_b32 s0, v153
	v_lshl_add_u64 v[250:251], v[246:247], 0, s[4:5]
	s_mov_b32 m0, s0
	v_readfirstlane_b32 s0, v154
	ds_read_b128 v[226:229], v145
	ds_read_b128 v[230:233], v145 offset:1024
	ds_read_b128 v[234:237], v145 offset:2048
	ds_read_b128 v[238:241], v145 offset:3072
	global_load_lds_dwordx4 v[250:251], off
	v_lshl_add_u64 v[250:251], v[248:249], 0, s[4:5]
	s_mov_b32 m0, s0
	s_nop 0
	global_load_lds_dwordx4 v[250:251], off
	s_barrier
	s_waitcnt lgkmcnt(0)
	v_mfma_f32_16x16x32_bf16 v[94:97], v[194:197], v[226:229], v[94:97]
	v_mfma_f32_16x16x32_bf16 v[90:93], v[194:197], v[234:237], v[90:93]
	v_mfma_f32_16x16x32_bf16 v[86:89], v[202:205], v[226:229], v[86:89]
	v_mfma_f32_16x16x32_bf16 v[82:85], v[202:205], v[234:237], v[82:85]
	v_mfma_f32_16x16x32_bf16 v[78:81], v[210:213], v[226:229], v[78:81]
	v_mfma_f32_16x16x32_bf16 v[74:77], v[210:213], v[234:237], v[74:77]
	v_mfma_f32_16x16x32_bf16 v[70:73], v[218:221], v[226:229], v[70:73]
	v_mfma_f32_16x16x32_bf16 v[66:69], v[218:221], v[234:237], v[66:69]
	v_mfma_f32_16x16x32_bf16 v[94:97], v[198:201], v[230:233], v[94:97]
	v_mfma_f32_16x16x32_bf16 v[90:93], v[198:201], v[238:241], v[90:93]
	v_mfma_f32_16x16x32_bf16 v[86:89], v[206:209], v[230:233], v[86:89]
	v_mfma_f32_16x16x32_bf16 v[82:85], v[206:209], v[238:241], v[82:85]
	v_mfma_f32_16x16x32_bf16 v[78:81], v[214:217], v[230:233], v[78:81]
	v_mfma_f32_16x16x32_bf16 v[74:77], v[214:217], v[238:241], v[74:77]
	v_mfma_f32_16x16x32_bf16 v[70:73], v[222:225], v[230:233], v[70:73]
	v_mfma_f32_16x16x32_bf16 v[66:69], v[222:225], v[238:241], v[66:69]
	v_readfirstlane_b32 s0, v155
	v_lshl_add_u64 v[242:243], v[242:243], 0, s[90:91]
	s_mov_b32 m0, s0
	v_readfirstlane_b32 s0, v156
	s_barrier
	ds_read_b128 v[194:197], v142 offset:49152
	ds_read_b128 v[198:201], v142 offset:50176
	ds_read_b128 v[202:205], v142 offset:51200
	ds_read_b128 v[206:209], v142 offset:52224
	ds_read_b128 v[210:213], v142 offset:53248
	ds_read_b128 v[214:217], v142 offset:54272
	ds_read_b128 v[218:221], v142 offset:55296
	ds_read_b128 v[222:225], v142 offset:56320
	global_load_lds_dwordx4 v[242:243], off
	v_lshl_add_u64 v[242:243], v[244:245], 0, s[90:91]
	s_mov_b32 m0, s0
	s_nop 0
	global_load_lds_dwordx4 v[242:243], off
	s_barrier
; #define G_LDA(dst, b, h)                                                                                                  \
;   _Pragma("unroll") for (int m = 0; m < 4; ++m) _Pragma("unroll") for (int k = 0; k < 2; ++k)                             \
;       dst[m][k] = *(const bf16x8*)((const char*)G_SA(b, h) + ((wr * 4 + m) * 2 + k) * 1024 + rdo)
; #define G_LDB(dst, b, h)                                                                                                  \
;   _Pragma("unroll") for (int n = 0; n < 2; ++n) _Pragma("unroll") for (int k = 0; k < 2; ++k)                             \
;       dst[n][k] = *(const bf16x8*)((const char*)G_SB(b, h) + ((wc * 2 + n) * 2 + k) * 1024 + rdo)
; #define G_WAIT_V(n) asm volatile("s_waitcnt vmcnt(" #n ")" ::: "memory")
; #define G_WAIT_L(n) asm volatile("s_waitcnt lgkmcnt(" #n ")" ::: "memory")
; #define G_BAR __builtin_amdgcn_s_barrier()
; #define G_SCHED __builtin_amdgcn_sched_barrier(0)
; DI void br_flush(PREF p, f32x4 (&acc)[2][2][4][2], int slot) { br_store(p, acc, slot); zero_acc256(acc); }
;     ...
;     G_LDA(At, 1, 1); G_STAGE(G_SA(1, 0), A, oa0, oa1, LDA, 0, KA(tt + 3));
;     G_BAR; G_WAIT_L(0); G_MMA(1, 0, At, B0); G_BAR; G_SCHED;
;     G_STAGE(G_SB(1, 1), B, ob0, ob1, LDB, 128, KB(tt + 3));
;     G_WAIT_V(6); G_BAR; G_MMA(1, 1, At, B1); G_BAR;
;     if (MODE && ((tt + 1) & 3) == 3) br_flush(p, acc, (tt + 1) >> 2);
;   }
;   {
;     G_LDB(B0, 0, 0); G_LDA(At, 0, 0); G_STAGE(G_SA(1, 1), A, oa0, oa1, LDA, 128, KA(nt - 1));
	s_waitcnt lgkmcnt(0)
	v_mfma_f32_16x16x32_bf16 v[62:65], v[194:197], v[164:167], v[62:65]
	v_mfma_f32_16x16x32_bf16 v[58:61], v[194:197], v[186:189], v[58:61]
	v_mfma_f32_16x16x32_bf16 v[54:57], v[202:205], v[164:167], v[54:57]
	v_mfma_f32_16x16x32_bf16 v[50:53], v[202:205], v[186:189], v[50:53]
	v_mfma_f32_16x16x32_bf16 v[46:49], v[210:213], v[164:167], v[46:49]
	v_mfma_f32_16x16x32_bf16 v[42:45], v[210:213], v[186:189], v[42:45]
	v_mfma_f32_16x16x32_bf16 v[38:41], v[218:221], v[164:167], v[38:41]
	v_mfma_f32_16x16x32_bf16 v[34:37], v[218:221], v[186:189], v[34:37]
	v_mfma_f32_16x16x32_bf16 v[62:65], v[198:201], v[182:185], v[62:65]
	v_mfma_f32_16x16x32_bf16 v[58:61], v[198:201], v[190:193], v[58:61]
	v_mfma_f32_16x16x32_bf16 v[54:57], v[206:209], v[182:185], v[54:57]
	v_mfma_f32_16x16x32_bf16 v[50:53], v[206:209], v[190:193], v[50:53]
	v_mfma_f32_16x16x32_bf16 v[46:49], v[214:217], v[182:185], v[46:49]
	v_mfma_f32_16x16x32_bf16 v[42:45], v[214:217], v[190:193], v[42:45]
	v_mfma_f32_16x16x32_bf16 v[38:41], v[222:225], v[182:185], v[38:41]
	v_mfma_f32_16x16x32_bf16 v[34:37], v[222:225], v[190:193], v[34:37]
	s_barrier
	v_readfirstlane_b32 s0, v157
	v_lshl_add_u64 v[164:165], v[246:247], 0, s[74:75]
	s_mov_b32 m0, s0
	v_readfirstlane_b32 s0, v159
	global_load_lds_dwordx4 v[164:165], off
	v_lshl_add_u64 v[164:165], v[248:249], 0, s[74:75]
	s_mov_b32 m0, s0
	s_nop 0
	global_load_lds_dwordx4 v[164:165], off
	s_waitcnt vmcnt(6)
	s_barrier
	v_mfma_f32_16x16x32_bf16 v[30:33], v[194:197], v[226:229], v[30:33]
	v_mfma_f32_16x16x32_bf16 v[26:29], v[194:197], v[234:237], v[26:29]
	v_mfma_f32_16x16x32_bf16 v[22:25], v[202:205], v[226:229], v[22:25]
	v_mfma_f32_16x16x32_bf16 v[18:21], v[202:205], v[234:237], v[18:21]
	v_mfma_f32_16x16x32_bf16 v[14:17], v[210:213], v[226:229], v[14:17]
	v_mfma_f32_16x16x32_bf16 v[10:13], v[210:213], v[234:237], v[10:13]
	v_mfma_f32_16x16x32_bf16 v[6:9], v[218:221], v[226:229], v[6:9]
	v_mfma_f32_16x16x32_bf16 v[2:5], v[218:221], v[234:237], v[2:5]
	v_mfma_f32_16x16x32_bf16 v[30:33], v[198:201], v[230:233], v[30:33]
	v_mfma_f32_16x16x32_bf16 v[26:29], v[198:201], v[238:241], v[26:29]
	v_mfma_f32_16x16x32_bf16 v[22:25], v[206:209], v[230:233], v[22:25]
	v_mfma_f32_16x16x32_bf16 v[18:21], v[206:209], v[238:241], v[18:21]
	v_mfma_f32_16x16x32_bf16 v[14:17], v[214:217], v[230:233], v[14:17]
	v_mfma_f32_16x16x32_bf16 v[10:13], v[214:217], v[238:241], v[10:13]
	v_mfma_f32_16x16x32_bf16 v[6:9], v[222:225], v[230:233], v[6:9]
	v_mfma_f32_16x16x32_bf16 v[2:5], v[222:225], v[238:241], v[2:5]
	s_add_i32 s10, s10, 2
	s_add_u32 s8, s8, 0x100
	s_addc_u32 s9, s9, 0
	s_cmp_lt_u32 s10, 12
	s_barrier
	s_cbranch_scc1 .LBB0_105
	v_readfirstlane_b32 s0, v161
	v_lshl_add_u64 v[132:133], v[132:133], 1, s[34:35]
	s_mov_b32 m0, s0
	v_readfirstlane_b32 s0, v162
	ds_read_b128 v[134:137], v160
	ds_read_b128 v[138:141], v160 offset:1024
	ds_read_b128 v[150:153], v160 offset:2048
	ds_read_b128 v[154:157], v160 offset:3072
	ds_read_b128 v[164:167], v142
	ds_read_b128 v[182:185], v142 offset:1024
	ds_read_b128 v[186:189], v142 offset:2048
	ds_read_b128 v[190:193], v142 offset:3072
	ds_read_b128 v[194:197], v142 offset:4096
	ds_read_b128 v[198:201], v142 offset:5120
	ds_read_b128 v[202:205], v142 offset:6144
	ds_read_b128 v[206:209], v142 offset:7168
	global_load_lds_dwordx4 v[132:133], off
	v_lshl_add_u64 v[130:131], v[130:131], 1, s[34:35]
	s_mov_b32 m0, s0
	s_nop 0
	global_load_lds_dwordx4 v[130:131], off
	s_lshl_b32 s1, s23, 8
	s_add_u32 s98, s25, s1
	s_addc_u32 s99, s48, 0
	v_bfe_u32 v251, v168, 6, 2
	v_lshlrev_b32_e32 v248, 6, v251
	v_and_b32_e32 v250, 15, v168
	v_lshl_or_b32 v248, v250, 2, v248
	global_load_dword v170, v248, s[98:99]
	s_add_u32 s98, s98, 0x1000
	s_addc_u32 s99, s99, 0
	global_load_dword v252, v248, s[98:99]
	s_add_u32 s98, s98, 0x1000
	s_addc_u32 s99, s99, 0
	global_load_dword v253, v248, s[98:99]
	s_add_u32 s98, s98, 0x1000
	s_addc_u32 s99, s99, 0
	global_load_dword v162, v248, s[98:99]
	s_lshl_b32 s1, s23, 1
	v_lshrrev_b32_e32 v249, 1, v251
	v_add_u32_e32 v249, s1, v249
	v_and_b32_e32 v249, 3, v249
	v_lshrrev_b32_e32 v250, 8, v168
	v_lshl_add_u32 v249, v250, 2, v249
	v_lshlrev_b32_e32 v249, 14, v249
	v_and_b32_e32 v250, 63, v168
	v_lshl_or_b32 v249, v250, 4, v249
	v_and_b32_e32 v250, 1, v251
	v_lshl_or_b32 v249, v250, 3, v249
	s_lshr_b32 s1, s23, 1
	s_lshl_b32 s1, s1, 12
	s_add_u32 s20, s63, s1
	s_addc_u32 s21, s64, 0
	global_load_dwordx2 v[230:231], v249, s[20:21] offset:0
	global_load_dwordx2 v[238:239], v249, s[20:21] offset:1024
	s_add_u32 s20, s20, 0x20000
	s_addc_u32 s21, s21, 0
	global_load_dwordx2 v[232:233], v249, s[20:21] offset:0
	global_load_dwordx2 v[240:241], v249, s[20:21] offset:1024
	s_add_u32 s20, s20, 0x20000
	s_addc_u32 s21, s21, 0
	global_load_dwordx2 v[234:235], v249, s[20:21] offset:0
	global_load_dwordx2 v[242:243], v249, s[20:21] offset:1024
	s_add_u32 s20, s20, 0x20000
	s_addc_u32 s21, s21, 0
	global_load_dwordx2 v[236:237], v249, s[20:21] offset:0
	global_load_dwordx2 v[244:245], v249, s[20:21] offset:1024
	s_barrier
; #define G_LDA(dst, b, h)                                                                                                  \
;   _Pragma("unroll") for (int m = 0; m < 4; ++m) _Pragma("unroll") for (int k = 0; k < 2; ++k)                             \
;       dst[m][k] = *(const bf16x8*)((const char*)G_SA(b, h) + ((wr * 4 + m) * 2 + k) * 1024 + rdo)
; #define G_LDB(dst, b, h)                                                                                                  \
;   _Pragma("unroll") for (int n = 0; n < 2; ++n) _Pragma("unroll") for (int k = 0; k < 2; ++k)                             \
;       dst[n][k] = *(const bf16x8*)((const char*)G_SB(b, h) + ((wc * 2 + n) * 2 + k) * 1024 + rdo)
; #define G_WAIT_V(n) asm volatile("s_waitcnt vmcnt(" #n ")" ::: "memory")
; #define G_WAIT_L(n) asm volatile("s_waitcnt lgkmcnt(" #n ")" ::: "memory")
; #define G_BAR __builtin_amdgcn_s_barrier()
;     ...
;     G_BAR; G_WAIT_L(0); G_MMA(0, 0, At, B0); G_BAR;
;     G_LDB(B1, 0, 1); G_BAR; G_WAIT_L(0); G_MMA(0, 1, At, B1); G_BAR;
;     G_LDA(At, 0, 1); G_WAIT_V(4); G_BAR; G_WAIT_L(0); G_MMA(1, 0, At, B0); G_MMA(1, 1, At, B1); G_BAR;
;   }
;   {
;     G_LDB(B0, 1, 0); G_LDA(At, 1, 0); G_WAIT_V(2); G_BAR; G_WAIT_L(0); G_MMA(0, 0, At, B0); G_BAR;
	s_waitcnt lgkmcnt(0)
	v_mfma_f32_16x16x32_bf16 v[126:129], v[164:167], v[134:137], v[126:129]
	v_mfma_f32_16x16x32_bf16 v[122:125], v[164:167], v[150:153], v[122:125]
	v_mfma_f32_16x16x32_bf16 v[114:117], v[186:189], v[150:153], v[114:117]
	v_mfma_f32_16x16x32_bf16 v[110:113], v[194:197], v[134:137], v[110:113]
	v_mfma_f32_16x16x32_bf16 v[106:109], v[194:197], v[150:153], v[106:109]
	v_mfma_f32_16x16x32_bf16 v[102:105], v[202:205], v[134:137], v[102:105]
	v_mfma_f32_16x16x32_bf16 v[98:101], v[202:205], v[150:153], v[98:101]
	v_mfma_f32_16x16x32_bf16 v[126:129], v[182:185], v[138:141], v[126:129]
	v_mfma_f32_16x16x32_bf16 v[122:125], v[182:185], v[154:157], v[122:125]
	v_mfma_f32_16x16x32_bf16 v[118:121], v[186:189], v[134:137], v[118:121]
	v_mfma_f32_16x16x32_bf16 v[114:117], v[190:193], v[154:157], v[114:117]
	v_mfma_f32_16x16x32_bf16 v[110:113], v[198:201], v[138:141], v[110:113]
	v_mfma_f32_16x16x32_bf16 v[106:109], v[198:201], v[154:157], v[106:109]
	v_mfma_f32_16x16x32_bf16 v[102:105], v[206:209], v[138:141], v[102:105]
	v_mfma_f32_16x16x32_bf16 v[98:101], v[206:209], v[154:157], v[98:101]
	v_mfma_f32_16x16x32_bf16 v[118:121], v[190:193], v[138:141], v[118:121]
	s_barrier
	ds_read_b128 v[130:133], v158
	ds_read_b128 v[210:213], v158 offset:1024
	ds_read_b128 v[214:217], v158 offset:2048
	ds_read_b128 v[158:161], v158 offset:3072
	s_barrier
	s_waitcnt lgkmcnt(0)
	v_mfma_f32_16x16x32_bf16 v[94:97], v[164:167], v[130:133], v[94:97]
	v_mfma_f32_16x16x32_bf16 v[90:93], v[164:167], v[214:217], v[90:93]
	v_mfma_f32_16x16x32_bf16 v[86:89], v[186:189], v[130:133], v[86:89]
	v_mfma_f32_16x16x32_bf16 v[82:85], v[186:189], v[214:217], v[82:85]
	v_mfma_f32_16x16x32_bf16 v[78:81], v[194:197], v[130:133], v[78:81]
	v_mfma_f32_16x16x32_bf16 v[74:77], v[194:197], v[214:217], v[74:77]
	v_mfma_f32_16x16x32_bf16 v[70:73], v[202:205], v[130:133], v[70:73]
	v_mfma_f32_16x16x32_bf16 v[66:69], v[202:205], v[214:217], v[66:69]
	v_mfma_f32_16x16x32_bf16 v[94:97], v[182:185], v[210:213], v[94:97]
	v_mfma_f32_16x16x32_bf16 v[90:93], v[182:185], v[158:161], v[90:93]
	v_mfma_f32_16x16x32_bf16 v[86:89], v[190:193], v[210:213], v[86:89]
	v_mfma_f32_16x16x32_bf16 v[82:85], v[190:193], v[158:161], v[82:85]
	v_mfma_f32_16x16x32_bf16 v[78:81], v[198:201], v[210:213], v[78:81]
	v_mfma_f32_16x16x32_bf16 v[74:77], v[198:201], v[158:161], v[74:77]
	v_mfma_f32_16x16x32_bf16 v[70:73], v[206:209], v[210:213], v[70:73]
	v_mfma_f32_16x16x32_bf16 v[66:69], v[206:209], v[158:161], v[66:69]
	s_barrier
	ds_read_b128 v[164:167], v142 offset:16384
	ds_read_b128 v[182:185], v142 offset:17408
	ds_read_b128 v[186:189], v142 offset:18432
	ds_read_b128 v[190:193], v142 offset:19456
	ds_read_b128 v[194:197], v142 offset:20480
	ds_read_b128 v[198:201], v142 offset:21504
	ds_read_b128 v[202:205], v142 offset:22528
	ds_read_b128 v[206:209], v142 offset:23552
	s_waitcnt vmcnt(16)
	s_barrier
	s_waitcnt lgkmcnt(0)
	v_mfma_f32_16x16x32_bf16 v[62:65], v[164:167], v[134:137], v[62:65]
	v_mfma_f32_16x16x32_bf16 v[58:61], v[164:167], v[150:153], v[58:61]
	v_mfma_f32_16x16x32_bf16 v[54:57], v[186:189], v[134:137], v[54:57]
	v_mfma_f32_16x16x32_bf16 v[50:53], v[186:189], v[150:153], v[50:53]
	v_mfma_f32_16x16x32_bf16 v[46:49], v[194:197], v[134:137], v[46:49]
	v_mfma_f32_16x16x32_bf16 v[38:41], v[202:205], v[134:137], v[38:41]
	v_mfma_f32_16x16x32_bf16 v[34:37], v[202:205], v[150:153], v[34:37]
	v_mfma_f32_16x16x32_bf16 v[62:65], v[182:185], v[138:141], v[62:65]
	v_mfma_f32_16x16x32_bf16 v[58:61], v[182:185], v[154:157], v[58:61]
	v_mfma_f32_16x16x32_bf16 v[54:57], v[190:193], v[138:141], v[54:57]
	v_mfma_f32_16x16x32_bf16 v[50:53], v[190:193], v[154:157], v[50:53]
	v_mfma_f32_16x16x32_bf16 v[46:49], v[198:201], v[138:141], v[46:49]
	v_mfma_f32_16x16x32_bf16 v[42:45], v[194:197], v[150:153], v[42:45]
	v_mfma_f32_16x16x32_bf16 v[38:41], v[206:209], v[138:141], v[38:41]
	v_mfma_f32_16x16x32_bf16 v[34:37], v[206:209], v[154:157], v[34:37]
	v_mfma_f32_16x16x32_bf16 v[42:45], v[198:201], v[154:157], v[42:45]
	v_mfma_f32_16x16x32_bf16 v[26:29], v[164:167], v[214:217], v[26:29]
	v_mfma_f32_16x16x32_bf16 v[22:25], v[186:189], v[130:133], v[22:25]
	v_mfma_f32_16x16x32_bf16 v[14:17], v[194:197], v[130:133], v[14:17]
	v_mfma_f32_16x16x32_bf16 v[10:13], v[194:197], v[214:217], v[10:13]
	v_mfma_f32_16x16x32_bf16 v[2:5], v[202:205], v[214:217], v[2:5]
	v_mfma_f32_16x16x32_bf16 v[30:33], v[164:167], v[130:133], v[30:33]
	v_mfma_f32_16x16x32_bf16 v[26:29], v[182:185], v[158:161], v[26:29]
	v_mfma_f32_16x16x32_bf16 v[22:25], v[190:193], v[210:213], v[22:25]
	v_mfma_f32_16x16x32_bf16 v[18:21], v[186:189], v[214:217], v[18:21]
	v_mfma_f32_16x16x32_bf16 v[14:17], v[198:201], v[210:213], v[14:17]
	v_mfma_f32_16x16x32_bf16 v[10:13], v[198:201], v[158:161], v[10:13]
	v_mfma_f32_16x16x32_bf16 v[6:9], v[202:205], v[130:133], v[6:9]
	v_mfma_f32_16x16x32_bf16 v[2:5], v[206:209], v[158:161], v[2:5]
	v_mfma_f32_16x16x32_bf16 v[30:33], v[182:185], v[210:213], v[30:33]
	v_mfma_f32_16x16x32_bf16 v[18:21], v[190:193], v[158:161], v[18:21]
	v_mfma_f32_16x16x32_bf16 v[6:9], v[206:209], v[210:213], v[6:9]
	s_barrier
	ds_read_b128 v[130:133], v148
	ds_read_b128 v[154:157], v148 offset:1024
	ds_read_b128 v[164:167], v148 offset:2048
	ds_read_b128 v[182:185], v148 offset:3072
	ds_read_b128 v[186:189], v142 offset:32768
	ds_read_b128 v[190:193], v142 offset:33792
	ds_read_b128 v[194:197], v142 offset:34816
	ds_read_b128 v[198:201], v142 offset:35840
	ds_read_b128 v[202:205], v142 offset:36864
	ds_read_b128 v[206:209], v142 offset:37888
	ds_read_b128 v[210:213], v142 offset:38912
	ds_read_b128 v[214:217], v142 offset:39936
	s_waitcnt vmcnt(14)
	s_barrier
; #define G_LDA(dst, b, h)                                                                                                  \
;   _Pragma("unroll") for (int m = 0; m < 4; ++m) _Pragma("unroll") for (int k = 0; k < 2; ++k)                             \
;       dst[m][k] = *(const bf16x8*)((const char*)G_SA(b, h) + ((wr * 4 + m) * 2 + k) * 1024 + rdo)
; #define G_LDB(dst, b, h)                                                                                                  \
;   _Pragma("unroll") for (int n = 0; n < 2; ++n) _Pragma("unroll") for (int k = 0; k < 2; ++k)                             \
;       dst[n][k] = *(const bf16x8*)((const char*)G_SB(b, h) + ((wc * 2 + n) * 2 + k) * 1024 + rdo)
; #define G_WAIT_V(n) asm volatile("s_waitcnt vmcnt(" #n ")" ::: "memory")
; #define G_WAIT_L(n) asm volatile("s_waitcnt lgkmcnt(" #n ")" ::: "memory")
; #define G_BAR __builtin_amdgcn_s_barrier()
;     ...
;     G_LDB(B0, 1, 0); G_LDA(At, 1, 0); G_WAIT_V(2); G_BAR; G_WAIT_L(0); G_MMA(0, 0, At, B0); G_BAR;
;     G_LDB(B1, 1, 1); G_WAIT_V(0); G_BAR; G_WAIT_L(0); G_MMA(0, 1, At, B1); G_BAR;
;     G_LDA(At, 1, 1); G_BAR; G_WAIT_L(0); G_MMA(1, 0, At, B0); G_MMA(1, 1, At, B1); G_BAR;
;   }
;   if (wr == 0) G_BAR;
	s_waitcnt lgkmcnt(0)
	v_mfma_f32_16x16x32_bf16 v[126:129], v[186:189], v[130:133], v[126:129]
	v_mfma_f32_16x16x32_bf16 v[122:125], v[186:189], v[164:167], v[122:125]
	v_mfma_f32_16x16x32_bf16 v[118:121], v[194:197], v[130:133], v[118:121]
	v_mfma_f32_16x16x32_bf16 v[114:117], v[194:197], v[164:167], v[114:117]
	v_mfma_f32_16x16x32_bf16 v[110:113], v[202:205], v[130:133], v[110:113]
	v_mfma_f32_16x16x32_bf16 v[106:109], v[202:205], v[164:167], v[106:109]
	v_mfma_f32_16x16x32_bf16 v[102:105], v[210:213], v[130:133], v[102:105]
	v_mfma_f32_16x16x32_bf16 v[98:101], v[210:213], v[164:167], v[98:101]
	v_mfma_f32_16x16x32_bf16 v[158:161], v[190:193], v[154:157], v[126:129]
	v_mfma_f32_16x16x32_bf16 v[150:153], v[190:193], v[182:185], v[122:125]
	v_mfma_f32_16x16x32_bf16 v[146:149], v[198:201], v[154:157], v[118:121]
	v_mfma_f32_16x16x32_bf16 v[138:141], v[198:201], v[182:185], v[114:117]
	v_mfma_f32_16x16x32_bf16 v[134:137], v[206:209], v[154:157], v[110:113]
	v_mfma_f32_16x16x32_bf16 v[126:129], v[206:209], v[182:185], v[106:109]
	v_mfma_f32_16x16x32_bf16 v[122:125], v[214:217], v[154:157], v[102:105]
	v_mfma_f32_16x16x32_bf16 v[114:117], v[214:217], v[182:185], v[98:101]
	s_barrier
	ds_read_b128 v[118:121], v145
	ds_read_b128 v[218:221], v145 offset:1024
	ds_read_b128 v[222:225], v145 offset:2048
	ds_read_b128 v[226:229], v145 offset:3072
	s_waitcnt vmcnt(12)
	s_barrier
	s_waitcnt lgkmcnt(0)
	v_mfma_f32_16x16x32_bf16 v[94:97], v[186:189], v[118:121], v[94:97]
	v_mfma_f32_16x16x32_bf16 v[90:93], v[186:189], v[222:225], v[90:93]
	v_mfma_f32_16x16x32_bf16 v[86:89], v[194:197], v[118:121], v[86:89]
	v_mfma_f32_16x16x32_bf16 v[82:85], v[194:197], v[222:225], v[82:85]
	v_mfma_f32_16x16x32_bf16 v[78:81], v[202:205], v[118:121], v[78:81]
	v_mfma_f32_16x16x32_bf16 v[74:77], v[202:205], v[222:225], v[74:77]
	v_mfma_f32_16x16x32_bf16 v[70:73], v[210:213], v[118:121], v[70:73]
	v_mfma_f32_16x16x32_bf16 v[66:69], v[210:213], v[222:225], v[66:69]
	v_mfma_f32_16x16x32_bf16 v[110:113], v[190:193], v[218:221], v[94:97]
	v_mfma_f32_16x16x32_bf16 v[106:109], v[190:193], v[226:229], v[90:93]
	v_mfma_f32_16x16x32_bf16 v[102:105], v[198:201], v[218:221], v[86:89]
	v_mfma_f32_16x16x32_bf16 v[98:101], v[198:201], v[226:229], v[82:85]
	v_mfma_f32_16x16x32_bf16 v[94:97], v[206:209], v[218:221], v[78:81]
	v_mfma_f32_16x16x32_bf16 v[90:93], v[206:209], v[226:229], v[74:77]
	v_mfma_f32_16x16x32_bf16 v[86:89], v[214:217], v[218:221], v[70:73]
	v_mfma_f32_16x16x32_bf16 v[82:85], v[214:217], v[226:229], v[66:69]
	s_barrier
	ds_read_b128 v[186:189], v142 offset:49152
	ds_read_b128 v[190:193], v142 offset:50176
	ds_read_b128 v[194:197], v142 offset:51200
	ds_read_b128 v[198:201], v142 offset:52224
	ds_read_b128 v[202:205], v142 offset:53248
	ds_read_b128 v[206:209], v142 offset:54272
	ds_read_b128 v[210:213], v142 offset:55296
	ds_read_b128 v[142:145], v142 offset:56320
	s_barrier
	s_waitcnt lgkmcnt(0)
	v_mfma_f32_16x16x32_bf16 v[62:65], v[186:189], v[130:133], v[62:65]
	v_mfma_f32_16x16x32_bf16 v[58:61], v[186:189], v[164:167], v[58:61]
	v_mfma_f32_16x16x32_bf16 v[54:57], v[194:197], v[130:133], v[54:57]
	v_mfma_f32_16x16x32_bf16 v[50:53], v[194:197], v[164:167], v[50:53]
	v_mfma_f32_16x16x32_bf16 v[46:49], v[202:205], v[130:133], v[46:49]
	v_mfma_f32_16x16x32_bf16 v[42:45], v[202:205], v[164:167], v[42:45]
	v_mfma_f32_16x16x32_bf16 v[38:41], v[210:213], v[130:133], v[38:41]
	v_mfma_f32_16x16x32_bf16 v[34:37], v[210:213], v[164:167], v[34:37]
	v_mfma_f32_16x16x32_bf16 v[78:81], v[190:193], v[154:157], v[62:65]
	v_mfma_f32_16x16x32_bf16 v[74:77], v[190:193], v[182:185], v[58:61]
	v_mfma_f32_16x16x32_bf16 v[70:73], v[198:201], v[154:157], v[54:57]
	v_mfma_f32_16x16x32_bf16 v[66:69], v[198:201], v[182:185], v[50:53]
	v_mfma_f32_16x16x32_bf16 v[62:65], v[206:209], v[154:157], v[46:49]
	v_mfma_f32_16x16x32_bf16 v[58:61], v[206:209], v[182:185], v[42:45]
	v_mfma_f32_16x16x32_bf16 v[54:57], v[142:145], v[154:157], v[38:41]
	v_mfma_f32_16x16x32_bf16 v[50:53], v[142:145], v[182:185], v[34:37]
	v_mfma_f32_16x16x32_bf16 v[30:33], v[186:189], v[118:121], v[30:33]
	v_mfma_f32_16x16x32_bf16 v[26:29], v[186:189], v[222:225], v[26:29]
	v_mfma_f32_16x16x32_bf16 v[22:25], v[194:197], v[118:121], v[22:25]
	v_mfma_f32_16x16x32_bf16 v[18:21], v[194:197], v[222:225], v[18:21]
	v_mfma_f32_16x16x32_bf16 v[14:17], v[202:205], v[118:121], v[14:17]
	v_mfma_f32_16x16x32_bf16 v[10:13], v[202:205], v[222:225], v[10:13]
	v_mfma_f32_16x16x32_bf16 v[6:9], v[210:213], v[118:121], v[6:9]
	v_mfma_f32_16x16x32_bf16 v[2:5], v[210:213], v[222:225], v[2:5]
	v_mfma_f32_16x16x32_bf16 v[46:49], v[190:193], v[218:221], v[30:33]
	v_mfma_f32_16x16x32_bf16 v[38:41], v[190:193], v[226:229], v[26:29]
	v_mfma_f32_16x16x32_bf16 v[34:37], v[198:201], v[218:221], v[22:25]
	v_mfma_f32_16x16x32_bf16 v[26:29], v[198:201], v[226:229], v[18:21]
	v_mfma_f32_16x16x32_bf16 v[22:25], v[206:209], v[218:221], v[14:17]
	v_mfma_f32_16x16x32_bf16 v[14:17], v[206:209], v[226:229], v[10:13]
	v_mfma_f32_16x16x32_bf16 v[10:13], v[142:145], v[218:221], v[6:9]
	v_mfma_f32_16x16x32_bf16 v[2:5], v[142:145], v[226:229], v[2:5]
	v_cmp_gt_u32_e32 vcc, s67, v0
	s_barrier
	s_and_saveexec_b64 s[8:9], vcc
	s_cbranch_execz .LBB0_108
	s_barrier

; #define G_LDA(dst, b, h)                                                                                                  \
;   _Pragma("unroll") for (int m = 0; m < 4; ++m) _Pragma("unroll") for (int k = 0; k < 2; ++k)                             \
;       dst[m][k] = *(const bf16x8*)((const char*)G_SA(b, h) + ((wr * 4 + m) * 2 + k) * 1024 + rdo)
; #define G_LDB(dst, b, h)                                                                                                  \
;   _Pragma("unroll") for (int n = 0; n < 2; ++n) _Pragma("unroll") for (int k = 0; k < 2; ++k)                             \
;       dst[n][k] = *(const bf16x8*)((const char*)G_SB(b, h) + ((wc * 2 + n) * 2 + k) * 1024 + rdo)
; #define G_WAIT_V(n) asm volatile("s_waitcnt vmcnt(" #n ")" ::: "memory")
; #define G_WAIT_L(n) asm volatile("s_waitcnt lgkmcnt(" #n ")" ::: "memory")
; #define G_BAR __builtin_amdgcn_s_barrier()
; #define G_SCHED __builtin_amdgcn_sched_barrier(0)
;     ...
;   G_WAIT_V(4); G_BAR;
;   G_STAGE(G_SB(1, 0), B, ob0, ob1, LDB, 0, KB(1)); G_STAGE(G_SA(1, 0), A, oa0, oa1, LDA, 0, KA(1)); G_STAGE(G_SB(1, 1), B, ob0, ob1, LDB, 128, KB(1));
;   G_WAIT_V(6); G_BAR;
;   for (int tt = 0; tt < nt - 2; tt += 2) {
;     G_LDB(B0, 0, 0); G_SCHED; G_LDA(At, 0, 0); G_STAGE(G_SA(1, 1), A, oa0, oa1, LDA, 128, KA(tt + 1));
;     G_WAIT_L(8); G_BAR; G_WAIT_L(0); G_MMA(0, 0, At, B0); G_BAR; G_SCHED;
;     G_LDB(B1, 0, 1); G_STAGE(G_SB(0, 0), B, ob0, ob1, LDB, 0, KB(tt + 2));
.LBB0_217:
	s_or_b64 exec, exec, s[20:21]
	v_add_u32_e32 v13, 0x18000, v18
	v_lshl_add_u64 v[24:25], v[6:7], 0, s[76:77]
	v_readfirstlane_b32 s27, v13
	v_add_u32_e32 v13, 0x1a000, v18
	s_mov_b32 m0, s27
	v_readfirstlane_b32 s28, v13
	v_add_u32_e32 v13, 0x8000, v18
	s_waitcnt vmcnt(4)
	s_barrier
	global_load_lds_dwordx4 v[24:25], off
	v_lshl_add_u64 v[24:25], v[8:9], 0, s[76:77]
	s_mov_b32 m0, s28
	v_readfirstlane_b32 s21, v13
	v_add_u32_e32 v13, 0xa000, v18
	global_load_lds_dwordx4 v[24:25], off
	v_lshl_add_u64 v[24:25], v[10:11], 0, s[76:77]
	s_mov_b32 m0, s21
	v_readfirstlane_b32 s26, v13
	s_add_u32 s0, s18, 0x10080
	v_add_u32_e32 v13, 0x1c000, v18
	global_load_lds_dwordx4 v[24:25], off
	v_lshl_add_u64 v[24:25], v[14:15], 0, s[76:77]
	s_mov_b32 m0, s26
	s_addc_u32 s1, s19, 0
	v_readfirstlane_b32 s15, v13
	v_add_u32_e32 v13, 0x1e000, v18
	global_load_lds_dwordx4 v[24:25], off
	v_lshl_add_u64 v[24:25], s[0:1], 0, v[2:3]
	s_mov_b32 m0, s15
	v_readfirstlane_b32 s20, v13
	global_load_lds_dwordx4 v[24:25], off
	v_lshl_add_u64 v[24:25], s[0:1], 0, v[4:5]
	s_mov_b32 m0, s20
	v_lshlrev_b32_e32 v26, 2, v0
	global_load_lds_dwordx4 v[24:25], off
	v_lshlrev_b32_e32 v24, 6, v0
	v_and_b32_e32 v13, 48, v0
	v_and_b32_e32 v25, 0x3c0, v24
	v_and_b32_e32 v41, 32, v26
	v_or_b32_e32 v40, v25, v13
	v_bitop3_b32 v13, v25, v41, v13 bitop3:0x36
	s_movk_i32 s0, 0x3000
	v_and_or_b32 v162, v24, s0, v13
	s_add_u32 s0, s16, 0x10080
	s_addc_u32 s1, s17, 0
	v_lshl_add_u64 v[72:73], s[0:1], 0, v[2:3]
	v_lshl_add_u64 v[74:75], s[0:1], 0, v[4:5]
	s_add_u32 s0, s18, 0x10100
	s_addc_u32 s1, s19, 0
	v_or_b32_e32 v230, 0x10000, v162
	v_or_b32_e32 v232, 0x10800, v162
	s_waitcnt vmcnt(6)
	s_barrier
	v_lshl_add_u64 v[160:161], s[0:1], 0, v[2:3]
	v_lshl_add_u64 v[194:195], s[0:1], 0, v[4:5]
	s_add_u32 s0, s16, 0x10100
	v_or_b32_e32 v231, 0x10400, v162
	ds_read_b128 v[24:27], v230
	ds_read_b128 v[28:31], v231
	v_or_b32_e32 v233, 0x10c00, v162
	ds_read_b128 v[32:35], v232
	ds_read_b128 v[36:39], v233
	s_addc_u32 s1, s17, 0
	v_lshl_add_u64 v[214:215], s[0:1], 0, v[2:3]
	v_lshl_add_u64 v[216:217], s[0:1], 0, v[4:5]
	s_add_u32 s0, s18, 0x10180
	s_addc_u32 s1, s19, 0
	v_lshlrev_b32_e32 v42, 13, v12
	v_lshl_add_u64 v[120:121], v[6:7], 0, s[82:83]
	v_lshl_add_u64 v[122:123], v[8:9], 0, s[82:83]
	v_lshl_add_u64 v[152:153], v[10:11], 0, s[82:83]
	v_lshl_add_u64 v[226:227], v[6:7], 0, s[90:91]
	v_lshl_add_u64 v[228:229], v[8:9], 0, s[90:91]
	v_lshl_add_u64 v[12:13], v[10:11], 0, s[90:91]
	v_lshl_add_u64 v[10:11], v[14:15], 0, s[90:91]
	v_lshl_add_u64 v[8:9], s[0:1], 0, v[2:3]
	v_lshl_add_u64 v[6:7], s[0:1], 0, v[4:5]
	v_lshl_add_u64 v[154:155], v[14:15], 0, s[82:83]
	v_add_u32_e32 v14, 0xc000, v18
	v_bitop3_b32 v242, v40, v42, v41 bitop3:0xde
	v_readfirstlane_b32 s19, v14
	v_add_u32_e32 v14, 0xe000, v18
	s_mov_b32 m0, s19
	v_readfirstlane_b32 s18, v14
	ds_read_b128 v[40:43], v242
	ds_read_b128 v[44:47], v242 offset:1024
	ds_read_b128 v[48:51], v242 offset:2048
	ds_read_b128 v[52:55], v242 offset:3072
	ds_read_b128 v[56:59], v242 offset:4096
	ds_read_b128 v[60:63], v242 offset:5120
	ds_read_b128 v[64:67], v242 offset:6144
	ds_read_b128 v[68:71], v242 offset:7168
	global_load_lds_dwordx4 v[72:73], off
	s_mov_b32 m0, s18
	s_nop 0
	global_load_lds_dwordx4 v[74:75], off
	s_waitcnt lgkmcnt(8)
	s_barrier
	s_waitcnt lgkmcnt(0)
	v_mfma_f32_16x16x32_bf16 v[72:75], v[40:43], v[24:27], 0
	v_mfma_f32_16x16x32_bf16 v[76:79], v[40:43], v[32:35], 0
	v_mfma_f32_16x16x32_bf16 v[80:83], v[48:51], v[24:27], 0
	v_mfma_f32_16x16x32_bf16 v[84:87], v[48:51], v[32:35], 0
	v_mfma_f32_16x16x32_bf16 v[88:91], v[56:59], v[24:27], 0
	v_mfma_f32_16x16x32_bf16 v[92:95], v[56:59], v[32:35], 0
	v_mfma_f32_16x16x32_bf16 v[96:99], v[64:67], v[24:27], 0
	v_mfma_f32_16x16x32_bf16 v[100:103], v[64:67], v[32:35], 0
	v_mfma_f32_16x16x32_bf16 v[72:75], v[44:47], v[28:31], v[72:75]
	v_mfma_f32_16x16x32_bf16 v[76:79], v[44:47], v[36:39], v[76:79]
	v_mfma_f32_16x16x32_bf16 v[80:83], v[52:55], v[28:31], v[80:83]
	v_mfma_f32_16x16x32_bf16 v[84:87], v[52:55], v[36:39], v[84:87]
	v_mfma_f32_16x16x32_bf16 v[88:91], v[60:63], v[28:31], v[88:91]
	v_mfma_f32_16x16x32_bf16 v[92:95], v[60:63], v[36:39], v[92:95]
	v_mfma_f32_16x16x32_bf16 v[96:99], v[68:71], v[28:31], v[96:99]
	v_mfma_f32_16x16x32_bf16 v[100:103], v[68:71], v[36:39], v[100:103]
	s_barrier
	v_readfirstlane_b32 s0, v22
	v_or_b32_e32 v234, 0x14000, v162
	v_or_b32_e32 v236, 0x14800, v162
	s_mov_b32 m0, s0
	v_readfirstlane_b32 s0, v23
	v_or_b32_e32 v235, 0x14400, v162
	ds_read_b128 v[104:107], v234
	ds_read_b128 v[108:111], v235
	v_or_b32_e32 v237, 0x14c00, v162
	ds_read_b128 v[112:115], v236
	ds_read_b128 v[116:119], v237
	global_load_lds_dwordx4 v[120:121], off
	s_mov_b32 m0, s0
	s_nop 0
	global_load_lds_dwordx4 v[122:123], off
	s_barrier
	s_waitcnt lgkmcnt(0)
	v_mfma_f32_16x16x32_bf16 v[120:123], v[40:43], v[104:107], 0
	v_mfma_f32_16x16x32_bf16 v[40:43], v[40:43], v[112:115], 0
	v_mfma_f32_16x16x32_bf16 v[120:123], v[44:47], v[108:111], v[120:123]
	v_mfma_f32_16x16x32_bf16 v[40:43], v[44:47], v[116:119], v[40:43]
	v_mfma_f32_16x16x32_bf16 v[44:47], v[48:51], v[104:107], 0
	v_mfma_f32_16x16x32_bf16 v[48:51], v[48:51], v[112:115], 0
	v_mfma_f32_16x16x32_bf16 v[44:47], v[52:55], v[108:111], v[44:47]
	v_mfma_f32_16x16x32_bf16 v[48:51], v[52:55], v[116:119], v[48:51]
	v_mfma_f32_16x16x32_bf16 v[52:55], v[56:59], v[104:107], 0
	v_mfma_f32_16x16x32_bf16 v[56:59], v[56:59], v[112:115], 0
	v_mfma_f32_16x16x32_bf16 v[52:55], v[60:63], v[108:111], v[52:55]
	v_mfma_f32_16x16x32_bf16 v[56:59], v[60:63], v[116:119], v[56:59]
	v_mfma_f32_16x16x32_bf16 v[60:63], v[64:67], v[104:107], 0
	v_mfma_f32_16x16x32_bf16 v[64:67], v[64:67], v[112:115], 0
	v_mfma_f32_16x16x32_bf16 v[60:63], v[68:71], v[108:111], v[60:63]
	v_mfma_f32_16x16x32_bf16 v[64:67], v[68:71], v[116:119], v[64:67]
	v_readfirstlane_b32 s0, v18
	s_mov_b32 m0, s0
	v_readfirstlane_b32 s0, v19
	s_barrier
; #define G_LDA(dst, b, h)                                                                                                  \
;   _Pragma("unroll") for (int m = 0; m < 4; ++m) _Pragma("unroll") for (int k = 0; k < 2; ++k)                             \
;       dst[m][k] = *(const bf16x8*)((const char*)G_SA(b, h) + ((wr * 4 + m) * 2 + k) * 1024 + rdo)
; #define G_LDB(dst, b, h)                                                                                                  \
;   _Pragma("unroll") for (int n = 0; n < 2; ++n) _Pragma("unroll") for (int k = 0; k < 2; ++k)                             \
;       dst[n][k] = *(const bf16x8*)((const char*)G_SB(b, h) + ((wc * 2 + n) * 2 + k) * 1024 + rdo)
; #define G_WAIT_V(n) asm volatile("s_waitcnt vmcnt(" #n ")" ::: "memory")
; #define G_WAIT_L(n) asm volatile("s_waitcnt lgkmcnt(" #n ")" ::: "memory")
; #define G_BAR __builtin_amdgcn_s_barrier()
; #define G_SCHED __builtin_amdgcn_sched_barrier(0)
;     ...
;     G_BAR; G_WAIT_L(0); G_MMA(0, 1, At, B1); G_BAR;
;     G_LDA(At, 0, 1); G_STAGE(G_SA(0, 0), A, oa0, oa1, LDA, 0, KA(tt + 2));
;     G_BAR; G_WAIT_L(0); G_MMA(1, 0, At, B0); G_BAR; G_SCHED;
;     G_STAGE(G_SB(0, 1), B, ob0, ob1, LDB, 128, KB(tt + 2));
;     G_WAIT_V(6); G_BAR; G_MMA(1, 1, At, B1); G_BAR;
;     G_LDB(B0, 1, 0); G_SCHED; G_LDA(At, 1, 0); G_STAGE(G_SA(0, 1), A, oa0, oa1, LDA, 128, KA(tt + 2));
;     G_WAIT_L(8); G_BAR; G_WAIT_L(0); G_MMA(0, 0, At, B0); G_BAR; G_SCHED;
;     G_LDB(B1, 1, 1); G_STAGE(G_SB(1, 0), B, ob0, ob1, LDB, 0, KB(tt + 3));
	ds_read_b128 v[68:71], v242 offset:16384
	ds_read_b128 v[124:127], v242 offset:17408
	ds_read_b128 v[128:131], v242 offset:18432
	ds_read_b128 v[132:135], v242 offset:19456
	ds_read_b128 v[136:139], v242 offset:20480
	ds_read_b128 v[140:143], v242 offset:21504
	ds_read_b128 v[144:147], v242 offset:22528
	ds_read_b128 v[148:151], v242 offset:23552
	global_load_lds_dwordx4 v[152:153], off
	s_mov_b32 m0, s0
	s_nop 0
	global_load_lds_dwordx4 v[154:155], off
	s_barrier
	s_waitcnt lgkmcnt(0)
	v_mfma_f32_16x16x32_bf16 v[152:155], v[68:71], v[24:27], 0
	v_mfma_f32_16x16x32_bf16 v[164:167], v[128:131], v[24:27], 0
	v_mfma_f32_16x16x32_bf16 v[186:189], v[136:139], v[24:27], 0
	v_mfma_f32_16x16x32_bf16 v[22:25], v[144:147], v[24:27], 0
	v_mfma_f32_16x16x32_bf16 v[152:155], v[124:127], v[28:31], v[152:155]
	v_mfma_f32_16x16x32_bf16 v[164:167], v[132:135], v[28:31], v[164:167]
	v_mfma_f32_16x16x32_bf16 v[186:189], v[140:143], v[28:31], v[186:189]
	v_mfma_f32_16x16x32_bf16 v[22:25], v[148:151], v[28:31], v[22:25]
	v_mfma_f32_16x16x32_bf16 v[26:29], v[144:147], v[32:35], 0
	v_mfma_f32_16x16x32_bf16 v[156:159], v[68:71], v[32:35], 0
	v_mfma_f32_16x16x32_bf16 v[182:185], v[128:131], v[32:35], 0
	v_mfma_f32_16x16x32_bf16 v[190:193], v[136:139], v[32:35], 0
	v_mfma_f32_16x16x32_bf16 v[26:29], v[148:151], v[36:39], v[26:29]
	v_mfma_f32_16x16x32_bf16 v[156:159], v[124:127], v[36:39], v[156:159]
	v_mfma_f32_16x16x32_bf16 v[182:185], v[132:135], v[36:39], v[182:185]
	v_mfma_f32_16x16x32_bf16 v[190:193], v[140:143], v[36:39], v[190:193]
	s_barrier
	v_readfirstlane_b32 s0, v20
	s_mov_b32 m0, s0
	v_readfirstlane_b32 s0, v21
	global_load_lds_dwordx4 v[160:161], off
	s_mov_b32 m0, s0
	s_nop 0
	global_load_lds_dwordx4 v[194:195], off
	s_waitcnt vmcnt(6)
	s_barrier
	v_mfma_f32_16x16x32_bf16 v[18:21], v[68:71], v[104:107], 0
	v_mfma_f32_16x16x32_bf16 v[30:33], v[68:71], v[112:115], 0
	v_mfma_f32_16x16x32_bf16 v[18:21], v[124:127], v[108:111], v[18:21]
	v_mfma_f32_16x16x32_bf16 v[30:33], v[124:127], v[116:119], v[30:33]
	v_mfma_f32_16x16x32_bf16 v[34:37], v[128:131], v[104:107], 0
	v_mfma_f32_16x16x32_bf16 v[124:127], v[136:139], v[104:107], 0
	v_mfma_f32_16x16x32_bf16 v[104:107], v[144:147], v[104:107], 0
	v_mfma_f32_16x16x32_bf16 v[34:37], v[132:135], v[108:111], v[34:37]
	v_mfma_f32_16x16x32_bf16 v[68:71], v[128:131], v[112:115], 0
	v_mfma_f32_16x16x32_bf16 v[124:127], v[140:143], v[108:111], v[124:127]
	v_mfma_f32_16x16x32_bf16 v[128:131], v[136:139], v[112:115], 0
	v_mfma_f32_16x16x32_bf16 v[104:107], v[148:151], v[108:111], v[104:107]
	v_mfma_f32_16x16x32_bf16 v[108:111], v[144:147], v[112:115], 0
	v_mfma_f32_16x16x32_bf16 v[68:71], v[132:135], v[116:119], v[68:71]
	v_mfma_f32_16x16x32_bf16 v[128:131], v[140:143], v[116:119], v[128:131]
	v_mfma_f32_16x16x32_bf16 v[108:111], v[148:151], v[116:119], v[108:111]
	v_or_b32_e32 v160, 0x18000, v162
	v_or_b32_e32 v238, 0x18800, v162
	s_barrier
	v_or_b32_e32 v161, 0x18400, v162
	ds_read_b128 v[112:115], v160
	ds_read_b128 v[116:119], v161
	v_or_b32_e32 v239, 0x18c00, v162
	ds_read_b128 v[132:135], v238
	ds_read_b128 v[136:139], v239
	v_readfirstlane_b32 s0, v16
	s_mov_b32 m0, s0
	v_readfirstlane_b32 s0, v17
	ds_read_b128 v[140:143], v242 offset:32768
	ds_read_b128 v[144:147], v242 offset:33792
	ds_read_b128 v[148:151], v242 offset:34816
	ds_read_b128 v[194:197], v242 offset:35840
	ds_read_b128 v[198:201], v242 offset:36864
	ds_read_b128 v[202:205], v242 offset:37888
	ds_read_b128 v[206:209], v242 offset:38912
	ds_read_b128 v[210:213], v242 offset:39936
	global_load_lds_dwordx4 v[214:215], off
	s_mov_b32 m0, s0
	s_nop 0
	global_load_lds_dwordx4 v[216:217], off
	s_waitcnt lgkmcnt(8)
	s_barrier
	s_waitcnt lgkmcnt(0)
	v_mfma_f32_16x16x32_bf16 v[14:17], v[140:143], v[112:115], v[72:75]
	v_mfma_f32_16x16x32_bf16 v[72:75], v[140:143], v[132:135], v[76:79]
	v_mfma_f32_16x16x32_bf16 v[76:79], v[148:151], v[112:115], v[80:83]
	v_mfma_f32_16x16x32_bf16 v[80:83], v[148:151], v[132:135], v[84:87]
	v_mfma_f32_16x16x32_bf16 v[84:87], v[198:201], v[112:115], v[88:91]
	v_mfma_f32_16x16x32_bf16 v[88:91], v[198:201], v[132:135], v[92:95]
	v_mfma_f32_16x16x32_bf16 v[92:95], v[206:209], v[112:115], v[96:99]
	v_mfma_f32_16x16x32_bf16 v[96:99], v[206:209], v[132:135], v[100:103]
	v_mfma_f32_16x16x32_bf16 v[14:17], v[144:147], v[116:119], v[14:17]
	v_mfma_f32_16x16x32_bf16 v[72:75], v[144:147], v[136:139], v[72:75]
	v_mfma_f32_16x16x32_bf16 v[76:79], v[194:197], v[116:119], v[76:79]
	v_mfma_f32_16x16x32_bf16 v[80:83], v[194:197], v[136:139], v[80:83]
	v_mfma_f32_16x16x32_bf16 v[84:87], v[202:205], v[116:119], v[84:87]
	v_mfma_f32_16x16x32_bf16 v[88:91], v[202:205], v[136:139], v[88:91]
	v_mfma_f32_16x16x32_bf16 v[92:95], v[210:213], v[116:119], v[92:95]
	v_mfma_f32_16x16x32_bf16 v[96:99], v[210:213], v[136:139], v[96:99]
	s_barrier
	v_or_b32_e32 v240, 0x1c000, v162
	v_or_b32_e32 v243, 0x1c800, v162
	s_mov_b32 m0, s27
	v_or_b32_e32 v241, 0x1c400, v162
	ds_read_b128 v[100:103], v240
	ds_read_b128 v[214:217], v241
	v_or_b32_e32 v162, 0x1cc00, v162
	ds_read_b128 v[218:221], v243
	ds_read_b128 v[222:225], v162
	global_load_lds_dwordx4 v[226:227], off
	s_mov_b32 m0, s28
	s_nop 0
	global_load_lds_dwordx4 v[228:229], off
	s_barrier
; #define G_LDA(dst, b, h)                                                                                                  \
;   _Pragma("unroll") for (int m = 0; m < 4; ++m) _Pragma("unroll") for (int k = 0; k < 2; ++k)                             \
;       dst[m][k] = *(const bf16x8*)((const char*)G_SA(b, h) + ((wr * 4 + m) * 2 + k) * 1024 + rdo)
; #define G_LDB(dst, b, h)                                                                                                  \
;   _Pragma("unroll") for (int n = 0; n < 2; ++n) _Pragma("unroll") for (int k = 0; k < 2; ++k)                             \
;       dst[n][k] = *(const bf16x8*)((const char*)G_SB(b, h) + ((wc * 2 + n) * 2 + k) * 1024 + rdo)
; #define G_WAIT_V(n) asm volatile("s_waitcnt vmcnt(" #n ")" ::: "memory")
; #define G_WAIT_L(n) asm volatile("s_waitcnt lgkmcnt(" #n ")" ::: "memory")
; #define G_BAR __builtin_amdgcn_s_barrier()
; #define G_SCHED __builtin_amdgcn_sched_barrier(0)
; DI void br_flush(PREF p, f32x4 (&acc)[2][2][4][2], int slot) { br_store(p, acc, slot); zero_acc256(acc); }
;     ...
;     G_BAR; G_WAIT_L(0); G_MMA(0, 1, At, B1); G_BAR;
;     G_LDA(At, 1, 1); G_STAGE(G_SA(1, 0), A, oa0, oa1, LDA, 0, KA(tt + 3));
;     G_BAR; G_WAIT_L(0); G_MMA(1, 0, At, B0); G_BAR; G_SCHED;
;     G_STAGE(G_SB(1, 1), B, ob0, ob1, LDB, 128, KB(tt + 3));
;     G_WAIT_V(6); G_BAR; G_MMA(1, 1, At, B1); G_BAR;
;     if (MODE && ((tt + 1) & 3) == 3) br_flush(p, acc, (tt + 1) >> 2);
;   }
;   {
;     G_LDB(B0, 0, 0); G_LDA(At, 0, 0); G_STAGE(G_SA(1, 1), A, oa0, oa1, LDA, 128, KA(nt - 1));
;     G_BAR; G_WAIT_L(0); G_MMA(0, 0, At, B0); G_BAR;
	s_waitcnt lgkmcnt(0)
	v_mfma_f32_16x16x32_bf16 v[120:123], v[140:143], v[100:103], v[120:123]
	v_mfma_f32_16x16x32_bf16 v[38:41], v[140:143], v[218:221], v[40:43]
	v_mfma_f32_16x16x32_bf16 v[42:45], v[148:151], v[100:103], v[44:47]
	v_mfma_f32_16x16x32_bf16 v[46:49], v[148:151], v[218:221], v[48:51]
	v_mfma_f32_16x16x32_bf16 v[50:53], v[198:201], v[100:103], v[52:55]
	v_mfma_f32_16x16x32_bf16 v[54:57], v[198:201], v[218:221], v[56:59]
	v_mfma_f32_16x16x32_bf16 v[58:61], v[206:209], v[100:103], v[60:63]
	v_mfma_f32_16x16x32_bf16 v[62:65], v[206:209], v[218:221], v[64:67]
	v_mfma_f32_16x16x32_bf16 v[120:123], v[144:147], v[214:217], v[120:123]
	v_mfma_f32_16x16x32_bf16 v[38:41], v[144:147], v[222:225], v[38:41]
	v_mfma_f32_16x16x32_bf16 v[42:45], v[194:197], v[214:217], v[42:45]
	v_mfma_f32_16x16x32_bf16 v[46:49], v[194:197], v[222:225], v[46:49]
	v_mfma_f32_16x16x32_bf16 v[50:53], v[202:205], v[214:217], v[50:53]
	v_mfma_f32_16x16x32_bf16 v[54:57], v[202:205], v[222:225], v[54:57]
	v_mfma_f32_16x16x32_bf16 v[58:61], v[210:213], v[214:217], v[58:61]
	v_mfma_f32_16x16x32_bf16 v[62:65], v[210:213], v[222:225], v[62:65]
	s_mov_b32 m0, s21
	s_barrier
	ds_read_b128 v[140:143], v242 offset:49152
	ds_read_b128 v[144:147], v242 offset:50176
	ds_read_b128 v[148:151], v242 offset:51200
	ds_read_b128 v[194:197], v242 offset:52224
	ds_read_b128 v[198:201], v242 offset:53248
	ds_read_b128 v[202:205], v242 offset:54272
	ds_read_b128 v[206:209], v242 offset:55296
	ds_read_b128 v[210:213], v242 offset:56320
	global_load_lds_dwordx4 v[12:13], off
	s_mov_b32 m0, s26
	s_nop 0
	global_load_lds_dwordx4 v[10:11], off
	s_barrier
	s_waitcnt lgkmcnt(0)
	v_mfma_f32_16x16x32_bf16 v[10:13], v[140:143], v[112:115], v[152:155]
	v_mfma_f32_16x16x32_bf16 v[22:25], v[206:209], v[112:115], v[22:25]
	v_mfma_f32_16x16x32_bf16 v[26:29], v[206:209], v[132:135], v[26:29]
	v_mfma_f32_16x16x32_bf16 v[10:13], v[144:147], v[116:119], v[10:13]
	v_mfma_f32_16x16x32_bf16 v[152:155], v[140:143], v[132:135], v[156:159]
	v_mfma_f32_16x16x32_bf16 v[156:159], v[148:151], v[112:115], v[164:167]
	v_mfma_f32_16x16x32_bf16 v[164:167], v[148:151], v[132:135], v[182:185]
	v_mfma_f32_16x16x32_bf16 v[182:185], v[198:201], v[112:115], v[186:189]
	v_mfma_f32_16x16x32_bf16 v[186:189], v[198:201], v[132:135], v[190:193]
	v_mfma_f32_16x16x32_bf16 v[22:25], v[210:213], v[116:119], v[22:25]
	v_mfma_f32_16x16x32_bf16 v[26:29], v[210:213], v[136:139], v[26:29]
	v_mfma_f32_16x16x32_bf16 v[152:155], v[144:147], v[136:139], v[152:155]
	v_mfma_f32_16x16x32_bf16 v[156:159], v[194:197], v[116:119], v[156:159]
	v_mfma_f32_16x16x32_bf16 v[164:167], v[194:197], v[136:139], v[164:167]
	v_mfma_f32_16x16x32_bf16 v[182:185], v[202:205], v[116:119], v[182:185]
	v_mfma_f32_16x16x32_bf16 v[186:189], v[202:205], v[136:139], v[186:189]
	s_barrier
	s_mov_b32 m0, s15
	s_nop 0
	global_load_lds_dwordx4 v[8:9], off
	s_mov_b32 m0, s20
	s_nop 0
	global_load_lds_dwordx4 v[6:7], off
	s_waitcnt vmcnt(6)
	s_barrier
	v_mfma_f32_16x16x32_bf16 v[6:9], v[140:143], v[100:103], v[18:21]
	v_mfma_f32_16x16x32_bf16 v[18:21], v[140:143], v[218:221], v[30:33]
	v_mfma_f32_16x16x32_bf16 v[30:33], v[148:151], v[100:103], v[34:37]
	v_mfma_f32_16x16x32_bf16 v[34:37], v[148:151], v[218:221], v[68:71]
	v_mfma_f32_16x16x32_bf16 v[66:69], v[198:201], v[100:103], v[124:127]
	v_mfma_f32_16x16x32_bf16 v[112:115], v[198:201], v[218:221], v[128:131]
	v_mfma_f32_16x16x32_bf16 v[100:103], v[206:209], v[100:103], v[104:107]
	v_mfma_f32_16x16x32_bf16 v[104:107], v[206:209], v[218:221], v[108:111]
	v_mfma_f32_16x16x32_bf16 v[6:9], v[144:147], v[214:217], v[6:9]
	v_mfma_f32_16x16x32_bf16 v[18:21], v[144:147], v[222:225], v[18:21]
	v_mfma_f32_16x16x32_bf16 v[30:33], v[194:197], v[214:217], v[30:33]
	v_mfma_f32_16x16x32_bf16 v[34:37], v[194:197], v[222:225], v[34:37]
	v_mfma_f32_16x16x32_bf16 v[66:69], v[202:205], v[214:217], v[66:69]
	v_mfma_f32_16x16x32_bf16 v[112:115], v[202:205], v[222:225], v[112:115]
	v_mfma_f32_16x16x32_bf16 v[100:103], v[210:213], v[214:217], v[100:103]
	v_mfma_f32_16x16x32_bf16 v[104:107], v[210:213], v[222:225], v[104:107]
	s_add_u32 s0, s16, 0x10180
	s_addc_u32 s1, s17, 0
	s_mov_b32 m0, s19
	v_lshl_add_u64 v[2:3], s[0:1], 0, v[2:3]
	s_barrier
	ds_read_b128 v[108:111], v230
	ds_read_b128 v[116:119], v231
	ds_read_b128 v[124:127], v232
	ds_read_b128 v[128:131], v233
	ds_read_b128 v[132:135], v242
	ds_read_b128 v[136:139], v242 offset:1024
	ds_read_b128 v[140:143], v242 offset:2048
	ds_read_b128 v[144:147], v242 offset:3072
	ds_read_b128 v[148:151], v242 offset:4096
	ds_read_b128 v[190:193], v242 offset:5120
	ds_read_b128 v[194:197], v242 offset:6144
	ds_read_b128 v[198:201], v242 offset:7168
	global_load_lds_dwordx4 v[2:3], off
	v_lshl_add_u64 v[2:3], s[0:1], 0, v[4:5]
	s_mov_b32 m0, s18
	s_nop 0
	global_load_lds_dwordx4 v[2:3], off
	s_barrier
	s_waitcnt lgkmcnt(0)
	v_mfma_f32_16x16x32_bf16 v[2:5], v[132:135], v[108:111], v[14:17]
	v_mfma_f32_16x16x32_bf16 v[14:17], v[132:135], v[124:127], v[72:75]
	v_mfma_f32_16x16x32_bf16 v[70:73], v[140:143], v[108:111], v[76:79]
	v_mfma_f32_16x16x32_bf16 v[74:77], v[140:143], v[124:127], v[80:83]
	v_mfma_f32_16x16x32_bf16 v[78:81], v[148:151], v[108:111], v[84:87]
	v_mfma_f32_16x16x32_bf16 v[82:85], v[148:151], v[124:127], v[88:91]
	v_mfma_f32_16x16x32_bf16 v[86:89], v[194:197], v[108:111], v[92:95]
	v_mfma_f32_16x16x32_bf16 v[90:93], v[194:197], v[124:127], v[96:99]
	v_mfma_f32_16x16x32_bf16 v[2:5], v[136:139], v[116:119], v[2:5]
	v_mfma_f32_16x16x32_bf16 v[14:17], v[136:139], v[128:131], v[14:17]
	v_mfma_f32_16x16x32_bf16 v[70:73], v[144:147], v[116:119], v[70:73]
	v_mfma_f32_16x16x32_bf16 v[74:77], v[144:147], v[128:131], v[74:77]
	v_mfma_f32_16x16x32_bf16 v[78:81], v[190:193], v[116:119], v[78:81]
	v_mfma_f32_16x16x32_bf16 v[82:85], v[190:193], v[128:131], v[82:85]
	v_mfma_f32_16x16x32_bf16 v[86:89], v[198:201], v[116:119], v[86:89]
	v_mfma_f32_16x16x32_bf16 v[90:93], v[198:201], v[128:131], v[90:93]
	s_barrier
; #define G_LDA(dst, b, h)                                                                                                  \
;   _Pragma("unroll") for (int m = 0; m < 4; ++m) _Pragma("unroll") for (int k = 0; k < 2; ++k)                             \
;       dst[m][k] = *(const bf16x8*)((const char*)G_SA(b, h) + ((wr * 4 + m) * 2 + k) * 1024 + rdo)
; #define G_LDB(dst, b, h)                                                                                                  \
;   _Pragma("unroll") for (int n = 0; n < 2; ++n) _Pragma("unroll") for (int k = 0; k < 2; ++k)                             \
;       dst[n][k] = *(const bf16x8*)((const char*)G_SB(b, h) + ((wc * 2 + n) * 2 + k) * 1024 + rdo)
; #define G_WAIT_V(n) asm volatile("s_waitcnt vmcnt(" #n ")" ::: "memory")
; #define G_WAIT_L(n) asm volatile("s_waitcnt lgkmcnt(" #n ")" ::: "memory")
; #define G_BAR __builtin_amdgcn_s_barrier()
;     ...
;     G_LDB(B1, 0, 1); G_BAR; G_WAIT_L(0); G_MMA(0, 1, At, B1); G_BAR;
;     G_LDA(At, 0, 1); G_WAIT_V(4); G_BAR; G_WAIT_L(0); G_MMA(1, 0, At, B0); G_MMA(1, 1, At, B1); G_BAR;
;   }
;   {
;     G_LDB(B0, 1, 0); G_LDA(At, 1, 0); G_WAIT_V(2); G_BAR; G_WAIT_L(0); G_MMA(0, 0, At, B0); G_BAR;
	ds_read_b128 v[94:97], v234
	ds_read_b128 v[202:205], v235
	ds_read_b128 v[206:209], v236
	ds_read_b128 v[210:213], v237
	s_barrier
	s_waitcnt lgkmcnt(0)
	v_mfma_f32_16x16x32_bf16 v[38:41], v[132:135], v[206:209], v[38:41]
	v_mfma_f32_16x16x32_bf16 v[42:45], v[140:143], v[94:97], v[42:45]
	v_mfma_f32_16x16x32_bf16 v[46:49], v[140:143], v[206:209], v[46:49]
	v_mfma_f32_16x16x32_bf16 v[50:53], v[148:151], v[94:97], v[50:53]
	v_mfma_f32_16x16x32_bf16 v[54:57], v[148:151], v[206:209], v[54:57]
	v_mfma_f32_16x16x32_bf16 v[58:61], v[194:197], v[94:97], v[58:61]
	v_mfma_f32_16x16x32_bf16 v[62:65], v[194:197], v[206:209], v[62:65]
	v_mfma_f32_16x16x32_bf16 v[120:123], v[132:135], v[94:97], v[120:123]
	v_mfma_f32_16x16x32_bf16 v[38:41], v[136:139], v[210:213], v[38:41]
	v_mfma_f32_16x16x32_bf16 v[42:45], v[144:147], v[202:205], v[42:45]
	v_mfma_f32_16x16x32_bf16 v[46:49], v[144:147], v[210:213], v[46:49]
	v_mfma_f32_16x16x32_bf16 v[50:53], v[190:193], v[202:205], v[50:53]
	v_mfma_f32_16x16x32_bf16 v[54:57], v[190:193], v[210:213], v[54:57]
	v_mfma_f32_16x16x32_bf16 v[58:61], v[198:201], v[202:205], v[58:61]
	v_mfma_f32_16x16x32_bf16 v[62:65], v[198:201], v[210:213], v[62:65]
	v_mfma_f32_16x16x32_bf16 v[214:217], v[136:139], v[202:205], v[120:123]
	s_barrier
	s_nop 0
	ds_read_b128 v[120:123], v242 offset:16384
	ds_read_b128 v[132:135], v242 offset:17408
	ds_read_b128 v[136:139], v242 offset:18432
	ds_read_b128 v[140:143], v242 offset:19456
	ds_read_b128 v[144:147], v242 offset:20480
	ds_read_b128 v[148:151], v242 offset:21504
	ds_read_b128 v[190:193], v242 offset:22528
	ds_read_b128 v[194:197], v242 offset:23552
	s_waitcnt vmcnt(4)
	s_barrier
	s_waitcnt lgkmcnt(0)
	v_mfma_f32_16x16x32_bf16 v[10:13], v[120:123], v[108:111], v[10:13]
	v_mfma_f32_16x16x32_bf16 v[22:25], v[190:193], v[108:111], v[22:25]
	v_mfma_f32_16x16x32_bf16 v[26:29], v[190:193], v[124:127], v[26:29]
	v_mfma_f32_16x16x32_bf16 v[10:13], v[132:135], v[116:119], v[10:13]
	v_mfma_f32_16x16x32_bf16 v[152:155], v[120:123], v[124:127], v[152:155]
	v_mfma_f32_16x16x32_bf16 v[156:159], v[136:139], v[108:111], v[156:159]
	v_mfma_f32_16x16x32_bf16 v[164:167], v[136:139], v[124:127], v[164:167]
	v_mfma_f32_16x16x32_bf16 v[182:185], v[144:147], v[108:111], v[182:185]
	v_mfma_f32_16x16x32_bf16 v[186:189], v[144:147], v[124:127], v[186:189]
	v_mfma_f32_16x16x32_bf16 v[22:25], v[194:197], v[116:119], v[22:25]
	v_mfma_f32_16x16x32_bf16 v[26:29], v[194:197], v[128:131], v[26:29]
	v_mfma_f32_16x16x32_bf16 v[152:155], v[132:135], v[128:131], v[152:155]
	v_mfma_f32_16x16x32_bf16 v[156:159], v[140:143], v[116:119], v[156:159]
	v_mfma_f32_16x16x32_bf16 v[164:167], v[140:143], v[128:131], v[164:167]
	v_mfma_f32_16x16x32_bf16 v[182:185], v[148:151], v[116:119], v[182:185]
	v_mfma_f32_16x16x32_bf16 v[186:189], v[148:151], v[128:131], v[186:189]
	v_mfma_f32_16x16x32_bf16 v[30:33], v[136:139], v[94:97], v[30:33]
	v_mfma_f32_16x16x32_bf16 v[6:9], v[120:123], v[94:97], v[6:9]
	v_mfma_f32_16x16x32_bf16 v[18:21], v[120:123], v[206:209], v[18:21]
	v_mfma_f32_16x16x32_bf16 v[118:121], v[140:143], v[202:205], v[30:33]
	v_mfma_f32_16x16x32_bf16 v[30:33], v[136:139], v[206:209], v[34:37]
	v_mfma_f32_16x16x32_bf16 v[138:141], v[140:143], v[210:213], v[30:33]
	v_mfma_f32_16x16x32_bf16 v[30:33], v[144:147], v[94:97], v[66:69]
	v_mfma_f32_16x16x32_bf16 v[198:201], v[148:151], v[202:205], v[30:33]
	v_mfma_f32_16x16x32_bf16 v[30:33], v[144:147], v[206:209], v[112:115]
	v_mfma_f32_16x16x32_bf16 v[142:145], v[148:151], v[210:213], v[30:33]
	v_mfma_f32_16x16x32_bf16 v[30:33], v[190:193], v[94:97], v[100:103]
	v_mfma_f32_16x16x32_bf16 v[6:9], v[132:135], v[202:205], v[6:9]
	v_mfma_f32_16x16x32_bf16 v[18:21], v[132:135], v[210:213], v[18:21]
	v_mfma_f32_16x16x32_bf16 v[98:101], v[194:197], v[202:205], v[30:33]
	v_mfma_f32_16x16x32_bf16 v[30:33], v[190:193], v[206:209], v[104:107]
	v_mfma_f32_16x16x32_bf16 v[146:149], v[194:197], v[210:213], v[30:33]
	s_barrier
	s_nop 4
	s_nop 0
	ds_read_b128 v[30:33], v160
	ds_read_b128 v[34:37], v161
	ds_read_b128 v[190:193], v238
	ds_read_b128 v[194:197], v239
	ds_read_b128 v[66:69], v242 offset:32768
	ds_read_b128 v[94:97], v242 offset:33792
	ds_read_b128 v[202:205], v242 offset:34816
	ds_read_b128 v[206:209], v242 offset:35840
	ds_read_b128 v[210:213], v242 offset:36864
	ds_read_b128 v[218:221], v242 offset:37888
	ds_read_b128 v[222:225], v242 offset:38912
	ds_read_b128 v[226:229], v242 offset:39936
	s_waitcnt vmcnt(2)
	s_barrier
; #define G_LDA(dst, b, h)                                                                                                  \
;   _Pragma("unroll") for (int m = 0; m < 4; ++m) _Pragma("unroll") for (int k = 0; k < 2; ++k)                             \
;       dst[m][k] = *(const bf16x8*)((const char*)G_SA(b, h) + ((wr * 4 + m) * 2 + k) * 1024 + rdo)
; #define G_LDB(dst, b, h)                                                                                                  \
;   _Pragma("unroll") for (int n = 0; n < 2; ++n) _Pragma("unroll") for (int k = 0; k < 2; ++k)                             \
;       dst[n][k] = *(const bf16x8*)((const char*)G_SB(b, h) + ((wc * 2 + n) * 2 + k) * 1024 + rdo)
; #define G_WAIT_V(n) asm volatile("s_waitcnt vmcnt(" #n ")" ::: "memory")
; #define G_WAIT_L(n) asm volatile("s_waitcnt lgkmcnt(" #n ")" ::: "memory")
; #define G_BAR __builtin_amdgcn_s_barrier()
;     ...
;     G_LDB(B0, 1, 0); G_LDA(At, 1, 0); G_WAIT_V(2); G_BAR; G_WAIT_L(0); G_MMA(0, 0, At, B0); G_BAR;
;     G_LDB(B1, 1, 1); G_WAIT_V(0); G_BAR; G_WAIT_L(0); G_MMA(0, 1, At, B1); G_BAR;
;     G_LDA(At, 1, 1); G_BAR; G_WAIT_L(0); G_MMA(1, 0, At, B0); G_MMA(1, 1, At, B1); G_BAR;
;   }
;   if (wr == 0) G_BAR;
	s_waitcnt lgkmcnt(0)
	v_mfma_f32_16x16x32_bf16 v[2:5], v[66:69], v[30:33], v[2:5]
	v_mfma_f32_16x16x32_bf16 v[126:129], v[94:97], v[34:37], v[2:5]
	v_mfma_f32_16x16x32_bf16 v[2:5], v[66:69], v[190:193], v[14:17]
	v_mfma_f32_16x16x32_bf16 v[134:137], v[94:97], v[194:197], v[2:5]
	v_mfma_f32_16x16x32_bf16 v[2:5], v[202:205], v[30:33], v[70:73]
	v_mfma_f32_16x16x32_bf16 v[122:125], v[206:209], v[34:37], v[2:5]
	v_mfma_f32_16x16x32_bf16 v[2:5], v[202:205], v[190:193], v[74:77]
	v_mfma_f32_16x16x32_bf16 v[130:133], v[206:209], v[194:197], v[2:5]
	v_mfma_f32_16x16x32_bf16 v[2:5], v[210:213], v[30:33], v[78:81]
	v_mfma_f32_16x16x32_bf16 v[110:113], v[218:221], v[34:37], v[2:5]
	v_mfma_f32_16x16x32_bf16 v[2:5], v[210:213], v[190:193], v[82:85]
	v_mfma_f32_16x16x32_bf16 v[114:117], v[218:221], v[194:197], v[2:5]
	v_mfma_f32_16x16x32_bf16 v[2:5], v[222:225], v[30:33], v[86:89]
	v_mfma_f32_16x16x32_bf16 v[102:105], v[226:229], v[34:37], v[2:5]
	v_mfma_f32_16x16x32_bf16 v[2:5], v[222:225], v[190:193], v[90:93]
	v_mfma_f32_16x16x32_bf16 v[106:109], v[226:229], v[194:197], v[2:5]
	s_barrier
	s_nop 4
	s_nop 0
	ds_read_b128 v[2:5], v240
	ds_read_b128 v[230:233], v241
	ds_read_b128 v[234:237], v243
	ds_read_b128 v[238:241], v162
	s_waitcnt vmcnt(0)
	s_barrier
	s_waitcnt lgkmcnt(0)
	v_mfma_f32_16x16x32_bf16 v[14:17], v[66:69], v[2:5], v[214:217]
	v_mfma_f32_16x16x32_bf16 v[86:89], v[94:97], v[230:233], v[14:17]
	v_mfma_f32_16x16x32_bf16 v[14:17], v[66:69], v[234:237], v[38:41]
	v_mfma_f32_16x16x32_bf16 v[94:97], v[94:97], v[238:241], v[14:17]
	v_mfma_f32_16x16x32_bf16 v[14:17], v[202:205], v[2:5], v[42:45]
	v_mfma_f32_16x16x32_bf16 v[82:85], v[206:209], v[230:233], v[14:17]
	v_mfma_f32_16x16x32_bf16 v[14:17], v[202:205], v[234:237], v[46:49]
	v_mfma_f32_16x16x32_bf16 v[90:93], v[206:209], v[238:241], v[14:17]
	v_mfma_f32_16x16x32_bf16 v[14:17], v[210:213], v[2:5], v[50:53]
	v_mfma_f32_16x16x32_bf16 v[74:77], v[218:221], v[230:233], v[14:17]
	v_mfma_f32_16x16x32_bf16 v[14:17], v[210:213], v[234:237], v[54:57]
	v_mfma_f32_16x16x32_bf16 v[78:81], v[218:221], v[238:241], v[14:17]
	v_mfma_f32_16x16x32_bf16 v[14:17], v[222:225], v[2:5], v[58:61]
	v_mfma_f32_16x16x32_bf16 v[66:69], v[226:229], v[230:233], v[14:17]
	v_mfma_f32_16x16x32_bf16 v[14:17], v[222:225], v[234:237], v[62:65]
	v_mfma_f32_16x16x32_bf16 v[70:73], v[226:229], v[238:241], v[14:17]
	s_barrier
	s_nop 4
	s_nop 0
	ds_read_b128 v[14:17], v242 offset:49152
	ds_read_b128 v[202:205], v242 offset:50176
	ds_read_b128 v[206:209], v242 offset:51200
	ds_read_b128 v[210:213], v242 offset:52224
	ds_read_b128 v[214:217], v242 offset:53248
	ds_read_b128 v[218:221], v242 offset:54272
	ds_read_b128 v[222:225], v242 offset:55296
	ds_read_b128 v[226:229], v242 offset:56320
	s_barrier
	s_waitcnt lgkmcnt(0)
	v_mfma_f32_16x16x32_bf16 v[10:13], v[14:17], v[30:33], v[10:13]
	v_mfma_f32_16x16x32_bf16 v[54:57], v[202:205], v[34:37], v[10:13]
	v_mfma_f32_16x16x32_bf16 v[10:13], v[14:17], v[190:193], v[152:155]
	v_mfma_f32_16x16x32_bf16 v[62:65], v[202:205], v[194:197], v[10:13]
	v_mfma_f32_16x16x32_bf16 v[10:13], v[206:209], v[30:33], v[156:159]
	v_mfma_f32_16x16x32_bf16 v[50:53], v[210:213], v[34:37], v[10:13]
	v_mfma_f32_16x16x32_bf16 v[10:13], v[206:209], v[190:193], v[164:167]
	v_mfma_f32_16x16x32_bf16 v[58:61], v[210:213], v[194:197], v[10:13]
	v_mfma_f32_16x16x32_bf16 v[10:13], v[214:217], v[30:33], v[182:185]
	v_mfma_f32_16x16x32_bf16 v[42:45], v[218:221], v[34:37], v[10:13]
	v_mfma_f32_16x16x32_bf16 v[10:13], v[214:217], v[190:193], v[186:189]
	v_mfma_f32_16x16x32_bf16 v[46:49], v[218:221], v[194:197], v[10:13]
	v_mfma_f32_16x16x32_bf16 v[10:13], v[222:225], v[30:33], v[22:25]
	v_mfma_f32_16x16x32_bf16 v[34:37], v[226:229], v[34:37], v[10:13]
	v_mfma_f32_16x16x32_bf16 v[10:13], v[222:225], v[190:193], v[26:29]
	v_mfma_f32_16x16x32_bf16 v[38:41], v[226:229], v[194:197], v[10:13]
	v_mfma_f32_16x16x32_bf16 v[6:9], v[14:17], v[2:5], v[6:9]
	v_mfma_f32_16x16x32_bf16 v[22:25], v[202:205], v[230:233], v[6:9]
	v_mfma_f32_16x16x32_bf16 v[6:9], v[14:17], v[234:237], v[18:21]
	v_mfma_f32_16x16x32_bf16 v[30:33], v[202:205], v[238:241], v[6:9]
	v_mfma_f32_16x16x32_bf16 v[6:9], v[206:209], v[2:5], v[118:121]
	v_mfma_f32_16x16x32_bf16 v[18:21], v[210:213], v[230:233], v[6:9]
	v_mfma_f32_16x16x32_bf16 v[6:9], v[206:209], v[234:237], v[138:141]
	v_mfma_f32_16x16x32_bf16 v[26:29], v[210:213], v[238:241], v[6:9]
	v_mfma_f32_16x16x32_bf16 v[6:9], v[214:217], v[2:5], v[198:201]
	v_mfma_f32_16x16x32_bf16 v[10:13], v[218:221], v[230:233], v[6:9]
	v_mfma_f32_16x16x32_bf16 v[6:9], v[214:217], v[234:237], v[142:145]
	v_mfma_f32_16x16x32_bf16 v[14:17], v[218:221], v[238:241], v[6:9]
	v_mfma_f32_16x16x32_bf16 v[2:5], v[222:225], v[2:5], v[98:101]
	v_mfma_f32_16x16x32_bf16 v[6:9], v[222:225], v[234:237], v[146:149]
	v_mfma_f32_16x16x32_bf16 v[2:5], v[226:229], v[230:233], v[2:5]
	v_mfma_f32_16x16x32_bf16 v[6:9], v[226:229], v[238:241], v[6:9]
	v_cmp_gt_u32_e32 vcc, s67, v0
	s_barrier
	s_and_saveexec_b64 s[16:17], vcc
	s_cbranch_execz .LBB0_214
	s_barrier
	s_branch .LBB0_214

; #define G_LDA(dst, b, h)                                                                                                  \
;   _Pragma("unroll") for (int m = 0; m < 4; ++m) _Pragma("unroll") for (int k = 0; k < 2; ++k)                             \
;       dst[m][k] = *(const bf16x8*)((const char*)G_SA(b, h) + ((wr * 4 + m) * 2 + k) * 1024 + rdo)
; #define G_LDB(dst, b, h)                                                                                                  \
;   _Pragma("unroll") for (int n = 0; n < 2; ++n) _Pragma("unroll") for (int k = 0; k < 2; ++k)                             \
;       dst[n][k] = *(const bf16x8*)((const char*)G_SB(b, h) + ((wc * 2 + n) * 2 + k) * 1024 + rdo)
; #define G_WAIT_L(n) asm volatile("s_waitcnt lgkmcnt(" #n ")" ::: "memory")
; #define G_BAR __builtin_amdgcn_s_barrier()
; #define G_SCHED __builtin_amdgcn_sched_barrier(0)
;     ...
;   for (int tt = 0; tt < nt - 2; tt += 2) {
;     G_LDB(B0, 0, 0); G_SCHED; G_LDA(At, 0, 0); G_STAGE(G_SA(1, 1), A, oa0, oa1, LDA, 128, KA(tt + 1));
;     G_WAIT_L(8); G_BAR; G_WAIT_L(0); G_MMA(0, 0, At, B0); G_BAR; G_SCHED;
;     G_LDB(B1, 0, 1); G_STAGE(G_SB(0, 0), B, ob0, ob1, LDB, 0, KB(tt + 2));
;     G_BAR; G_WAIT_L(0); G_MMA(0, 1, At, B1); G_BAR;
;     G_LDA(At, 0, 1); G_STAGE(G_SA(0, 0), A, oa0, oa1, LDA, 0, KA(tt + 2));
;     G_BAR; G_WAIT_L(0); G_MMA(1, 0, At, B0); G_BAR; G_SCHED;
.LBB0_453:
	ds_read_b128 v[182:185], v161
	ds_read_b128 v[186:189], v161 offset:1024
	ds_read_b128 v[190:193], v161 offset:2048
	ds_read_b128 v[194:197], v161 offset:3072
	v_add_u32_e32 v162, 0xc000, v144
	v_lshl_add_u64 v[166:167], v[136:137], 0, s[20:21]
	v_readfirstlane_b32 s0, v162
	v_lshl_add_u64 v[164:165], v[166:167], 0, s[78:79]
	s_mov_b32 m0, s0
	ds_read_b128 v[198:201], v143
	ds_read_b128 v[202:205], v143 offset:1024
	ds_read_b128 v[206:209], v143 offset:2048
	ds_read_b128 v[210:213], v143 offset:3072
	ds_read_b128 v[214:217], v143 offset:4096
	ds_read_b128 v[218:221], v143 offset:5120
	ds_read_b128 v[222:225], v143 offset:6144
	ds_read_b128 v[226:229], v143 offset:7168
	global_load_lds_dwordx4 v[164:165], off
	v_add_u32_e32 v164, 0xe000, v144
	v_lshl_add_u64 v[246:247], v[134:135], 0, s[20:21]
	v_readfirstlane_b32 s0, v164
	v_lshl_add_u64 v[230:231], v[246:247], 0, s[78:79]
	s_mov_b32 m0, s0
	s_nop 0
	global_load_lds_dwordx4 v[230:231], off
	s_waitcnt lgkmcnt(8)
	s_barrier
	s_waitcnt lgkmcnt(0)
	v_mfma_f32_16x16x32_bf16 v[126:129], v[198:201], v[182:185], v[126:129]
	v_mfma_f32_16x16x32_bf16 v[122:125], v[198:201], v[190:193], v[122:125]
	v_mfma_f32_16x16x32_bf16 v[118:121], v[206:209], v[182:185], v[118:121]
	v_mfma_f32_16x16x32_bf16 v[114:117], v[206:209], v[190:193], v[114:117]
	v_mfma_f32_16x16x32_bf16 v[110:113], v[214:217], v[182:185], v[110:113]
	v_mfma_f32_16x16x32_bf16 v[106:109], v[214:217], v[190:193], v[106:109]
	v_mfma_f32_16x16x32_bf16 v[102:105], v[222:225], v[182:185], v[102:105]
	v_mfma_f32_16x16x32_bf16 v[98:101], v[222:225], v[190:193], v[98:101]
	v_mfma_f32_16x16x32_bf16 v[126:129], v[202:205], v[186:189], v[126:129]
	v_mfma_f32_16x16x32_bf16 v[122:125], v[202:205], v[194:197], v[122:125]
	v_mfma_f32_16x16x32_bf16 v[118:121], v[210:213], v[186:189], v[118:121]
	v_mfma_f32_16x16x32_bf16 v[114:117], v[210:213], v[194:197], v[114:117]
	v_mfma_f32_16x16x32_bf16 v[110:113], v[218:221], v[186:189], v[110:113]
	v_mfma_f32_16x16x32_bf16 v[106:109], v[218:221], v[194:197], v[106:109]
	v_mfma_f32_16x16x32_bf16 v[102:105], v[226:229], v[186:189], v[102:105]
	v_mfma_f32_16x16x32_bf16 v[98:101], v[226:229], v[194:197], v[98:101]
	s_barrier
	v_lshl_add_u64 v[248:249], v[140:141], 0, s[20:21]
	v_readfirstlane_b32 s0, v147
	v_lshl_add_u64 v[250:251], v[248:249], 0, s[82:83]
	s_mov_b32 m0, s0
	ds_read_b128 v[230:233], v159
	ds_read_b128 v[234:237], v159 offset:1024
	ds_read_b128 v[238:241], v159 offset:2048
	ds_read_b128 v[242:245], v159 offset:3072
	global_load_lds_dwordx4 v[250:251], off
	v_lshl_add_u64 v[250:251], v[138:139], 0, s[20:21]
	v_readfirstlane_b32 s0, v148
	v_lshl_add_u64 v[252:253], v[250:251], 0, s[82:83]
	s_mov_b32 m0, s0
	s_nop 0
	global_load_lds_dwordx4 v[252:253], off
	s_barrier
	s_waitcnt lgkmcnt(0)
	v_mfma_f32_16x16x32_bf16 v[94:97], v[198:201], v[230:233], v[94:97]
	v_mfma_f32_16x16x32_bf16 v[86:89], v[198:201], v[238:241], v[86:89]
	v_mfma_f32_16x16x32_bf16 v[70:73], v[206:209], v[230:233], v[70:73]
	v_mfma_f32_16x16x32_bf16 v[58:61], v[206:209], v[238:241], v[58:61]
	v_mfma_f32_16x16x32_bf16 v[54:57], v[214:217], v[230:233], v[54:57]
	v_mfma_f32_16x16x32_bf16 v[50:53], v[214:217], v[238:241], v[50:53]
	v_mfma_f32_16x16x32_bf16 v[46:49], v[222:225], v[230:233], v[46:49]
	v_mfma_f32_16x16x32_bf16 v[42:45], v[222:225], v[238:241], v[42:45]
	v_mfma_f32_16x16x32_bf16 v[94:97], v[202:205], v[234:237], v[94:97]
	v_mfma_f32_16x16x32_bf16 v[86:89], v[202:205], v[242:245], v[86:89]
	v_mfma_f32_16x16x32_bf16 v[70:73], v[210:213], v[234:237], v[70:73]
	v_mfma_f32_16x16x32_bf16 v[58:61], v[210:213], v[242:245], v[58:61]
	v_mfma_f32_16x16x32_bf16 v[54:57], v[218:221], v[234:237], v[54:57]
	v_mfma_f32_16x16x32_bf16 v[50:53], v[218:221], v[242:245], v[50:53]
	v_mfma_f32_16x16x32_bf16 v[46:49], v[226:229], v[234:237], v[46:49]
	v_mfma_f32_16x16x32_bf16 v[42:45], v[226:229], v[242:245], v[42:45]
	v_readfirstlane_b32 s0, v144
	v_lshl_add_u64 v[252:253], v[166:167], 0, s[82:83]
	s_mov_b32 m0, s0
	v_readfirstlane_b32 s0, v145
	s_barrier
	ds_read_b128 v[198:201], v143 offset:16384
	ds_read_b128 v[202:205], v143 offset:17408
	ds_read_b128 v[206:209], v143 offset:18432
	ds_read_b128 v[210:213], v143 offset:19456
	ds_read_b128 v[214:217], v143 offset:20480
	ds_read_b128 v[218:221], v143 offset:21504
	ds_read_b128 v[222:225], v143 offset:22528
	ds_read_b128 v[226:229], v143 offset:23552
	global_load_lds_dwordx4 v[252:253], off
	v_lshl_add_u64 v[252:253], v[246:247], 0, s[82:83]
	s_mov_b32 m0, s0
	s_nop 0
	global_load_lds_dwordx4 v[252:253], off
	s_barrier
	s_waitcnt lgkmcnt(0)
	v_mfma_f32_16x16x32_bf16 v[38:41], v[198:201], v[182:185], v[38:41]
	v_mfma_f32_16x16x32_bf16 v[34:37], v[198:201], v[190:193], v[34:37]
	v_mfma_f32_16x16x32_bf16 v[30:33], v[206:209], v[182:185], v[30:33]
	v_mfma_f32_16x16x32_bf16 v[26:29], v[206:209], v[190:193], v[26:29]
	v_mfma_f32_16x16x32_bf16 v[22:25], v[214:217], v[182:185], v[22:25]
	v_mfma_f32_16x16x32_bf16 v[18:21], v[214:217], v[190:193], v[18:21]
	v_mfma_f32_16x16x32_bf16 v[14:17], v[222:225], v[182:185], v[14:17]
	v_mfma_f32_16x16x32_bf16 v[10:13], v[222:225], v[190:193], v[10:13]
	v_mfma_f32_16x16x32_bf16 v[38:41], v[202:205], v[186:189], v[38:41]
	v_mfma_f32_16x16x32_bf16 v[34:37], v[202:205], v[194:197], v[34:37]
	v_mfma_f32_16x16x32_bf16 v[30:33], v[210:213], v[186:189], v[30:33]
	v_mfma_f32_16x16x32_bf16 v[26:29], v[210:213], v[194:197], v[26:29]
	v_mfma_f32_16x16x32_bf16 v[22:25], v[218:221], v[186:189], v[22:25]
	v_mfma_f32_16x16x32_bf16 v[18:21], v[218:221], v[194:197], v[18:21]
	v_mfma_f32_16x16x32_bf16 v[14:17], v[226:229], v[186:189], v[14:17]
	v_mfma_f32_16x16x32_bf16 v[10:13], v[226:229], v[194:197], v[10:13]
	s_barrier
; #define G_LDA(dst, b, h)                                                                                                  \
;   _Pragma("unroll") for (int m = 0; m < 4; ++m) _Pragma("unroll") for (int k = 0; k < 2; ++k)                             \
;       dst[m][k] = *(const bf16x8*)((const char*)G_SA(b, h) + ((wr * 4 + m) * 2 + k) * 1024 + rdo)
; #define G_LDB(dst, b, h)                                                                                                  \
;   _Pragma("unroll") for (int n = 0; n < 2; ++n) _Pragma("unroll") for (int k = 0; k < 2; ++k)                             \
;       dst[n][k] = *(const bf16x8*)((const char*)G_SB(b, h) + ((wc * 2 + n) * 2 + k) * 1024 + rdo)
; #define G_WAIT_V(n) asm volatile("s_waitcnt vmcnt(" #n ")" ::: "memory")
; #define G_WAIT_L(n) asm volatile("s_waitcnt lgkmcnt(" #n ")" ::: "memory")
; #define G_BAR __builtin_amdgcn_s_barrier()
; #define G_SCHED __builtin_amdgcn_sched_barrier(0)
;     ...
;     G_STAGE(G_SB(0, 1), B, ob0, ob1, LDB, 128, KB(tt + 2));
;     G_WAIT_V(6); G_BAR; G_MMA(1, 1, At, B1); G_BAR;
;     G_LDB(B0, 1, 0); G_SCHED; G_LDA(At, 1, 0); G_STAGE(G_SA(0, 1), A, oa0, oa1, LDA, 128, KA(tt + 2));
;     G_WAIT_L(8); G_BAR; G_WAIT_L(0); G_MMA(0, 0, At, B0); G_BAR; G_SCHED;
;     G_LDB(B1, 1, 1); G_STAGE(G_SB(1, 0), B, ob0, ob1, LDB, 0, KB(tt + 3));
;     G_BAR; G_WAIT_L(0); G_MMA(0, 1, At, B1); G_BAR;
;     G_LDA(At, 1, 1); G_STAGE(G_SA(1, 0), A, oa0, oa1, LDA, 0, KA(tt + 3));
	v_readfirstlane_b32 s0, v149
	v_lshl_add_u64 v[182:183], v[248:249], 0, s[86:87]
	s_mov_b32 m0, s0
	v_readfirstlane_b32 s0, v151
	global_load_lds_dwordx4 v[182:183], off
	v_lshl_add_u64 v[182:183], v[250:251], 0, s[86:87]
	s_mov_b32 m0, s0
	s_nop 0
	global_load_lds_dwordx4 v[182:183], off
	s_waitcnt vmcnt(6)
	s_barrier
	v_mfma_f32_16x16x32_bf16 v[6:9], v[198:201], v[230:233], v[6:9]
	v_mfma_f32_16x16x32_bf16 v[2:5], v[198:201], v[238:241], v[2:5]
	v_mfma_f32_16x16x32_bf16 v[62:65], v[206:209], v[230:233], v[62:65]
	v_mfma_f32_16x16x32_bf16 v[66:69], v[206:209], v[238:241], v[66:69]
	v_mfma_f32_16x16x32_bf16 v[74:77], v[214:217], v[230:233], v[74:77]
	v_mfma_f32_16x16x32_bf16 v[78:81], v[214:217], v[238:241], v[78:81]
	v_mfma_f32_16x16x32_bf16 v[82:85], v[222:225], v[230:233], v[82:85]
	v_mfma_f32_16x16x32_bf16 v[90:93], v[222:225], v[238:241], v[90:93]
	v_mfma_f32_16x16x32_bf16 v[6:9], v[202:205], v[234:237], v[6:9]
	v_mfma_f32_16x16x32_bf16 v[2:5], v[202:205], v[242:245], v[2:5]
	v_mfma_f32_16x16x32_bf16 v[62:65], v[210:213], v[234:237], v[62:65]
	v_mfma_f32_16x16x32_bf16 v[66:69], v[210:213], v[242:245], v[66:69]
	v_mfma_f32_16x16x32_bf16 v[74:77], v[218:221], v[234:237], v[74:77]
	v_mfma_f32_16x16x32_bf16 v[78:81], v[218:221], v[242:245], v[78:81]
	v_mfma_f32_16x16x32_bf16 v[82:85], v[226:229], v[234:237], v[82:85]
	v_mfma_f32_16x16x32_bf16 v[90:93], v[226:229], v[242:245], v[90:93]
	s_barrier
	ds_read_b128 v[182:185], v150
	ds_read_b128 v[186:189], v150 offset:1024
	ds_read_b128 v[190:193], v150 offset:2048
	ds_read_b128 v[194:197], v150 offset:3072
	v_readfirstlane_b32 s0, v152
	v_lshl_add_u64 v[230:231], v[166:167], 0, s[86:87]
	s_mov_b32 m0, s0
	v_readfirstlane_b32 s0, v153
	ds_read_b128 v[198:201], v143 offset:32768
	ds_read_b128 v[202:205], v143 offset:33792
	ds_read_b128 v[206:209], v143 offset:34816
	ds_read_b128 v[210:213], v143 offset:35840
	ds_read_b128 v[214:217], v143 offset:36864
	ds_read_b128 v[218:221], v143 offset:37888
	ds_read_b128 v[222:225], v143 offset:38912
	ds_read_b128 v[226:229], v143 offset:39936
	global_load_lds_dwordx4 v[230:231], off
	v_lshl_add_u64 v[230:231], v[246:247], 0, s[86:87]
	s_mov_b32 m0, s0
	s_nop 0
	global_load_lds_dwordx4 v[230:231], off
	s_waitcnt lgkmcnt(8)
	s_barrier
	s_waitcnt lgkmcnt(0)
	v_mfma_f32_16x16x32_bf16 v[126:129], v[198:201], v[182:185], v[126:129]
	v_mfma_f32_16x16x32_bf16 v[122:125], v[198:201], v[190:193], v[122:125]
	v_mfma_f32_16x16x32_bf16 v[118:121], v[206:209], v[182:185], v[118:121]
	v_mfma_f32_16x16x32_bf16 v[114:117], v[206:209], v[190:193], v[114:117]
	v_mfma_f32_16x16x32_bf16 v[110:113], v[214:217], v[182:185], v[110:113]
	v_mfma_f32_16x16x32_bf16 v[106:109], v[214:217], v[190:193], v[106:109]
	v_mfma_f32_16x16x32_bf16 v[102:105], v[222:225], v[182:185], v[102:105]
	v_mfma_f32_16x16x32_bf16 v[98:101], v[222:225], v[190:193], v[98:101]
	v_mfma_f32_16x16x32_bf16 v[126:129], v[202:205], v[186:189], v[126:129]
	v_mfma_f32_16x16x32_bf16 v[122:125], v[202:205], v[194:197], v[122:125]
	v_mfma_f32_16x16x32_bf16 v[118:121], v[210:213], v[186:189], v[118:121]
	v_mfma_f32_16x16x32_bf16 v[114:117], v[210:213], v[194:197], v[114:117]
	v_mfma_f32_16x16x32_bf16 v[110:113], v[218:221], v[186:189], v[110:113]
	v_mfma_f32_16x16x32_bf16 v[106:109], v[218:221], v[194:197], v[106:109]
	v_mfma_f32_16x16x32_bf16 v[102:105], v[226:229], v[186:189], v[102:105]
	v_mfma_f32_16x16x32_bf16 v[98:101], v[226:229], v[194:197], v[98:101]
	s_barrier
	v_readfirstlane_b32 s0, v154
	v_lshl_add_u64 v[252:253], v[248:249], 0, s[90:91]
	s_mov_b32 m0, s0
	v_readfirstlane_b32 s0, v155
	ds_read_b128 v[230:233], v146
	ds_read_b128 v[234:237], v146 offset:1024
	ds_read_b128 v[238:241], v146 offset:2048
	ds_read_b128 v[242:245], v146 offset:3072
	global_load_lds_dwordx4 v[252:253], off
	v_lshl_add_u64 v[252:253], v[250:251], 0, s[90:91]
	s_mov_b32 m0, s0
	s_nop 0
	global_load_lds_dwordx4 v[252:253], off
	s_barrier
	s_waitcnt lgkmcnt(0)
	v_mfma_f32_16x16x32_bf16 v[94:97], v[198:201], v[230:233], v[94:97]
	v_mfma_f32_16x16x32_bf16 v[86:89], v[198:201], v[238:241], v[86:89]
	v_mfma_f32_16x16x32_bf16 v[70:73], v[206:209], v[230:233], v[70:73]
	v_mfma_f32_16x16x32_bf16 v[58:61], v[206:209], v[238:241], v[58:61]
	v_mfma_f32_16x16x32_bf16 v[54:57], v[214:217], v[230:233], v[54:57]
	v_mfma_f32_16x16x32_bf16 v[50:53], v[214:217], v[238:241], v[50:53]
	v_mfma_f32_16x16x32_bf16 v[46:49], v[222:225], v[230:233], v[46:49]
	v_mfma_f32_16x16x32_bf16 v[42:45], v[222:225], v[238:241], v[42:45]
	v_mfma_f32_16x16x32_bf16 v[94:97], v[202:205], v[234:237], v[94:97]
	v_mfma_f32_16x16x32_bf16 v[86:89], v[202:205], v[242:245], v[86:89]
	v_mfma_f32_16x16x32_bf16 v[70:73], v[210:213], v[234:237], v[70:73]
	v_mfma_f32_16x16x32_bf16 v[58:61], v[210:213], v[242:245], v[58:61]
	v_mfma_f32_16x16x32_bf16 v[54:57], v[218:221], v[234:237], v[54:57]
	v_mfma_f32_16x16x32_bf16 v[50:53], v[218:221], v[242:245], v[50:53]
	v_mfma_f32_16x16x32_bf16 v[46:49], v[226:229], v[234:237], v[46:49]
	v_mfma_f32_16x16x32_bf16 v[42:45], v[226:229], v[242:245], v[42:45]
	v_readfirstlane_b32 s0, v156
	v_lshl_add_u64 v[166:167], v[166:167], 0, s[90:91]
	s_mov_b32 m0, s0
	v_readfirstlane_b32 s0, v157
	s_barrier
	ds_read_b128 v[198:201], v143 offset:49152
	ds_read_b128 v[202:205], v143 offset:50176
	ds_read_b128 v[206:209], v143 offset:51200
	ds_read_b128 v[210:213], v143 offset:52224
	ds_read_b128 v[214:217], v143 offset:53248
	ds_read_b128 v[218:221], v143 offset:54272
	ds_read_b128 v[222:225], v143 offset:55296
	ds_read_b128 v[226:229], v143 offset:56320
	global_load_lds_dwordx4 v[166:167], off
	v_lshl_add_u64 v[166:167], v[246:247], 0, s[90:91]
	s_mov_b32 m0, s0
	s_nop 0
	global_load_lds_dwordx4 v[166:167], off
	s_barrier
; #define G_LDA(dst, b, h)                                                                                                  \
;   _Pragma("unroll") for (int m = 0; m < 4; ++m) _Pragma("unroll") for (int k = 0; k < 2; ++k)                             \
;       dst[m][k] = *(const bf16x8*)((const char*)G_SA(b, h) + ((wr * 4 + m) * 2 + k) * 1024 + rdo)
; #define G_LDB(dst, b, h)                                                                                                  \
;   _Pragma("unroll") for (int n = 0; n < 2; ++n) _Pragma("unroll") for (int k = 0; k < 2; ++k)                             \
;       dst[n][k] = *(const bf16x8*)((const char*)G_SB(b, h) + ((wc * 2 + n) * 2 + k) * 1024 + rdo)
; #define G_WAIT_V(n) asm volatile("s_waitcnt vmcnt(" #n ")" ::: "memory")
; #define G_WAIT_L(n) asm volatile("s_waitcnt lgkmcnt(" #n ")" ::: "memory")
; #define G_BAR __builtin_amdgcn_s_barrier()
; #define G_SCHED __builtin_amdgcn_sched_barrier(0)
; DI void br_flush(PREF p, f32x4 (&acc)[2][2][4][2], int slot) { br_store(p, acc, slot); zero_acc256(acc); }
;     ...
;     G_LDA(At, 1, 1); G_STAGE(G_SA(1, 0), A, oa0, oa1, LDA, 0, KA(tt + 3));
;     G_BAR; G_WAIT_L(0); G_MMA(1, 0, At, B0); G_BAR; G_SCHED;
;     G_STAGE(G_SB(1, 1), B, ob0, ob1, LDB, 128, KB(tt + 3));
;     G_WAIT_V(6); G_BAR; G_MMA(1, 1, At, B1); G_BAR;
;     if (MODE && ((tt + 1) & 3) == 3) br_flush(p, acc, (tt + 1) >> 2);
;   }
;   {
;     G_LDB(B0, 0, 0); G_LDA(At, 0, 0); G_STAGE(G_SA(1, 1), A, oa0, oa1, LDA, 128, KA(nt - 1));
;     G_BAR; G_WAIT_L(0); G_MMA(0, 0, At, B0); G_BAR;
;     G_LDB(B1, 0, 1); G_BAR; G_WAIT_L(0); G_MMA(0, 1, At, B1); G_BAR;
	s_waitcnt lgkmcnt(0)
	v_mfma_f32_16x16x32_bf16 v[38:41], v[198:201], v[182:185], v[38:41]
	v_mfma_f32_16x16x32_bf16 v[34:37], v[198:201], v[190:193], v[34:37]
	v_mfma_f32_16x16x32_bf16 v[30:33], v[206:209], v[182:185], v[30:33]
	v_mfma_f32_16x16x32_bf16 v[26:29], v[206:209], v[190:193], v[26:29]
	v_mfma_f32_16x16x32_bf16 v[22:25], v[214:217], v[182:185], v[22:25]
	v_mfma_f32_16x16x32_bf16 v[18:21], v[214:217], v[190:193], v[18:21]
	v_mfma_f32_16x16x32_bf16 v[14:17], v[222:225], v[182:185], v[14:17]
	v_mfma_f32_16x16x32_bf16 v[10:13], v[222:225], v[190:193], v[10:13]
	v_mfma_f32_16x16x32_bf16 v[38:41], v[202:205], v[186:189], v[38:41]
	v_mfma_f32_16x16x32_bf16 v[34:37], v[202:205], v[194:197], v[34:37]
	v_mfma_f32_16x16x32_bf16 v[30:33], v[210:213], v[186:189], v[30:33]
	v_mfma_f32_16x16x32_bf16 v[26:29], v[210:213], v[194:197], v[26:29]
	v_mfma_f32_16x16x32_bf16 v[22:25], v[218:221], v[186:189], v[22:25]
	v_mfma_f32_16x16x32_bf16 v[18:21], v[218:221], v[194:197], v[18:21]
	v_mfma_f32_16x16x32_bf16 v[14:17], v[226:229], v[186:189], v[14:17]
	v_mfma_f32_16x16x32_bf16 v[10:13], v[226:229], v[194:197], v[10:13]
	s_barrier
	v_readfirstlane_b32 s0, v158
	v_lshl_add_u64 v[166:167], v[248:249], 0, s[6:7]
	s_mov_b32 m0, s0
	v_readfirstlane_b32 s0, v160
	global_load_lds_dwordx4 v[166:167], off
	v_lshl_add_u64 v[166:167], v[250:251], 0, s[6:7]
	s_mov_b32 m0, s0
	s_nop 0
	global_load_lds_dwordx4 v[166:167], off
	s_waitcnt vmcnt(6)
	s_barrier
	v_mfma_f32_16x16x32_bf16 v[6:9], v[198:201], v[230:233], v[6:9]
	v_mfma_f32_16x16x32_bf16 v[2:5], v[198:201], v[238:241], v[2:5]
	v_mfma_f32_16x16x32_bf16 v[62:65], v[206:209], v[230:233], v[62:65]
	v_mfma_f32_16x16x32_bf16 v[66:69], v[206:209], v[238:241], v[66:69]
	v_mfma_f32_16x16x32_bf16 v[74:77], v[214:217], v[230:233], v[74:77]
	v_mfma_f32_16x16x32_bf16 v[78:81], v[214:217], v[238:241], v[78:81]
	v_mfma_f32_16x16x32_bf16 v[82:85], v[222:225], v[230:233], v[82:85]
	v_mfma_f32_16x16x32_bf16 v[90:93], v[222:225], v[238:241], v[90:93]
	v_mfma_f32_16x16x32_bf16 v[6:9], v[202:205], v[234:237], v[6:9]
	v_mfma_f32_16x16x32_bf16 v[2:5], v[202:205], v[242:245], v[2:5]
	v_mfma_f32_16x16x32_bf16 v[62:65], v[210:213], v[234:237], v[62:65]
	v_mfma_f32_16x16x32_bf16 v[66:69], v[210:213], v[242:245], v[66:69]
	v_mfma_f32_16x16x32_bf16 v[74:77], v[218:221], v[234:237], v[74:77]
	v_mfma_f32_16x16x32_bf16 v[78:81], v[218:221], v[242:245], v[78:81]
	v_mfma_f32_16x16x32_bf16 v[82:85], v[226:229], v[234:237], v[82:85]
	v_mfma_f32_16x16x32_bf16 v[90:93], v[226:229], v[242:245], v[90:93]
	s_add_i32 s15, s15, 2
	s_add_u32 s20, s20, 0x100
	s_addc_u32 s21, s21, 0
	s_cmp_lt_u32 s15, 12
	s_barrier
	s_cbranch_scc1 .LBB0_453
	s_add_u32 s0, s18, 0x40780
	s_addc_u32 s1, s19, 0
	v_readfirstlane_b32 s15, v162
	v_lshl_add_u64 v[132:133], v[132:133], 1, s[0:1]
	s_mov_b32 m0, s15
	v_lshl_add_u64 v[130:131], v[130:131], 1, s[0:1]
	v_readfirstlane_b32 s0, v164
	ds_read_b128 v[134:137], v161
	ds_read_b128 v[138:141], v161 offset:1024
	ds_read_b128 v[152:155], v161 offset:2048
	ds_read_b128 v[182:185], v161 offset:3072
	ds_read_b128 v[186:189], v143
	ds_read_b128 v[190:193], v143 offset:1024
	ds_read_b128 v[194:197], v143 offset:2048
	ds_read_b128 v[198:201], v143 offset:3072
	ds_read_b128 v[202:205], v143 offset:4096
	ds_read_b128 v[206:209], v143 offset:5120
	ds_read_b128 v[210:213], v143 offset:6144
	ds_read_b128 v[214:217], v143 offset:7168
	global_load_lds_dwordx4 v[132:133], off
	s_mov_b32 m0, s0
	s_nop 0
	global_load_lds_dwordx4 v[130:131], off
	s_barrier
	s_waitcnt lgkmcnt(0)
	v_mfma_f32_16x16x32_bf16 v[126:129], v[186:189], v[134:137], v[126:129]
	v_mfma_f32_16x16x32_bf16 v[122:125], v[186:189], v[152:155], v[122:125]
	v_mfma_f32_16x16x32_bf16 v[110:113], v[202:205], v[134:137], v[110:113]
	v_mfma_f32_16x16x32_bf16 v[102:105], v[210:213], v[134:137], v[102:105]
	v_mfma_f32_16x16x32_bf16 v[126:129], v[190:193], v[138:141], v[126:129]
	v_mfma_f32_16x16x32_bf16 v[122:125], v[190:193], v[182:185], v[122:125]
	v_mfma_f32_16x16x32_bf16 v[118:121], v[194:197], v[134:137], v[118:121]
	v_mfma_f32_16x16x32_bf16 v[114:117], v[194:197], v[152:155], v[114:117]
	v_mfma_f32_16x16x32_bf16 v[110:113], v[206:209], v[138:141], v[110:113]
	v_mfma_f32_16x16x32_bf16 v[106:109], v[202:205], v[152:155], v[106:109]
	v_mfma_f32_16x16x32_bf16 v[102:105], v[214:217], v[138:141], v[102:105]
	v_mfma_f32_16x16x32_bf16 v[98:101], v[210:213], v[152:155], v[98:101]
	v_mfma_f32_16x16x32_bf16 v[130:133], v[198:201], v[138:141], v[118:121]
	v_mfma_f32_16x16x32_bf16 v[164:167], v[198:201], v[182:185], v[114:117]
	v_mfma_f32_16x16x32_bf16 v[218:221], v[206:209], v[182:185], v[106:109]
	v_mfma_f32_16x16x32_bf16 v[222:225], v[214:217], v[182:185], v[98:101]
	s_barrier
	s_nop 1
	s_nop 0
	ds_read_b128 v[98:101], v159
	ds_read_b128 v[106:109], v159 offset:1024
	ds_read_b128 v[114:117], v159 offset:2048
	ds_read_b128 v[118:121], v159 offset:3072
	s_barrier
	s_waitcnt lgkmcnt(0)
	v_mfma_f32_16x16x32_bf16 v[94:97], v[186:189], v[98:101], v[94:97]
	v_mfma_f32_16x16x32_bf16 v[70:73], v[194:197], v[98:101], v[70:73]
	v_mfma_f32_16x16x32_bf16 v[58:61], v[194:197], v[114:117], v[58:61]
	v_mfma_f32_16x16x32_bf16 v[54:57], v[202:205], v[98:101], v[54:57]
	v_mfma_f32_16x16x32_bf16 v[50:53], v[202:205], v[114:117], v[50:53]
	v_mfma_f32_16x16x32_bf16 v[46:49], v[210:213], v[98:101], v[46:49]
	v_mfma_f32_16x16x32_bf16 v[42:45], v[210:213], v[114:117], v[42:45]
	v_mfma_f32_16x16x32_bf16 v[94:97], v[190:193], v[106:109], v[94:97]
	v_mfma_f32_16x16x32_bf16 v[86:89], v[186:189], v[114:117], v[86:89]
	v_mfma_f32_16x16x32_bf16 v[70:73], v[198:201], v[106:109], v[70:73]
	v_mfma_f32_16x16x32_bf16 v[58:61], v[198:201], v[118:121], v[58:61]
	v_mfma_f32_16x16x32_bf16 v[54:57], v[206:209], v[106:109], v[54:57]
	v_mfma_f32_16x16x32_bf16 v[50:53], v[206:209], v[118:121], v[50:53]
	v_mfma_f32_16x16x32_bf16 v[46:49], v[214:217], v[106:109], v[46:49]
	v_mfma_f32_16x16x32_bf16 v[42:45], v[214:217], v[118:121], v[42:45]
	v_mfma_f32_16x16x32_bf16 v[156:159], v[190:193], v[118:121], v[86:89]
	s_barrier
; #define G_LDA(dst, b, h)                                                                                                  \
;   _Pragma("unroll") for (int m = 0; m < 4; ++m) _Pragma("unroll") for (int k = 0; k < 2; ++k)                             \
;       dst[m][k] = *(const bf16x8*)((const char*)G_SA(b, h) + ((wr * 4 + m) * 2 + k) * 1024 + rdo)
; #define G_LDB(dst, b, h)                                                                                                  \
;   _Pragma("unroll") for (int n = 0; n < 2; ++n) _Pragma("unroll") for (int k = 0; k < 2; ++k)                             \
;       dst[n][k] = *(const bf16x8*)((const char*)G_SB(b, h) + ((wc * 2 + n) * 2 + k) * 1024 + rdo)
; #define G_WAIT_V(n) asm volatile("s_waitcnt vmcnt(" #n ")" ::: "memory")
; #define G_WAIT_L(n) asm volatile("s_waitcnt lgkmcnt(" #n ")" ::: "memory")
; #define G_BAR __builtin_amdgcn_s_barrier()
;     ...
;     G_LDB(B1, 0, 1); G_BAR; G_WAIT_L(0); G_MMA(0, 1, At, B1); G_BAR;
;     G_LDA(At, 0, 1); G_WAIT_V(4); G_BAR; G_WAIT_L(0); G_MMA(1, 0, At, B0); G_MMA(1, 1, At, B1); G_BAR;
;   }
;   {
;     G_LDB(B0, 1, 0); G_LDA(At, 1, 0); G_WAIT_V(2); G_BAR; G_WAIT_L(0); G_MMA(0, 0, At, B0); G_BAR;
	s_nop 0
	ds_read_b128 v[86:89], v143 offset:16384
	ds_read_b128 v[186:189], v143 offset:17408
	ds_read_b128 v[190:193], v143 offset:18432
	ds_read_b128 v[194:197], v143 offset:19456
	ds_read_b128 v[198:201], v143 offset:20480
	ds_read_b128 v[202:205], v143 offset:21504
	ds_read_b128 v[206:209], v143 offset:22528
	ds_read_b128 v[210:213], v143 offset:23552
	s_waitcnt vmcnt(4)
	s_barrier
	s_waitcnt lgkmcnt(0)
	v_mfma_f32_16x16x32_bf16 v[38:41], v[86:89], v[134:137], v[38:41]
	v_mfma_f32_16x16x32_bf16 v[34:37], v[86:89], v[152:155], v[34:37]
	v_mfma_f32_16x16x32_bf16 v[30:33], v[190:193], v[134:137], v[30:33]
	v_mfma_f32_16x16x32_bf16 v[26:29], v[190:193], v[152:155], v[26:29]
	v_mfma_f32_16x16x32_bf16 v[22:25], v[198:201], v[134:137], v[22:25]
	v_mfma_f32_16x16x32_bf16 v[18:21], v[198:201], v[152:155], v[18:21]
	v_mfma_f32_16x16x32_bf16 v[14:17], v[206:209], v[134:137], v[14:17]
	v_mfma_f32_16x16x32_bf16 v[10:13], v[206:209], v[152:155], v[10:13]
	v_mfma_f32_16x16x32_bf16 v[38:41], v[186:189], v[138:141], v[38:41]
	v_mfma_f32_16x16x32_bf16 v[34:37], v[186:189], v[182:185], v[34:37]
	v_mfma_f32_16x16x32_bf16 v[30:33], v[194:197], v[138:141], v[30:33]
	v_mfma_f32_16x16x32_bf16 v[26:29], v[194:197], v[182:185], v[26:29]
	v_mfma_f32_16x16x32_bf16 v[22:25], v[202:205], v[138:141], v[22:25]
	v_mfma_f32_16x16x32_bf16 v[18:21], v[202:205], v[182:185], v[18:21]
	v_mfma_f32_16x16x32_bf16 v[14:17], v[210:213], v[138:141], v[14:17]
	v_mfma_f32_16x16x32_bf16 v[10:13], v[210:213], v[182:185], v[10:13]
	v_mfma_f32_16x16x32_bf16 v[62:65], v[190:193], v[98:101], v[62:65]
	v_mfma_f32_16x16x32_bf16 v[134:137], v[194:197], v[106:109], v[62:65]
	v_mfma_f32_16x16x32_bf16 v[62:65], v[190:193], v[114:117], v[66:69]
	v_mfma_f32_16x16x32_bf16 v[138:141], v[194:197], v[118:121], v[62:65]
	v_mfma_f32_16x16x32_bf16 v[62:65], v[198:201], v[98:101], v[74:77]
	v_mfma_f32_16x16x32_bf16 v[152:155], v[202:205], v[106:109], v[62:65]
	v_mfma_f32_16x16x32_bf16 v[62:65], v[198:201], v[114:117], v[78:81]
	v_mfma_f32_16x16x32_bf16 v[6:9], v[86:89], v[98:101], v[6:9]
	v_mfma_f32_16x16x32_bf16 v[2:5], v[86:89], v[114:117], v[2:5]
	v_mfma_f32_16x16x32_bf16 v[182:185], v[202:205], v[118:121], v[62:65]
	v_mfma_f32_16x16x32_bf16 v[62:65], v[206:209], v[98:101], v[82:85]
	v_mfma_f32_16x16x32_bf16 v[6:9], v[186:189], v[106:109], v[6:9]
	v_mfma_f32_16x16x32_bf16 v[2:5], v[186:189], v[118:121], v[2:5]
	v_mfma_f32_16x16x32_bf16 v[186:189], v[210:213], v[106:109], v[62:65]
	v_mfma_f32_16x16x32_bf16 v[62:65], v[206:209], v[114:117], v[90:93]
	v_mfma_f32_16x16x32_bf16 v[190:193], v[210:213], v[118:121], v[62:65]
	s_barrier
	ds_read_b128 v[194:197], v150
	ds_read_b128 v[198:201], v150 offset:1024
	ds_read_b128 v[202:205], v150 offset:2048
	ds_read_b128 v[148:151], v150 offset:3072
	s_nop 0
	s_nop 0
	ds_read_b128 v[62:65], v143 offset:32768
	ds_read_b128 v[66:69], v143 offset:33792
	ds_read_b128 v[74:77], v143 offset:34816
	ds_read_b128 v[78:81], v143 offset:35840
	ds_read_b128 v[206:209], v143 offset:36864
	ds_read_b128 v[210:213], v143 offset:37888
	ds_read_b128 v[214:217], v143 offset:38912
	ds_read_b128 v[226:229], v143 offset:39936
	s_waitcnt vmcnt(2)
	s_barrier
	s_waitcnt lgkmcnt(0)
	v_mfma_f32_16x16x32_bf16 v[82:85], v[62:65], v[194:197], v[126:129]
	v_mfma_f32_16x16x32_bf16 v[118:121], v[66:69], v[198:201], v[82:85]
	v_mfma_f32_16x16x32_bf16 v[82:85], v[62:65], v[202:205], v[122:125]
	v_mfma_f32_16x16x32_bf16 v[126:129], v[66:69], v[148:151], v[82:85]
	v_mfma_f32_16x16x32_bf16 v[82:85], v[74:77], v[194:197], v[130:133]
	v_mfma_f32_16x16x32_bf16 v[114:117], v[78:81], v[198:201], v[82:85]
	v_mfma_f32_16x16x32_bf16 v[82:85], v[74:77], v[202:205], v[164:167]
	v_mfma_f32_16x16x32_bf16 v[122:125], v[78:81], v[148:151], v[82:85]
	v_mfma_f32_16x16x32_bf16 v[82:85], v[206:209], v[194:197], v[110:113]
	v_mfma_f32_16x16x32_bf16 v[106:109], v[210:213], v[198:201], v[82:85]
	v_mfma_f32_16x16x32_bf16 v[82:85], v[206:209], v[202:205], v[218:221]
	v_mfma_f32_16x16x32_bf16 v[110:113], v[210:213], v[148:151], v[82:85]
	v_mfma_f32_16x16x32_bf16 v[82:85], v[214:217], v[194:197], v[102:105]
	v_mfma_f32_16x16x32_bf16 v[98:101], v[226:229], v[198:201], v[82:85]
	v_mfma_f32_16x16x32_bf16 v[82:85], v[214:217], v[202:205], v[222:225]
	v_mfma_f32_16x16x32_bf16 v[102:105], v[226:229], v[148:151], v[82:85]
	s_barrier
; #define G_LDA(dst, b, h)                                                                                                  \
;   _Pragma("unroll") for (int m = 0; m < 4; ++m) _Pragma("unroll") for (int k = 0; k < 2; ++k)                             \
;       dst[m][k] = *(const bf16x8*)((const char*)G_SA(b, h) + ((wr * 4 + m) * 2 + k) * 1024 + rdo)
; #define G_LDB(dst, b, h)                                                                                                  \
;   _Pragma("unroll") for (int n = 0; n < 2; ++n) _Pragma("unroll") for (int k = 0; k < 2; ++k)                             \
;       dst[n][k] = *(const bf16x8*)((const char*)G_SB(b, h) + ((wc * 2 + n) * 2 + k) * 1024 + rdo)
; #define G_WAIT_V(n) asm volatile("s_waitcnt vmcnt(" #n ")" ::: "memory")
; #define G_WAIT_L(n) asm volatile("s_waitcnt lgkmcnt(" #n ")" ::: "memory")
; #define G_BAR __builtin_amdgcn_s_barrier()
;     ...
;     G_LDB(B0, 1, 0); G_LDA(At, 1, 0); G_WAIT_V(2); G_BAR; G_WAIT_L(0); G_MMA(0, 0, At, B0); G_BAR;
;     G_LDB(B1, 1, 1); G_WAIT_V(0); G_BAR; G_WAIT_L(0); G_MMA(0, 1, At, B1); G_BAR;
;     G_LDA(At, 1, 1); G_BAR; G_WAIT_L(0); G_MMA(1, 0, At, B0); G_MMA(1, 1, At, B1); G_BAR;
;   }
;   if (wr == 0) G_BAR;
	ds_read_b128 v[130:133], v146
	ds_read_b128 v[164:167], v146 offset:1024
	ds_read_b128 v[218:221], v146 offset:2048
	ds_read_b128 v[144:147], v146 offset:3072
	s_waitcnt vmcnt(0)
	s_barrier
	s_waitcnt lgkmcnt(0)
	v_mfma_f32_16x16x32_bf16 v[82:85], v[62:65], v[130:133], v[94:97]
	v_mfma_f32_16x16x32_bf16 v[62:65], v[62:65], v[218:221], v[156:159]
	v_mfma_f32_16x16x32_bf16 v[94:97], v[66:69], v[144:147], v[62:65]
	v_mfma_f32_16x16x32_bf16 v[62:65], v[74:77], v[130:133], v[70:73]
	v_mfma_f32_16x16x32_bf16 v[58:61], v[74:77], v[218:221], v[58:61]
	v_mfma_f32_16x16x32_bf16 v[54:57], v[206:209], v[130:133], v[54:57]
	v_mfma_f32_16x16x32_bf16 v[50:53], v[206:209], v[218:221], v[50:53]
	v_mfma_f32_16x16x32_bf16 v[46:49], v[214:217], v[130:133], v[46:49]
	v_mfma_f32_16x16x32_bf16 v[42:45], v[214:217], v[218:221], v[42:45]
	v_mfma_f32_16x16x32_bf16 v[86:89], v[66:69], v[164:167], v[82:85]
	v_mfma_f32_16x16x32_bf16 v[82:85], v[78:81], v[164:167], v[62:65]
	v_mfma_f32_16x16x32_bf16 v[90:93], v[78:81], v[144:147], v[58:61]
	v_mfma_f32_16x16x32_bf16 v[74:77], v[210:213], v[164:167], v[54:57]
	v_mfma_f32_16x16x32_bf16 v[78:81], v[210:213], v[144:147], v[50:53]
	v_mfma_f32_16x16x32_bf16 v[66:69], v[226:229], v[164:167], v[46:49]
	v_mfma_f32_16x16x32_bf16 v[70:73], v[226:229], v[144:147], v[42:45]
	s_barrier
	ds_read_b128 v[156:159], v143 offset:49152
	ds_read_b128 v[206:209], v143 offset:50176
	ds_read_b128 v[210:213], v143 offset:51200
	ds_read_b128 v[214:217], v143 offset:52224
	ds_read_b128 v[222:225], v143 offset:53248
	ds_read_b128 v[226:229], v143 offset:54272
	ds_read_b128 v[230:233], v143 offset:55296
	ds_read_b128 v[234:237], v143 offset:56320
	s_barrier
	s_waitcnt lgkmcnt(0)
	v_mfma_f32_16x16x32_bf16 v[38:41], v[156:159], v[194:197], v[38:41]
	v_mfma_f32_16x16x32_bf16 v[34:37], v[156:159], v[202:205], v[34:37]
	v_mfma_f32_16x16x32_bf16 v[30:33], v[210:213], v[194:197], v[30:33]
	v_mfma_f32_16x16x32_bf16 v[26:29], v[210:213], v[202:205], v[26:29]
	v_mfma_f32_16x16x32_bf16 v[22:25], v[222:225], v[194:197], v[22:25]
	v_mfma_f32_16x16x32_bf16 v[18:21], v[222:225], v[202:205], v[18:21]
	v_mfma_f32_16x16x32_bf16 v[14:17], v[230:233], v[194:197], v[14:17]
	v_mfma_f32_16x16x32_bf16 v[10:13], v[230:233], v[202:205], v[10:13]
	v_mfma_f32_16x16x32_bf16 v[54:57], v[206:209], v[198:201], v[38:41]
	v_mfma_f32_16x16x32_bf16 v[62:65], v[206:209], v[148:151], v[34:37]
	v_mfma_f32_16x16x32_bf16 v[50:53], v[214:217], v[198:201], v[30:33]
	v_mfma_f32_16x16x32_bf16 v[58:61], v[214:217], v[148:151], v[26:29]
	v_mfma_f32_16x16x32_bf16 v[42:45], v[226:229], v[198:201], v[22:25]
	v_mfma_f32_16x16x32_bf16 v[46:49], v[226:229], v[148:151], v[18:21]
	v_mfma_f32_16x16x32_bf16 v[34:37], v[234:237], v[198:201], v[14:17]
	v_mfma_f32_16x16x32_bf16 v[38:41], v[234:237], v[148:151], v[10:13]
	v_mfma_f32_16x16x32_bf16 v[2:5], v[156:159], v[218:221], v[2:5]
	v_mfma_f32_16x16x32_bf16 v[30:33], v[206:209], v[144:147], v[2:5]
	v_mfma_f32_16x16x32_bf16 v[2:5], v[210:213], v[130:133], v[134:137]
	v_mfma_f32_16x16x32_bf16 v[18:21], v[214:217], v[164:167], v[2:5]
	v_mfma_f32_16x16x32_bf16 v[2:5], v[210:213], v[218:221], v[138:141]
	v_mfma_f32_16x16x32_bf16 v[26:29], v[214:217], v[144:147], v[2:5]
	v_mfma_f32_16x16x32_bf16 v[2:5], v[222:225], v[130:133], v[152:155]
	v_mfma_f32_16x16x32_bf16 v[6:9], v[156:159], v[130:133], v[6:9]
	v_mfma_f32_16x16x32_bf16 v[10:13], v[226:229], v[164:167], v[2:5]
	v_mfma_f32_16x16x32_bf16 v[2:5], v[222:225], v[218:221], v[182:185]
	v_mfma_f32_16x16x32_bf16 v[22:25], v[206:209], v[164:167], v[6:9]
	v_mfma_f32_16x16x32_bf16 v[14:17], v[226:229], v[144:147], v[2:5]
	v_mfma_f32_16x16x32_bf16 v[2:5], v[230:233], v[130:133], v[186:189]
	v_mfma_f32_16x16x32_bf16 v[6:9], v[230:233], v[218:221], v[190:193]
	v_mfma_f32_16x16x32_bf16 v[2:5], v[234:237], v[164:167], v[2:5]
	v_mfma_f32_16x16x32_bf16 v[6:9], v[234:237], v[144:147], v[6:9]
	v_cmp_gt_u32_e32 vcc, s67, v0
	s_barrier
	s_and_saveexec_b64 s[18:19], vcc
	s_cbranch_execz .LBB0_456
	s_barrier
